# q6 + scan recurrence: v_mov broadcast copies folded into packed-op op_sel
# speedup vs baseline: 1.0150x; 1.0017x over previous
; #define LAS __attribute__((address_space(3)))
; DI unsigned pk2(float a, float b) { f32x2 v = {a, b}; bf2_t r = __builtin_convertvector(v, bf2_t); return __builtin_bit_cast(unsigned, r); }
; DI f32x2 red16p(f32x2 x) { float a = x.x, b = x.y; red16x2(a, b); return (f32x2){a, b}; }
; DI void scan_bh2(const Args& a, int l, int bh, int halfsel, LAS unsigned char* lds) {
;     ...
;         for (int c = 0; c < SEQ / T; ++c) {
;             const LAS float* cur = opbuf + (c & 1) * CH;
;             LAS unsigned char* yb = ybuf + (c & 1) * (T * 128);
;             f32x4 r4 = *(const LAS f32x4*)(cur + kq * 4), d4 = *(const LAS f32x4*)(cur + 64 + kq * 4), k4 = *(const LAS f32x4*)(cur + 128 + kq * 4),
;                   kk4 = *(const LAS f32x4*)(cur + 192 + kq * 4), b4 = *(const LAS f32x4*)(cur + 256 + kq * 4);
;             f32x2 v2 = *(const LAS f32x2*)(cur + 320 + row0);
; #pragma unroll
;             for (int st = 0; st < T; ++st) {
;                 f32x4 nr4, nd4, nk4, nkk4, nb4; f32x2 nv2;
;                 if (st < T - 1) {
;                     const LAS float* o = cur + (st + 1) * 384;
;                     nr4 = *(const LAS f32x4*)(o + kq * 4); nd4 = *(const LAS f32x4*)(o + 64 + kq * 4); nk4 = *(const LAS f32x4*)(o + 128 + kq * 4);
;                     nkk4 = *(const LAS f32x4*)(o + 192 + kq * 4); nb4 = *(const LAS f32x4*)(o + 256 + kq * 4); nv2 = *(const LAS f32x2*)(o + 320 + row0);
;                 }
;                 f32x2 sa = S[0] * kk4[0]; sa += S[1] * kk4[1]; f32x2 sb = S[2] * kk4[2]; sb += S[3] * kk4[3]; sa += sb;
;                 sa = red16p(sa); sa = -sa;
; #pragma unroll
;                 for (int j = 0; j < 4; ++j) S[j] = S[j] * d4[j] + sa * b4[j] + v2 * k4[j];
;                 f32x2 y = S[0] * r4[0]; y += S[1] * r4[1]; f32x2 yc = S[2] * r4[2]; yc += S[3] * r4[3]; y += yc;
;                 y = red16p(y);
;                 *(LAS unsigned*)(yb + st * 128 + row0 * 2) = pk2(y.x, y.y);
.LBB0_497:
	s_and_b32 s2, s4, 1
	s_mul_i32 s3, s2, 0xc000
	s_add_i32 s3, s3, 0
	v_lshl_add_u32 v15, v11, 2, s3
	ds_read_b128 v[18:21], v15
	ds_read_b128 v[22:25], v15 offset:256
	ds_read_b128 v[26:29], v15 offset:512
	ds_read_b128 v[30:33], v15 offset:768
	v_lshl_add_u32 v16, v10, 2, s3
	v_add_u32_e32 v14, 0x100, v16
	ds_read2st64_b64 v[34:37], v14 offset0:2 offset1:5
	ds_read_b128 v[38:41], v15 offset:1024
	ds_read_b128 v[42:45], v15 offset:1536
	ds_read_b128 v[46:49], v15 offset:1792
	ds_read_b128 v[50:53], v15 offset:2048
	ds_read_b128 v[54:57], v15 offset:2304
	ds_read_b128 v[58:61], v15 offset:2560
	s_waitcnt lgkmcnt(7)
	v_pk_mul_f32 v[62:63], v[4:5], v[30:31] op_sel:[0,1]
	s_lshl_b32 s2, s2, 12
	v_pk_fma_f32 v[30:31], v[2:3], v[30:31], v[62:63] op_sel_hi:[1,0,1]
	v_pk_mul_f32 v[62:63], v[8:9], v[32:33] op_sel:[0,1] op_sel_hi:[1,1]
	s_add_i32 s5, s2, 0
	v_pk_fma_f32 v[32:33], v[6:7], v[32:33], v[62:63] op_sel_hi:[1,0,1]
	s_add_i32 s5, s5, 0x18000
	v_pk_add_f32 v[30:31], v[30:31], v[32:33]
	v_add_u32_e32 v14, s5, v12
	s_nop 0
	v_add_f32_dpp v30, v30, v30 quad_perm:[1,0,3,2] row_mask:0xf bank_mask:0xf bound_ctrl:1
	v_add_f32_dpp v31, v31, v31 quad_perm:[1,0,3,2] row_mask:0xf bank_mask:0xf bound_ctrl:1
	s_nop 0
	v_add_f32_dpp v30, v30, v30 quad_perm:[2,3,0,1] row_mask:0xf bank_mask:0xf bound_ctrl:1
	v_add_f32_dpp v31, v31, v31 quad_perm:[2,3,0,1] row_mask:0xf bank_mask:0xf bound_ctrl:1
	s_nop 0
	v_add_f32_dpp v30, v30, v30 row_half_mirror row_mask:0xf bank_mask:0xf bound_ctrl:1
	v_add_f32_dpp v31, v31, v31 row_half_mirror row_mask:0xf bank_mask:0xf bound_ctrl:1
	s_nop 0
	v_add_f32_dpp v30, v30, v30 row_mirror row_mask:0xf bank_mask:0xf bound_ctrl:1
	v_add_f32_dpp v31, v31, v31 row_mirror row_mask:0xf bank_mask:0xf bound_ctrl:1
	s_waitcnt lgkmcnt(5)
	v_pk_mul_f32 v[32:33], v[38:39], v[30:31] op_sel_hi:[0,1]
	v_pk_fma_f32 v[2:3], v[2:3], v[22:23], v[32:33] op_sel_hi:[1,0,1] neg_lo:[0,0,1] neg_hi:[0,0,1]
	s_nop 0
	v_pk_fma_f32 v[32:33], v[26:27], v[34:35], v[2:3] op_sel_hi:[0,1,1]
	v_pk_mul_f32 v[2:3], v[38:39], v[30:31] op_sel:[1,0]
	s_nop 0
	v_pk_fma_f32 v[2:3], v[4:5], v[22:23], v[2:3] op_sel:[0,1,0] neg_lo:[0,0,1] neg_hi:[0,0,1]
	s_nop 0
	v_pk_fma_f32 v[38:39], v[26:27], v[34:35], v[2:3] op_sel:[1,0,0]
	v_pk_mul_f32 v[2:3], v[40:41], v[30:31] op_sel_hi:[0,1]
	v_pk_fma_f32 v[2:3], v[6:7], v[24:25], v[2:3] op_sel_hi:[1,0,1] neg_lo:[0,0,1] neg_hi:[0,0,1]
	v_pk_mul_f32 v[4:5], v[40:41], v[30:31] op_sel:[1,0] op_sel_hi:[1,1]
	v_pk_fma_f32 v[62:63], v[28:29], v[34:35], v[2:3] op_sel_hi:[0,1,1]
	v_pk_fma_f32 v[2:3], v[8:9], v[24:25], v[4:5] op_sel:[0,1,0] op_sel_hi:[1,1,1] neg_lo:[0,0,1] neg_hi:[0,0,1]
	s_nop 0
	v_pk_fma_f32 v[30:31], v[28:29], v[34:35], v[2:3] op_sel:[1,0,0] op_sel_hi:[1,1,1]
	s_waitcnt lgkmcnt(1)
	v_pk_mul_f32 v[34:35], v[54:55], v[38:39] op_sel:[1,0]
	v_pk_mul_f32 v[40:41], v[56:57], v[30:31] op_sel:[1,0] op_sel_hi:[1,1]
	v_pk_mul_f32 v[2:3], v[18:19], v[38:39] op_sel:[1,0]
	v_pk_mul_f32 v[4:5], v[20:21], v[30:31] op_sel:[1,0] op_sel_hi:[1,1]
	v_pk_fma_f32 v[34:35], v[54:55], v[32:33], v[34:35] op_sel_hi:[0,1,1]
	v_pk_fma_f32 v[40:41], v[56:57], v[62:63], v[40:41] op_sel_hi:[0,1,1]
	v_pk_fma_f32 v[2:3], v[18:19], v[32:33], v[2:3] op_sel_hi:[0,1,1]
	v_pk_fma_f32 v[4:5], v[20:21], v[62:63], v[4:5] op_sel_hi:[0,1,1]
	v_pk_add_f32 v[34:35], v[34:35], v[40:41]
	v_pk_add_f32 v[2:3], v[2:3], v[4:5]
	s_nop 0
	v_add_f32_dpp v34, v34, v34 quad_perm:[1,0,3,2] row_mask:0xf bank_mask:0xf bound_ctrl:1
	v_add_f32_dpp v35, v35, v35 quad_perm:[1,0,3,2] row_mask:0xf bank_mask:0xf bound_ctrl:1
	v_add_f32_dpp v2, v2, v2 quad_perm:[1,0,3,2] row_mask:0xf bank_mask:0xf bound_ctrl:1
	v_add_f32_dpp v3, v3, v3 quad_perm:[1,0,3,2] row_mask:0xf bank_mask:0xf bound_ctrl:1
	v_add_f32_dpp v34, v34, v34 quad_perm:[2,3,0,1] row_mask:0xf bank_mask:0xf bound_ctrl:1
	v_add_f32_dpp v35, v35, v35 quad_perm:[2,3,0,1] row_mask:0xf bank_mask:0xf bound_ctrl:1
	v_add_f32_dpp v2, v2, v2 quad_perm:[2,3,0,1] row_mask:0xf bank_mask:0xf bound_ctrl:1
	v_add_f32_dpp v3, v3, v3 quad_perm:[2,3,0,1] row_mask:0xf bank_mask:0xf bound_ctrl:1
	v_add_f32_dpp v34, v34, v34 row_half_mirror row_mask:0xf bank_mask:0xf bound_ctrl:1
	v_add_f32_dpp v35, v35, v35 row_half_mirror row_mask:0xf bank_mask:0xf bound_ctrl:1
	v_add_f32_dpp v2, v2, v2 row_half_mirror row_mask:0xf bank_mask:0xf bound_ctrl:1
	v_add_f32_dpp v3, v3, v3 row_half_mirror row_mask:0xf bank_mask:0xf bound_ctrl:1
	v_add_f32_dpp v34, v34, v34 row_mirror row_mask:0xf bank_mask:0xf bound_ctrl:1
	v_add_f32_dpp v35, v35, v35 row_mirror row_mask:0xf bank_mask:0xf bound_ctrl:1
	s_waitcnt lgkmcnt(0)
	v_pk_mul_f32 v[40:41], v[58:59], v[34:35] op_sel_hi:[0,1]
	v_add_f32_dpp v2, v2, v2 row_mirror row_mask:0xf bank_mask:0xf bound_ctrl:1
	v_add_f32_dpp v3, v3, v3 row_mirror row_mask:0xf bank_mask:0xf bound_ctrl:1
	v_pk_fma_f32 v[32:33], v[46:47], v[32:33], v[40:41] op_sel_hi:[0,1,1] neg_lo:[0,0,1] neg_hi:[0,0,1]
	v_cvt_pk_bf16_f32 v2, v2, v3
	v_pk_fma_f32 v[54:55], v[50:51], v[36:37], v[32:33] op_sel_hi:[0,1,1]
	v_pk_mul_f32 v[32:33], v[58:59], v[34:35] op_sel:[1,0]
	ds_write_b32 v14, v2
	v_pk_fma_f32 v[32:33], v[46:47], v[38:39], v[32:33] op_sel:[1,0,0] neg_lo:[0,0,1] neg_hi:[0,0,1]
	ds_read_b128 v[2:5], v15 offset:3072
	ds_read_b128 v[6:9], v15 offset:3328
	ds_read_b128 v[18:21], v15 offset:3584
	ds_read_b128 v[22:25], v15 offset:3840
	ds_read_b128 v[26:29], v15 offset:4096
	ds_read_b64 v[64:65], v16 offset:4352
	v_pk_fma_f32 v[50:51], v[50:51], v[36:37], v[32:33] op_sel:[1,0,0]
	v_pk_mul_f32 v[32:33], v[60:61], v[34:35] op_sel_hi:[0,1]
	v_pk_fma_f32 v[32:33], v[48:49], v[62:63], v[32:33] op_sel_hi:[0,1,1] neg_lo:[0,0,1] neg_hi:[0,0,1]
	v_pk_fma_f32 v[56:57], v[52:53], v[36:37], v[32:33] op_sel_hi:[0,1,1]
	v_pk_mul_f32 v[34:35], v[60:61], v[34:35] op_sel:[1,0] op_sel_hi:[1,1]
	s_nop 0
	v_pk_fma_f32 v[30:31], v[48:49], v[30:31], v[34:35] op_sel:[1,0,0] op_sel_hi:[1,1,1] neg_lo:[0,0,1] neg_hi:[0,0,1]
	s_waitcnt lgkmcnt(2)
; #define LAS __attribute__((address_space(3)))
; DI unsigned pk2(float a, float b) { f32x2 v = {a, b}; bf2_t r = __builtin_convertvector(v, bf2_t); return __builtin_bit_cast(unsigned, r); }
; DI f32x2 red16p(f32x2 x) { float a = x.x, b = x.y; red16x2(a, b); return (f32x2){a, b}; }
; DI void scan_bh2(const Args& a, int l, int bh, int halfsel, LAS unsigned char* lds) {
;     ...
;             for (int st = 0; st < T; ++st) {
;                 f32x4 nr4, nd4, nk4, nkk4, nb4; f32x2 nv2;
;                 if (st < T - 1) {
;                     const LAS float* o = cur + (st + 1) * 384;
;                     nr4 = *(const LAS f32x4*)(o + kq * 4); nd4 = *(const LAS f32x4*)(o + 64 + kq * 4); nk4 = *(const LAS f32x4*)(o + 128 + kq * 4);
;                     nkk4 = *(const LAS f32x4*)(o + 192 + kq * 4); nb4 = *(const LAS f32x4*)(o + 256 + kq * 4); nv2 = *(const LAS f32x2*)(o + 320 + row0);
;                 }
;                 f32x2 sa = S[0] * kk4[0]; sa += S[1] * kk4[1]; f32x2 sb = S[2] * kk4[2]; sb += S[3] * kk4[3]; sa += sb;
;                 sa = red16p(sa); sa = -sa;
; #pragma unroll
;                 for (int j = 0; j < 4; ++j) S[j] = S[j] * d4[j] + sa * b4[j] + v2 * k4[j];
;                 f32x2 y = S[0] * r4[0]; y += S[1] * r4[1]; f32x2 yc = S[2] * r4[2]; yc += S[3] * r4[3]; y += yc;
;                 y = red16p(y);
;                 *(LAS unsigned*)(yb + st * 128 + row0 * 2) = pk2(y.x, y.y);
;                 if (st < T - 1) { r4 = nr4; d4 = nd4; k4 = nk4; kk4 = nkk4; b4 = nb4; v2 = nv2; }
	v_pk_mul_f32 v[60:61], v[22:23], v[50:51] op_sel:[1,0]
	v_pk_fma_f32 v[52:53], v[52:53], v[36:37], v[30:31] op_sel:[1,0,0] op_sel_hi:[1,1,1]
	v_pk_fma_f32 v[22:23], v[22:23], v[54:55], v[60:61] op_sel_hi:[0,1,1]
	v_pk_mul_f32 v[60:61], v[24:25], v[52:53] op_sel:[1,0] op_sel_hi:[1,1]
	s_nop 0
	v_pk_fma_f32 v[24:25], v[24:25], v[56:57], v[60:61] op_sel_hi:[0,1,1]
	v_pk_mul_f32 v[30:31], v[42:43], v[50:51] op_sel:[1,0]
	v_pk_mul_f32 v[32:33], v[44:45], v[52:53] op_sel:[1,0] op_sel_hi:[1,1]
	v_pk_add_f32 v[22:23], v[22:23], v[24:25]
	v_pk_fma_f32 v[30:31], v[42:43], v[54:55], v[30:31] op_sel_hi:[0,1,1]
	v_pk_fma_f32 v[32:33], v[44:45], v[56:57], v[32:33] op_sel_hi:[0,1,1]
	v_add_f32_dpp v22, v22, v22 quad_perm:[1,0,3,2] row_mask:0xf bank_mask:0xf bound_ctrl:1
	v_add_f32_dpp v23, v23, v23 quad_perm:[1,0,3,2] row_mask:0xf bank_mask:0xf bound_ctrl:1
	v_pk_add_f32 v[30:31], v[30:31], v[32:33]
	v_add_f32_dpp v22, v22, v22 quad_perm:[2,3,0,1] row_mask:0xf bank_mask:0xf bound_ctrl:1
	v_add_f32_dpp v23, v23, v23 quad_perm:[2,3,0,1] row_mask:0xf bank_mask:0xf bound_ctrl:1
	v_add_f32_dpp v30, v30, v30 quad_perm:[1,0,3,2] row_mask:0xf bank_mask:0xf bound_ctrl:1
	v_add_f32_dpp v31, v31, v31 quad_perm:[1,0,3,2] row_mask:0xf bank_mask:0xf bound_ctrl:1
	v_add_f32_dpp v22, v22, v22 row_half_mirror row_mask:0xf bank_mask:0xf bound_ctrl:1
	v_add_f32_dpp v23, v23, v23 row_half_mirror row_mask:0xf bank_mask:0xf bound_ctrl:1
	v_add_f32_dpp v30, v30, v30 quad_perm:[2,3,0,1] row_mask:0xf bank_mask:0xf bound_ctrl:1
	v_add_f32_dpp v31, v31, v31 quad_perm:[2,3,0,1] row_mask:0xf bank_mask:0xf bound_ctrl:1
	v_add_f32_dpp v22, v22, v22 row_mirror row_mask:0xf bank_mask:0xf bound_ctrl:1
	v_add_f32_dpp v23, v23, v23 row_mirror row_mask:0xf bank_mask:0xf bound_ctrl:1
	s_waitcnt lgkmcnt(1)
	v_pk_mul_f32 v[24:25], v[26:27], v[22:23] op_sel_hi:[0,1]
	v_add_f32_dpp v30, v30, v30 row_half_mirror row_mask:0xf bank_mask:0xf bound_ctrl:1
	v_add_f32_dpp v31, v31, v31 row_half_mirror row_mask:0xf bank_mask:0xf bound_ctrl:1
	v_pk_fma_f32 v[24:25], v[6:7], v[54:55], v[24:25] op_sel_hi:[0,1,1] neg_lo:[0,0,1] neg_hi:[0,0,1]
	v_add_f32_dpp v30, v30, v30 row_mirror row_mask:0xf bank_mask:0xf bound_ctrl:1
	v_add_f32_dpp v31, v31, v31 row_mirror row_mask:0xf bank_mask:0xf bound_ctrl:1
	s_waitcnt lgkmcnt(0)
	v_pk_fma_f32 v[54:55], v[18:19], v[64:65], v[24:25] op_sel_hi:[0,1,1]
	v_cvt_pk_bf16_f32 v17, v30, v31
	v_pk_mul_f32 v[24:25], v[26:27], v[22:23] op_sel:[1,0]
	ds_write_b32 v14, v17 offset:128
	v_pk_fma_f32 v[6:7], v[6:7], v[50:51], v[24:25] op_sel:[1,0,0] neg_lo:[0,0,1] neg_hi:[0,0,1]
	ds_read_b128 v[30:33], v15 offset:4608
	ds_read_b128 v[34:37], v15 offset:4864
	ds_read_b128 v[38:41], v15 offset:5120
	ds_read_b128 v[42:45], v15 offset:5376
	ds_read_b128 v[46:49], v15 offset:5632
	ds_read_b64 v[58:59], v16 offset:5888
	v_pk_fma_f32 v[50:51], v[18:19], v[64:65], v[6:7] op_sel:[1,0,0]
	v_pk_mul_f32 v[6:7], v[28:29], v[22:23] op_sel_hi:[0,1]
	v_pk_fma_f32 v[6:7], v[8:9], v[56:57], v[6:7] op_sel_hi:[0,1,1] neg_lo:[0,0,1] neg_hi:[0,0,1]
	v_pk_fma_f32 v[56:57], v[20:21], v[64:65], v[6:7] op_sel_hi:[0,1,1]
	v_mov_b32_e32 v6, v9
	v_pk_mul_f32 v[8:9], v[28:29], v[22:23] op_sel:[1,0] op_sel_hi:[1,1]
	s_nop 0
	v_pk_fma_f32 v[6:7], v[6:7], v[52:53], v[8:9] op_sel_hi:[0,1,1] neg_lo:[0,0,1] neg_hi:[0,0,1]
	s_waitcnt lgkmcnt(2)
	v_pk_mul_f32 v[62:63], v[42:43], v[50:51] op_sel:[1,0]
	v_pk_fma_f32 v[52:53], v[20:21], v[64:65], v[6:7] op_sel:[1,0,0] op_sel_hi:[1,1,1]
	v_pk_mul_f32 v[6:7], v[2:3], v[50:51] op_sel:[1,0]
	v_pk_fma_f32 v[42:43], v[42:43], v[54:55], v[62:63] op_sel_hi:[0,1,1]
	v_pk_fma_f32 v[2:3], v[2:3], v[54:55], v[6:7] op_sel_hi:[0,1,1]
	v_pk_mul_f32 v[62:63], v[44:45], v[52:53] op_sel:[1,0] op_sel_hi:[1,1]
	v_pk_mul_f32 v[6:7], v[4:5], v[52:53] op_sel:[1,0] op_sel_hi:[1,1]
	v_pk_fma_f32 v[44:45], v[44:45], v[56:57], v[62:63] op_sel_hi:[0,1,1]
	v_pk_fma_f32 v[4:5], v[4:5], v[56:57], v[6:7] op_sel_hi:[0,1,1]
	v_pk_add_f32 v[42:43], v[42:43], v[44:45]
	v_pk_add_f32 v[2:3], v[2:3], v[4:5]
	s_nop 0
	v_add_f32_dpp v42, v42, v42 quad_perm:[1,0,3,2] row_mask:0xf bank_mask:0xf bound_ctrl:1
	v_add_f32_dpp v43, v43, v43 quad_perm:[1,0,3,2] row_mask:0xf bank_mask:0xf bound_ctrl:1
	v_add_f32_dpp v2, v2, v2 quad_perm:[1,0,3,2] row_mask:0xf bank_mask:0xf bound_ctrl:1
	v_add_f32_dpp v3, v3, v3 quad_perm:[1,0,3,2] row_mask:0xf bank_mask:0xf bound_ctrl:1
	v_add_f32_dpp v42, v42, v42 quad_perm:[2,3,0,1] row_mask:0xf bank_mask:0xf bound_ctrl:1
	v_add_f32_dpp v43, v43, v43 quad_perm:[2,3,0,1] row_mask:0xf bank_mask:0xf bound_ctrl:1
	v_add_f32_dpp v2, v2, v2 quad_perm:[2,3,0,1] row_mask:0xf bank_mask:0xf bound_ctrl:1
	v_add_f32_dpp v3, v3, v3 quad_perm:[2,3,0,1] row_mask:0xf bank_mask:0xf bound_ctrl:1
	v_add_f32_dpp v42, v42, v42 row_half_mirror row_mask:0xf bank_mask:0xf bound_ctrl:1
	v_add_f32_dpp v43, v43, v43 row_half_mirror row_mask:0xf bank_mask:0xf bound_ctrl:1
	v_add_f32_dpp v2, v2, v2 row_half_mirror row_mask:0xf bank_mask:0xf bound_ctrl:1
	v_add_f32_dpp v3, v3, v3 row_half_mirror row_mask:0xf bank_mask:0xf bound_ctrl:1
	v_add_f32_dpp v42, v42, v42 row_mirror row_mask:0xf bank_mask:0xf bound_ctrl:1
	v_add_f32_dpp v43, v43, v43 row_mirror row_mask:0xf bank_mask:0xf bound_ctrl:1
	s_waitcnt lgkmcnt(1)
	v_pk_mul_f32 v[44:45], v[46:47], v[42:43] op_sel_hi:[0,1]
	v_add_f32_dpp v2, v2, v2 row_mirror row_mask:0xf bank_mask:0xf bound_ctrl:1
	v_add_f32_dpp v3, v3, v3 row_mirror row_mask:0xf bank_mask:0xf bound_ctrl:1
	v_pk_fma_f32 v[44:45], v[34:35], v[54:55], v[44:45] op_sel_hi:[0,1,1] neg_lo:[0,0,1] neg_hi:[0,0,1]
	v_cvt_pk_bf16_f32 v2, v2, v3
	s_waitcnt lgkmcnt(0)
; #define LAS __attribute__((address_space(3)))
; DI unsigned pk2(float a, float b) { f32x2 v = {a, b}; bf2_t r = __builtin_convertvector(v, bf2_t); return __builtin_bit_cast(unsigned, r); }
; DI f32x2 red16p(f32x2 x) { float a = x.x, b = x.y; red16x2(a, b); return (f32x2){a, b}; }
; DI void scan_bh2(const Args& a, int l, int bh, int halfsel, LAS unsigned char* lds) {
;     ...
;             for (int st = 0; st < T; ++st) {
;                 f32x4 nr4, nd4, nk4, nkk4, nb4; f32x2 nv2;
;                 if (st < T - 1) {
;                     const LAS float* o = cur + (st + 1) * 384;
;                     nr4 = *(const LAS f32x4*)(o + kq * 4); nd4 = *(const LAS f32x4*)(o + 64 + kq * 4); nk4 = *(const LAS f32x4*)(o + 128 + kq * 4);
;                     nkk4 = *(const LAS f32x4*)(o + 192 + kq * 4); nb4 = *(const LAS f32x4*)(o + 256 + kq * 4); nv2 = *(const LAS f32x2*)(o + 320 + row0);
;                 }
;                 f32x2 sa = S[0] * kk4[0]; sa += S[1] * kk4[1]; f32x2 sb = S[2] * kk4[2]; sb += S[3] * kk4[3]; sa += sb;
;                 sa = red16p(sa); sa = -sa;
; #pragma unroll
;                 for (int j = 0; j < 4; ++j) S[j] = S[j] * d4[j] + sa * b4[j] + v2 * k4[j];
;                 f32x2 y = S[0] * r4[0]; y += S[1] * r4[1]; f32x2 yc = S[2] * r4[2]; yc += S[3] * r4[3]; y += yc;
;                 y = red16p(y);
;                 *(LAS unsigned*)(yb + st * 128 + row0 * 2) = pk2(y.x, y.y);
;                 if (st < T - 1) { r4 = nr4; d4 = nd4; k4 = nk4; kk4 = nkk4; b4 = nb4; v2 = nv2; }
	v_pk_fma_f32 v[54:55], v[38:39], v[58:59], v[44:45] op_sel_hi:[0,1,1]
	v_pk_mul_f32 v[44:45], v[46:47], v[42:43] op_sel:[1,0]
	ds_write_b32 v14, v2 offset:256
	v_pk_fma_f32 v[34:35], v[34:35], v[50:51], v[44:45] op_sel:[1,0,0] neg_lo:[0,0,1] neg_hi:[0,0,1]
	ds_read_b128 v[2:5], v15 offset:6144
	ds_read_b128 v[6:9], v15 offset:6400
	ds_read_b128 v[18:21], v15 offset:6656
	ds_read_b128 v[22:25], v15 offset:6912
	ds_read_b128 v[26:29], v15 offset:7168
	ds_read_b64 v[60:61], v16 offset:7424
	v_pk_fma_f32 v[50:51], v[38:39], v[58:59], v[34:35] op_sel:[1,0,0]
	v_pk_mul_f32 v[34:35], v[48:49], v[42:43] op_sel_hi:[0,1]
	v_pk_fma_f32 v[34:35], v[36:37], v[56:57], v[34:35] op_sel_hi:[0,1,1] neg_lo:[0,0,1] neg_hi:[0,0,1]
	v_pk_fma_f32 v[56:57], v[40:41], v[58:59], v[34:35] op_sel_hi:[0,1,1]
	v_mov_b32_e32 v34, v37
	v_pk_mul_f32 v[36:37], v[48:49], v[42:43] op_sel:[1,0] op_sel_hi:[1,1]
	s_nop 0
	v_pk_fma_f32 v[34:35], v[34:35], v[52:53], v[36:37] op_sel_hi:[0,1,1] neg_lo:[0,0,1] neg_hi:[0,0,1]
	s_waitcnt lgkmcnt(2)
	v_pk_mul_f32 v[62:63], v[22:23], v[50:51] op_sel:[1,0]
	v_pk_fma_f32 v[52:53], v[40:41], v[58:59], v[34:35] op_sel:[1,0,0] op_sel_hi:[1,1,1]
	v_pk_fma_f32 v[22:23], v[22:23], v[54:55], v[62:63] op_sel_hi:[0,1,1]
	v_pk_mul_f32 v[34:35], v[30:31], v[50:51] op_sel:[1,0]
	v_pk_mul_f32 v[62:63], v[24:25], v[52:53] op_sel:[1,0] op_sel_hi:[1,1]
	v_pk_fma_f32 v[30:31], v[30:31], v[54:55], v[34:35] op_sel_hi:[0,1,1]
	v_pk_fma_f32 v[24:25], v[24:25], v[56:57], v[62:63] op_sel_hi:[0,1,1]
	v_pk_mul_f32 v[34:35], v[32:33], v[52:53] op_sel:[1,0] op_sel_hi:[1,1]
	v_pk_add_f32 v[22:23], v[22:23], v[24:25]
	v_pk_fma_f32 v[32:33], v[32:33], v[56:57], v[34:35] op_sel_hi:[0,1,1]
	s_nop 0
	v_add_f32_dpp v22, v22, v22 quad_perm:[1,0,3,2] row_mask:0xf bank_mask:0xf bound_ctrl:1
	v_add_f32_dpp v23, v23, v23 quad_perm:[1,0,3,2] row_mask:0xf bank_mask:0xf bound_ctrl:1
	v_pk_add_f32 v[30:31], v[30:31], v[32:33]
	v_add_f32_dpp v22, v22, v22 quad_perm:[2,3,0,1] row_mask:0xf bank_mask:0xf bound_ctrl:1
	v_add_f32_dpp v23, v23, v23 quad_perm:[2,3,0,1] row_mask:0xf bank_mask:0xf bound_ctrl:1
	v_add_f32_dpp v30, v30, v30 quad_perm:[1,0,3,2] row_mask:0xf bank_mask:0xf bound_ctrl:1
	v_add_f32_dpp v31, v31, v31 quad_perm:[1,0,3,2] row_mask:0xf bank_mask:0xf bound_ctrl:1
	v_add_f32_dpp v22, v22, v22 row_half_mirror row_mask:0xf bank_mask:0xf bound_ctrl:1
	v_add_f32_dpp v23, v23, v23 row_half_mirror row_mask:0xf bank_mask:0xf bound_ctrl:1
	v_add_f32_dpp v30, v30, v30 quad_perm:[2,3,0,1] row_mask:0xf bank_mask:0xf bound_ctrl:1
	v_add_f32_dpp v31, v31, v31 quad_perm:[2,3,0,1] row_mask:0xf bank_mask:0xf bound_ctrl:1
	v_add_f32_dpp v22, v22, v22 row_mirror row_mask:0xf bank_mask:0xf bound_ctrl:1
	v_add_f32_dpp v23, v23, v23 row_mirror row_mask:0xf bank_mask:0xf bound_ctrl:1
	s_waitcnt lgkmcnt(1)
	v_pk_mul_f32 v[24:25], v[26:27], v[22:23] op_sel_hi:[0,1]
	v_add_f32_dpp v30, v30, v30 row_half_mirror row_mask:0xf bank_mask:0xf bound_ctrl:1
	v_add_f32_dpp v31, v31, v31 row_half_mirror row_mask:0xf bank_mask:0xf bound_ctrl:1
	v_pk_fma_f32 v[24:25], v[6:7], v[54:55], v[24:25] op_sel_hi:[0,1,1] neg_lo:[0,0,1] neg_hi:[0,0,1]
	v_add_f32_dpp v30, v30, v30 row_mirror row_mask:0xf bank_mask:0xf bound_ctrl:1
	v_add_f32_dpp v31, v31, v31 row_mirror row_mask:0xf bank_mask:0xf bound_ctrl:1
	s_waitcnt lgkmcnt(0)
	v_pk_fma_f32 v[54:55], v[18:19], v[60:61], v[24:25] op_sel_hi:[0,1,1]
	v_cvt_pk_bf16_f32 v17, v30, v31
	v_pk_mul_f32 v[24:25], v[26:27], v[22:23] op_sel:[1,0]
	ds_write_b32 v14, v17 offset:384
	v_pk_fma_f32 v[6:7], v[6:7], v[50:51], v[24:25] op_sel:[1,0,0] neg_lo:[0,0,1] neg_hi:[0,0,1]
	ds_read_b128 v[30:33], v15 offset:7680
	ds_read_b128 v[34:37], v15 offset:7936
	ds_read_b128 v[38:41], v15 offset:8192
	ds_read_b128 v[42:45], v15 offset:8448
	ds_read_b128 v[46:49], v15 offset:8704
	ds_read_b64 v[58:59], v16 offset:8960
	v_pk_fma_f32 v[50:51], v[18:19], v[60:61], v[6:7] op_sel:[1,0,0]
	v_pk_mul_f32 v[6:7], v[28:29], v[22:23] op_sel_hi:[0,1]
	v_pk_fma_f32 v[6:7], v[8:9], v[56:57], v[6:7] op_sel_hi:[0,1,1] neg_lo:[0,0,1] neg_hi:[0,0,1]
	v_pk_fma_f32 v[56:57], v[20:21], v[60:61], v[6:7] op_sel_hi:[0,1,1]
	v_mov_b32_e32 v6, v9
	v_pk_mul_f32 v[8:9], v[28:29], v[22:23] op_sel:[1,0] op_sel_hi:[1,1]
	s_nop 0
	v_pk_fma_f32 v[6:7], v[6:7], v[52:53], v[8:9] op_sel_hi:[0,1,1] neg_lo:[0,0,1] neg_hi:[0,0,1]
	s_waitcnt lgkmcnt(2)
	v_pk_mul_f32 v[62:63], v[42:43], v[50:51] op_sel:[1,0]
	v_pk_fma_f32 v[52:53], v[20:21], v[60:61], v[6:7] op_sel:[1,0,0] op_sel_hi:[1,1,1]
	v_pk_mul_f32 v[6:7], v[2:3], v[50:51] op_sel:[1,0]
	v_pk_fma_f32 v[42:43], v[42:43], v[54:55], v[62:63] op_sel_hi:[0,1,1]
	v_pk_fma_f32 v[2:3], v[2:3], v[54:55], v[6:7] op_sel_hi:[0,1,1]
	v_pk_mul_f32 v[62:63], v[44:45], v[52:53] op_sel:[1,0] op_sel_hi:[1,1]
	v_pk_mul_f32 v[6:7], v[4:5], v[52:53] op_sel:[1,0] op_sel_hi:[1,1]
	v_pk_fma_f32 v[44:45], v[44:45], v[56:57], v[62:63] op_sel_hi:[0,1,1]
	v_pk_fma_f32 v[4:5], v[4:5], v[56:57], v[6:7] op_sel_hi:[0,1,1]
	v_pk_add_f32 v[42:43], v[42:43], v[44:45]
	v_pk_add_f32 v[2:3], v[2:3], v[4:5]
	s_nop 0
	v_add_f32_dpp v42, v42, v42 quad_perm:[1,0,3,2] row_mask:0xf bank_mask:0xf bound_ctrl:1
	v_add_f32_dpp v43, v43, v43 quad_perm:[1,0,3,2] row_mask:0xf bank_mask:0xf bound_ctrl:1
	v_add_f32_dpp v2, v2, v2 quad_perm:[1,0,3,2] row_mask:0xf bank_mask:0xf bound_ctrl:1
	v_add_f32_dpp v3, v3, v3 quad_perm:[1,0,3,2] row_mask:0xf bank_mask:0xf bound_ctrl:1
	v_add_f32_dpp v42, v42, v42 quad_perm:[2,3,0,1] row_mask:0xf bank_mask:0xf bound_ctrl:1
	v_add_f32_dpp v43, v43, v43 quad_perm:[2,3,0,1] row_mask:0xf bank_mask:0xf bound_ctrl:1
	v_add_f32_dpp v2, v2, v2 quad_perm:[2,3,0,1] row_mask:0xf bank_mask:0xf bound_ctrl:1
	v_add_f32_dpp v3, v3, v3 quad_perm:[2,3,0,1] row_mask:0xf bank_mask:0xf bound_ctrl:1
	v_add_f32_dpp v42, v42, v42 row_half_mirror row_mask:0xf bank_mask:0xf bound_ctrl:1
	v_add_f32_dpp v43, v43, v43 row_half_mirror row_mask:0xf bank_mask:0xf bound_ctrl:1
	v_add_f32_dpp v2, v2, v2 row_half_mirror row_mask:0xf bank_mask:0xf bound_ctrl:1
	v_add_f32_dpp v3, v3, v3 row_half_mirror row_mask:0xf bank_mask:0xf bound_ctrl:1
	v_add_f32_dpp v42, v42, v42 row_mirror row_mask:0xf bank_mask:0xf bound_ctrl:1
	v_add_f32_dpp v43, v43, v43 row_mirror row_mask:0xf bank_mask:0xf bound_ctrl:1
	s_waitcnt lgkmcnt(1)
; #define LAS __attribute__((address_space(3)))
; DI unsigned pk2(float a, float b) { f32x2 v = {a, b}; bf2_t r = __builtin_convertvector(v, bf2_t); return __builtin_bit_cast(unsigned, r); }
; DI f32x2 red16p(f32x2 x) { float a = x.x, b = x.y; red16x2(a, b); return (f32x2){a, b}; }
; DI void scan_bh2(const Args& a, int l, int bh, int halfsel, LAS unsigned char* lds) {
;     ...
;             for (int st = 0; st < T; ++st) {
;                 f32x4 nr4, nd4, nk4, nkk4, nb4; f32x2 nv2;
;                 if (st < T - 1) {
;                     const LAS float* o = cur + (st + 1) * 384;
;                     nr4 = *(const LAS f32x4*)(o + kq * 4); nd4 = *(const LAS f32x4*)(o + 64 + kq * 4); nk4 = *(const LAS f32x4*)(o + 128 + kq * 4);
;                     nkk4 = *(const LAS f32x4*)(o + 192 + kq * 4); nb4 = *(const LAS f32x4*)(o + 256 + kq * 4); nv2 = *(const LAS f32x2*)(o + 320 + row0);
;                 }
;                 f32x2 sa = S[0] * kk4[0]; sa += S[1] * kk4[1]; f32x2 sb = S[2] * kk4[2]; sb += S[3] * kk4[3]; sa += sb;
;                 sa = red16p(sa); sa = -sa;
; #pragma unroll
;                 for (int j = 0; j < 4; ++j) S[j] = S[j] * d4[j] + sa * b4[j] + v2 * k4[j];
;                 f32x2 y = S[0] * r4[0]; y += S[1] * r4[1]; f32x2 yc = S[2] * r4[2]; yc += S[3] * r4[3]; y += yc;
;                 y = red16p(y);
;                 *(LAS unsigned*)(yb + st * 128 + row0 * 2) = pk2(y.x, y.y);
;                 if (st < T - 1) { r4 = nr4; d4 = nd4; k4 = nk4; kk4 = nkk4; b4 = nb4; v2 = nv2; }
	v_pk_mul_f32 v[44:45], v[46:47], v[42:43] op_sel_hi:[0,1]
	v_add_f32_dpp v2, v2, v2 row_mirror row_mask:0xf bank_mask:0xf bound_ctrl:1
	v_add_f32_dpp v3, v3, v3 row_mirror row_mask:0xf bank_mask:0xf bound_ctrl:1
	v_pk_fma_f32 v[44:45], v[34:35], v[54:55], v[44:45] op_sel_hi:[0,1,1] neg_lo:[0,0,1] neg_hi:[0,0,1]
	v_cvt_pk_bf16_f32 v2, v2, v3
	s_waitcnt lgkmcnt(0)
	v_pk_fma_f32 v[54:55], v[38:39], v[58:59], v[44:45] op_sel_hi:[0,1,1]
	v_pk_mul_f32 v[44:45], v[46:47], v[42:43] op_sel:[1,0]
	ds_write_b32 v14, v2 offset:512
	v_pk_fma_f32 v[34:35], v[34:35], v[50:51], v[44:45] op_sel:[1,0,0] neg_lo:[0,0,1] neg_hi:[0,0,1]
	ds_read_b128 v[2:5], v15 offset:9216
	ds_read_b128 v[6:9], v15 offset:9472
	ds_read_b128 v[18:21], v15 offset:9728
	ds_read_b128 v[22:25], v15 offset:9984
	ds_read_b128 v[26:29], v15 offset:10240
	ds_read_b64 v[60:61], v16 offset:10496
	v_pk_fma_f32 v[50:51], v[38:39], v[58:59], v[34:35] op_sel:[1,0,0]
	v_pk_mul_f32 v[34:35], v[48:49], v[42:43] op_sel_hi:[0,1]
	v_pk_fma_f32 v[34:35], v[36:37], v[56:57], v[34:35] op_sel_hi:[0,1,1] neg_lo:[0,0,1] neg_hi:[0,0,1]
	v_pk_fma_f32 v[56:57], v[40:41], v[58:59], v[34:35] op_sel_hi:[0,1,1]
	v_mov_b32_e32 v34, v37
	v_pk_mul_f32 v[36:37], v[48:49], v[42:43] op_sel:[1,0] op_sel_hi:[1,1]
	s_nop 0
	v_pk_fma_f32 v[34:35], v[34:35], v[52:53], v[36:37] op_sel_hi:[0,1,1] neg_lo:[0,0,1] neg_hi:[0,0,1]
	s_waitcnt lgkmcnt(2)
	v_pk_mul_f32 v[62:63], v[22:23], v[50:51] op_sel:[1,0]
	v_pk_fma_f32 v[52:53], v[40:41], v[58:59], v[34:35] op_sel:[1,0,0] op_sel_hi:[1,1,1]
	v_pk_fma_f32 v[22:23], v[22:23], v[54:55], v[62:63] op_sel_hi:[0,1,1]
	v_pk_mul_f32 v[34:35], v[30:31], v[50:51] op_sel:[1,0]
	v_pk_mul_f32 v[62:63], v[24:25], v[52:53] op_sel:[1,0] op_sel_hi:[1,1]
	v_pk_fma_f32 v[30:31], v[30:31], v[54:55], v[34:35] op_sel_hi:[0,1,1]
	v_pk_fma_f32 v[24:25], v[24:25], v[56:57], v[62:63] op_sel_hi:[0,1,1]
	v_pk_mul_f32 v[34:35], v[32:33], v[52:53] op_sel:[1,0] op_sel_hi:[1,1]
	v_pk_add_f32 v[22:23], v[22:23], v[24:25]
	v_pk_fma_f32 v[32:33], v[32:33], v[56:57], v[34:35] op_sel_hi:[0,1,1]
	s_nop 0
	v_add_f32_dpp v22, v22, v22 quad_perm:[1,0,3,2] row_mask:0xf bank_mask:0xf bound_ctrl:1
	v_add_f32_dpp v23, v23, v23 quad_perm:[1,0,3,2] row_mask:0xf bank_mask:0xf bound_ctrl:1
	v_pk_add_f32 v[30:31], v[30:31], v[32:33]
	v_add_f32_dpp v22, v22, v22 quad_perm:[2,3,0,1] row_mask:0xf bank_mask:0xf bound_ctrl:1
	v_add_f32_dpp v23, v23, v23 quad_perm:[2,3,0,1] row_mask:0xf bank_mask:0xf bound_ctrl:1
	v_add_f32_dpp v30, v30, v30 quad_perm:[1,0,3,2] row_mask:0xf bank_mask:0xf bound_ctrl:1
	v_add_f32_dpp v31, v31, v31 quad_perm:[1,0,3,2] row_mask:0xf bank_mask:0xf bound_ctrl:1
	v_add_f32_dpp v22, v22, v22 row_half_mirror row_mask:0xf bank_mask:0xf bound_ctrl:1
	v_add_f32_dpp v23, v23, v23 row_half_mirror row_mask:0xf bank_mask:0xf bound_ctrl:1
	v_add_f32_dpp v30, v30, v30 quad_perm:[2,3,0,1] row_mask:0xf bank_mask:0xf bound_ctrl:1
	v_add_f32_dpp v31, v31, v31 quad_perm:[2,3,0,1] row_mask:0xf bank_mask:0xf bound_ctrl:1
	v_add_f32_dpp v22, v22, v22 row_mirror row_mask:0xf bank_mask:0xf bound_ctrl:1
	v_add_f32_dpp v23, v23, v23 row_mirror row_mask:0xf bank_mask:0xf bound_ctrl:1
	s_waitcnt lgkmcnt(1)
	v_pk_mul_f32 v[24:25], v[26:27], v[22:23] op_sel_hi:[0,1]
	v_add_f32_dpp v30, v30, v30 row_half_mirror row_mask:0xf bank_mask:0xf bound_ctrl:1
	v_add_f32_dpp v31, v31, v31 row_half_mirror row_mask:0xf bank_mask:0xf bound_ctrl:1
	v_pk_fma_f32 v[24:25], v[6:7], v[54:55], v[24:25] op_sel_hi:[0,1,1] neg_lo:[0,0,1] neg_hi:[0,0,1]
	v_add_f32_dpp v30, v30, v30 row_mirror row_mask:0xf bank_mask:0xf bound_ctrl:1
	v_add_f32_dpp v31, v31, v31 row_mirror row_mask:0xf bank_mask:0xf bound_ctrl:1
	s_waitcnt lgkmcnt(0)
	v_pk_fma_f32 v[54:55], v[18:19], v[60:61], v[24:25] op_sel_hi:[0,1,1]
	v_cvt_pk_bf16_f32 v17, v30, v31
	v_pk_mul_f32 v[24:25], v[26:27], v[22:23] op_sel:[1,0]
	ds_write_b32 v14, v17 offset:640
	v_pk_fma_f32 v[6:7], v[6:7], v[50:51], v[24:25] op_sel:[1,0,0] neg_lo:[0,0,1] neg_hi:[0,0,1]
	ds_read_b128 v[30:33], v15 offset:10752
	ds_read_b128 v[34:37], v15 offset:11008
	ds_read_b128 v[38:41], v15 offset:11264
	ds_read_b128 v[42:45], v15 offset:11520
	ds_read_b128 v[46:49], v15 offset:11776
	ds_read_b64 v[58:59], v16 offset:12032
	v_pk_fma_f32 v[50:51], v[18:19], v[60:61], v[6:7] op_sel:[1,0,0]
	v_pk_mul_f32 v[6:7], v[28:29], v[22:23] op_sel_hi:[0,1]
	v_pk_fma_f32 v[6:7], v[8:9], v[56:57], v[6:7] op_sel_hi:[0,1,1] neg_lo:[0,0,1] neg_hi:[0,0,1]
	v_pk_fma_f32 v[56:57], v[20:21], v[60:61], v[6:7] op_sel_hi:[0,1,1]
	v_mov_b32_e32 v6, v9
	v_pk_mul_f32 v[8:9], v[28:29], v[22:23] op_sel:[1,0] op_sel_hi:[1,1]
	s_nop 0
	v_pk_fma_f32 v[6:7], v[6:7], v[52:53], v[8:9] op_sel_hi:[0,1,1] neg_lo:[0,0,1] neg_hi:[0,0,1]
	s_waitcnt lgkmcnt(2)
; #define LAS __attribute__((address_space(3)))
; DI unsigned pk2(float a, float b) { f32x2 v = {a, b}; bf2_t r = __builtin_convertvector(v, bf2_t); return __builtin_bit_cast(unsigned, r); }
; DI f32x2 red16p(f32x2 x) { float a = x.x, b = x.y; red16x2(a, b); return (f32x2){a, b}; }
; DI void scan_bh2(const Args& a, int l, int bh, int halfsel, LAS unsigned char* lds) {
;     ...
;             for (int st = 0; st < T; ++st) {
;                 f32x4 nr4, nd4, nk4, nkk4, nb4; f32x2 nv2;
;                 if (st < T - 1) {
;                     const LAS float* o = cur + (st + 1) * 384;
;                     nr4 = *(const LAS f32x4*)(o + kq * 4); nd4 = *(const LAS f32x4*)(o + 64 + kq * 4); nk4 = *(const LAS f32x4*)(o + 128 + kq * 4);
;                     nkk4 = *(const LAS f32x4*)(o + 192 + kq * 4); nb4 = *(const LAS f32x4*)(o + 256 + kq * 4); nv2 = *(const LAS f32x2*)(o + 320 + row0);
;                 }
;                 f32x2 sa = S[0] * kk4[0]; sa += S[1] * kk4[1]; f32x2 sb = S[2] * kk4[2]; sb += S[3] * kk4[3]; sa += sb;
;                 sa = red16p(sa); sa = -sa;
; #pragma unroll
;                 for (int j = 0; j < 4; ++j) S[j] = S[j] * d4[j] + sa * b4[j] + v2 * k4[j];
;                 f32x2 y = S[0] * r4[0]; y += S[1] * r4[1]; f32x2 yc = S[2] * r4[2]; yc += S[3] * r4[3]; y += yc;
;                 y = red16p(y);
;                 *(LAS unsigned*)(yb + st * 128 + row0 * 2) = pk2(y.x, y.y);
;                 if (st < T - 1) { r4 = nr4; d4 = nd4; k4 = nk4; kk4 = nkk4; b4 = nb4; v2 = nv2; }
	v_pk_mul_f32 v[62:63], v[42:43], v[50:51] op_sel:[1,0]
	v_pk_fma_f32 v[52:53], v[20:21], v[60:61], v[6:7] op_sel:[1,0,0] op_sel_hi:[1,1,1]
	v_pk_mul_f32 v[6:7], v[2:3], v[50:51] op_sel:[1,0]
	v_pk_fma_f32 v[42:43], v[42:43], v[54:55], v[62:63] op_sel_hi:[0,1,1]
	v_pk_fma_f32 v[2:3], v[2:3], v[54:55], v[6:7] op_sel_hi:[0,1,1]
	v_pk_mul_f32 v[62:63], v[44:45], v[52:53] op_sel:[1,0] op_sel_hi:[1,1]
	v_pk_mul_f32 v[6:7], v[4:5], v[52:53] op_sel:[1,0] op_sel_hi:[1,1]
	v_pk_fma_f32 v[44:45], v[44:45], v[56:57], v[62:63] op_sel_hi:[0,1,1]
	v_pk_fma_f32 v[4:5], v[4:5], v[56:57], v[6:7] op_sel_hi:[0,1,1]
	v_pk_add_f32 v[42:43], v[42:43], v[44:45]
	v_pk_add_f32 v[2:3], v[2:3], v[4:5]
	s_nop 0
	v_add_f32_dpp v42, v42, v42 quad_perm:[1,0,3,2] row_mask:0xf bank_mask:0xf bound_ctrl:1
	v_add_f32_dpp v43, v43, v43 quad_perm:[1,0,3,2] row_mask:0xf bank_mask:0xf bound_ctrl:1
	v_add_f32_dpp v2, v2, v2 quad_perm:[1,0,3,2] row_mask:0xf bank_mask:0xf bound_ctrl:1
	v_add_f32_dpp v3, v3, v3 quad_perm:[1,0,3,2] row_mask:0xf bank_mask:0xf bound_ctrl:1
	v_add_f32_dpp v42, v42, v42 quad_perm:[2,3,0,1] row_mask:0xf bank_mask:0xf bound_ctrl:1
	v_add_f32_dpp v43, v43, v43 quad_perm:[2,3,0,1] row_mask:0xf bank_mask:0xf bound_ctrl:1
	v_add_f32_dpp v2, v2, v2 quad_perm:[2,3,0,1] row_mask:0xf bank_mask:0xf bound_ctrl:1
	v_add_f32_dpp v3, v3, v3 quad_perm:[2,3,0,1] row_mask:0xf bank_mask:0xf bound_ctrl:1
	v_add_f32_dpp v42, v42, v42 row_half_mirror row_mask:0xf bank_mask:0xf bound_ctrl:1
	v_add_f32_dpp v43, v43, v43 row_half_mirror row_mask:0xf bank_mask:0xf bound_ctrl:1
	v_add_f32_dpp v2, v2, v2 row_half_mirror row_mask:0xf bank_mask:0xf bound_ctrl:1
	v_add_f32_dpp v3, v3, v3 row_half_mirror row_mask:0xf bank_mask:0xf bound_ctrl:1
	v_add_f32_dpp v42, v42, v42 row_mirror row_mask:0xf bank_mask:0xf bound_ctrl:1
	v_add_f32_dpp v43, v43, v43 row_mirror row_mask:0xf bank_mask:0xf bound_ctrl:1
	s_waitcnt lgkmcnt(1)
	v_pk_mul_f32 v[44:45], v[46:47], v[42:43] op_sel_hi:[0,1]
	v_add_f32_dpp v2, v2, v2 row_mirror row_mask:0xf bank_mask:0xf bound_ctrl:1
	v_add_f32_dpp v3, v3, v3 row_mirror row_mask:0xf bank_mask:0xf bound_ctrl:1
	v_pk_fma_f32 v[44:45], v[34:35], v[54:55], v[44:45] op_sel_hi:[0,1,1] neg_lo:[0,0,1] neg_hi:[0,0,1]
	v_cvt_pk_bf16_f32 v2, v2, v3
	s_waitcnt lgkmcnt(0)
	v_pk_fma_f32 v[54:55], v[38:39], v[58:59], v[44:45] op_sel_hi:[0,1,1]
	v_pk_mul_f32 v[44:45], v[46:47], v[42:43] op_sel:[1,0]
	ds_write_b32 v14, v2 offset:768
	v_pk_fma_f32 v[34:35], v[34:35], v[50:51], v[44:45] op_sel:[1,0,0] neg_lo:[0,0,1] neg_hi:[0,0,1]
	ds_read_b128 v[2:5], v15 offset:12288
	ds_read_b128 v[6:9], v15 offset:12544
	ds_read_b128 v[18:21], v15 offset:12800
	ds_read_b128 v[22:25], v15 offset:13056
	ds_read_b128 v[26:29], v15 offset:13312
	ds_read_b64 v[60:61], v16 offset:13568
	v_pk_fma_f32 v[50:51], v[38:39], v[58:59], v[34:35] op_sel:[1,0,0]
	v_pk_mul_f32 v[34:35], v[48:49], v[42:43] op_sel_hi:[0,1]
	v_pk_fma_f32 v[34:35], v[36:37], v[56:57], v[34:35] op_sel_hi:[0,1,1] neg_lo:[0,0,1] neg_hi:[0,0,1]
	v_pk_fma_f32 v[56:57], v[40:41], v[58:59], v[34:35] op_sel_hi:[0,1,1]
	v_mov_b32_e32 v34, v37
	v_pk_mul_f32 v[36:37], v[48:49], v[42:43] op_sel:[1,0] op_sel_hi:[1,1]
	s_nop 0
	v_pk_fma_f32 v[34:35], v[34:35], v[52:53], v[36:37] op_sel_hi:[0,1,1] neg_lo:[0,0,1] neg_hi:[0,0,1]
	s_waitcnt lgkmcnt(2)
	v_pk_mul_f32 v[62:63], v[22:23], v[50:51] op_sel:[1,0]
	v_pk_fma_f32 v[52:53], v[40:41], v[58:59], v[34:35] op_sel:[1,0,0] op_sel_hi:[1,1,1]
	v_pk_fma_f32 v[22:23], v[22:23], v[54:55], v[62:63] op_sel_hi:[0,1,1]
	v_pk_mul_f32 v[34:35], v[30:31], v[50:51] op_sel:[1,0]
	v_pk_mul_f32 v[62:63], v[24:25], v[52:53] op_sel:[1,0] op_sel_hi:[1,1]
	v_pk_fma_f32 v[30:31], v[30:31], v[54:55], v[34:35] op_sel_hi:[0,1,1]
	v_pk_fma_f32 v[24:25], v[24:25], v[56:57], v[62:63] op_sel_hi:[0,1,1]
	v_pk_mul_f32 v[34:35], v[32:33], v[52:53] op_sel:[1,0] op_sel_hi:[1,1]
	v_pk_add_f32 v[22:23], v[22:23], v[24:25]
	v_pk_fma_f32 v[32:33], v[32:33], v[56:57], v[34:35] op_sel_hi:[0,1,1]
	s_nop 0
	v_add_f32_dpp v22, v22, v22 quad_perm:[1,0,3,2] row_mask:0xf bank_mask:0xf bound_ctrl:1
	v_add_f32_dpp v23, v23, v23 quad_perm:[1,0,3,2] row_mask:0xf bank_mask:0xf bound_ctrl:1
	v_pk_add_f32 v[30:31], v[30:31], v[32:33]
	v_add_f32_dpp v22, v22, v22 quad_perm:[2,3,0,1] row_mask:0xf bank_mask:0xf bound_ctrl:1
	v_add_f32_dpp v23, v23, v23 quad_perm:[2,3,0,1] row_mask:0xf bank_mask:0xf bound_ctrl:1
	v_add_f32_dpp v30, v30, v30 quad_perm:[1,0,3,2] row_mask:0xf bank_mask:0xf bound_ctrl:1
	v_add_f32_dpp v31, v31, v31 quad_perm:[1,0,3,2] row_mask:0xf bank_mask:0xf bound_ctrl:1
	v_add_f32_dpp v22, v22, v22 row_half_mirror row_mask:0xf bank_mask:0xf bound_ctrl:1
	v_add_f32_dpp v23, v23, v23 row_half_mirror row_mask:0xf bank_mask:0xf bound_ctrl:1
	v_add_f32_dpp v30, v30, v30 quad_perm:[2,3,0,1] row_mask:0xf bank_mask:0xf bound_ctrl:1
	v_add_f32_dpp v31, v31, v31 quad_perm:[2,3,0,1] row_mask:0xf bank_mask:0xf bound_ctrl:1
	v_add_f32_dpp v22, v22, v22 row_mirror row_mask:0xf bank_mask:0xf bound_ctrl:1
	v_add_f32_dpp v23, v23, v23 row_mirror row_mask:0xf bank_mask:0xf bound_ctrl:1
	s_waitcnt lgkmcnt(1)
	v_pk_mul_f32 v[24:25], v[26:27], v[22:23] op_sel_hi:[0,1]
	v_add_f32_dpp v30, v30, v30 row_half_mirror row_mask:0xf bank_mask:0xf bound_ctrl:1
	v_add_f32_dpp v31, v31, v31 row_half_mirror row_mask:0xf bank_mask:0xf bound_ctrl:1
	v_pk_fma_f32 v[24:25], v[6:7], v[54:55], v[24:25] op_sel_hi:[0,1,1] neg_lo:[0,0,1] neg_hi:[0,0,1]
	v_add_f32_dpp v30, v30, v30 row_mirror row_mask:0xf bank_mask:0xf bound_ctrl:1
	v_add_f32_dpp v31, v31, v31 row_mirror row_mask:0xf bank_mask:0xf bound_ctrl:1
	s_waitcnt lgkmcnt(0)
; #define LAS __attribute__((address_space(3)))
; DI unsigned pk2(float a, float b) { f32x2 v = {a, b}; bf2_t r = __builtin_convertvector(v, bf2_t); return __builtin_bit_cast(unsigned, r); }
; DI f32x2 red16p(f32x2 x) { float a = x.x, b = x.y; red16x2(a, b); return (f32x2){a, b}; }
; DI void scan_bh2(const Args& a, int l, int bh, int halfsel, LAS unsigned char* lds) {
;     ...
;             for (int st = 0; st < T; ++st) {
;                 f32x4 nr4, nd4, nk4, nkk4, nb4; f32x2 nv2;
;                 if (st < T - 1) {
;                     const LAS float* o = cur + (st + 1) * 384;
;                     nr4 = *(const LAS f32x4*)(o + kq * 4); nd4 = *(const LAS f32x4*)(o + 64 + kq * 4); nk4 = *(const LAS f32x4*)(o + 128 + kq * 4);
;                     nkk4 = *(const LAS f32x4*)(o + 192 + kq * 4); nb4 = *(const LAS f32x4*)(o + 256 + kq * 4); nv2 = *(const LAS f32x2*)(o + 320 + row0);
;                 }
;                 f32x2 sa = S[0] * kk4[0]; sa += S[1] * kk4[1]; f32x2 sb = S[2] * kk4[2]; sb += S[3] * kk4[3]; sa += sb;
;                 sa = red16p(sa); sa = -sa;
; #pragma unroll
;                 for (int j = 0; j < 4; ++j) S[j] = S[j] * d4[j] + sa * b4[j] + v2 * k4[j];
;                 f32x2 y = S[0] * r4[0]; y += S[1] * r4[1]; f32x2 yc = S[2] * r4[2]; yc += S[3] * r4[3]; y += yc;
;                 y = red16p(y);
;                 *(LAS unsigned*)(yb + st * 128 + row0 * 2) = pk2(y.x, y.y);
;                 if (st < T - 1) { r4 = nr4; d4 = nd4; k4 = nk4; kk4 = nkk4; b4 = nb4; v2 = nv2; }
	v_pk_fma_f32 v[54:55], v[18:19], v[60:61], v[24:25] op_sel_hi:[0,1,1]
	v_cvt_pk_bf16_f32 v17, v30, v31
	v_pk_mul_f32 v[24:25], v[26:27], v[22:23] op_sel:[1,0]
	ds_write_b32 v14, v17 offset:896
	v_pk_fma_f32 v[6:7], v[6:7], v[50:51], v[24:25] op_sel:[1,0,0] neg_lo:[0,0,1] neg_hi:[0,0,1]
	ds_read_b128 v[30:33], v15 offset:13824
	ds_read_b128 v[34:37], v15 offset:14080
	ds_read_b128 v[38:41], v15 offset:14336
	ds_read_b128 v[42:45], v15 offset:14592
	ds_read_b128 v[46:49], v15 offset:14848
	ds_read_b64 v[58:59], v16 offset:15104
	v_pk_fma_f32 v[50:51], v[18:19], v[60:61], v[6:7] op_sel:[1,0,0]
	v_pk_mul_f32 v[6:7], v[28:29], v[22:23] op_sel_hi:[0,1]
	v_pk_fma_f32 v[6:7], v[8:9], v[56:57], v[6:7] op_sel_hi:[0,1,1] neg_lo:[0,0,1] neg_hi:[0,0,1]
	v_pk_fma_f32 v[56:57], v[20:21], v[60:61], v[6:7] op_sel_hi:[0,1,1]
	v_mov_b32_e32 v6, v9
	v_pk_mul_f32 v[8:9], v[28:29], v[22:23] op_sel:[1,0] op_sel_hi:[1,1]
	s_nop 0
	v_pk_fma_f32 v[6:7], v[6:7], v[52:53], v[8:9] op_sel_hi:[0,1,1] neg_lo:[0,0,1] neg_hi:[0,0,1]
	s_waitcnt lgkmcnt(2)
	v_pk_mul_f32 v[62:63], v[42:43], v[50:51] op_sel:[1,0]
	v_pk_fma_f32 v[52:53], v[20:21], v[60:61], v[6:7] op_sel:[1,0,0] op_sel_hi:[1,1,1]
	v_pk_mul_f32 v[6:7], v[2:3], v[50:51] op_sel:[1,0]
	v_pk_fma_f32 v[42:43], v[42:43], v[54:55], v[62:63] op_sel_hi:[0,1,1]
	v_pk_fma_f32 v[2:3], v[2:3], v[54:55], v[6:7] op_sel_hi:[0,1,1]
	v_pk_mul_f32 v[62:63], v[44:45], v[52:53] op_sel:[1,0] op_sel_hi:[1,1]
	v_pk_mul_f32 v[6:7], v[4:5], v[52:53] op_sel:[1,0] op_sel_hi:[1,1]
	v_pk_fma_f32 v[44:45], v[44:45], v[56:57], v[62:63] op_sel_hi:[0,1,1]
	v_pk_fma_f32 v[4:5], v[4:5], v[56:57], v[6:7] op_sel_hi:[0,1,1]
	v_pk_add_f32 v[42:43], v[42:43], v[44:45]
	v_pk_add_f32 v[2:3], v[2:3], v[4:5]
	s_nop 0
	v_add_f32_dpp v42, v42, v42 quad_perm:[1,0,3,2] row_mask:0xf bank_mask:0xf bound_ctrl:1
	v_add_f32_dpp v43, v43, v43 quad_perm:[1,0,3,2] row_mask:0xf bank_mask:0xf bound_ctrl:1
	v_add_f32_dpp v2, v2, v2 quad_perm:[1,0,3,2] row_mask:0xf bank_mask:0xf bound_ctrl:1
	v_add_f32_dpp v3, v3, v3 quad_perm:[1,0,3,2] row_mask:0xf bank_mask:0xf bound_ctrl:1
	v_add_f32_dpp v42, v42, v42 quad_perm:[2,3,0,1] row_mask:0xf bank_mask:0xf bound_ctrl:1
	v_add_f32_dpp v43, v43, v43 quad_perm:[2,3,0,1] row_mask:0xf bank_mask:0xf bound_ctrl:1
	v_add_f32_dpp v2, v2, v2 quad_perm:[2,3,0,1] row_mask:0xf bank_mask:0xf bound_ctrl:1
	v_add_f32_dpp v3, v3, v3 quad_perm:[2,3,0,1] row_mask:0xf bank_mask:0xf bound_ctrl:1
	v_add_f32_dpp v42, v42, v42 row_half_mirror row_mask:0xf bank_mask:0xf bound_ctrl:1
	v_add_f32_dpp v43, v43, v43 row_half_mirror row_mask:0xf bank_mask:0xf bound_ctrl:1
	v_add_f32_dpp v2, v2, v2 row_half_mirror row_mask:0xf bank_mask:0xf bound_ctrl:1
	v_add_f32_dpp v3, v3, v3 row_half_mirror row_mask:0xf bank_mask:0xf bound_ctrl:1
	v_add_f32_dpp v42, v42, v42 row_mirror row_mask:0xf bank_mask:0xf bound_ctrl:1
	v_add_f32_dpp v43, v43, v43 row_mirror row_mask:0xf bank_mask:0xf bound_ctrl:1
	s_waitcnt lgkmcnt(1)
	v_pk_mul_f32 v[44:45], v[46:47], v[42:43] op_sel_hi:[0,1]
	v_add_f32_dpp v2, v2, v2 row_mirror row_mask:0xf bank_mask:0xf bound_ctrl:1
	v_add_f32_dpp v3, v3, v3 row_mirror row_mask:0xf bank_mask:0xf bound_ctrl:1
	v_pk_fma_f32 v[44:45], v[34:35], v[54:55], v[44:45] op_sel_hi:[0,1,1] neg_lo:[0,0,1] neg_hi:[0,0,1]
	v_cvt_pk_bf16_f32 v2, v2, v3
	s_waitcnt lgkmcnt(0)
	v_pk_fma_f32 v[54:55], v[38:39], v[58:59], v[44:45] op_sel_hi:[0,1,1]
	v_pk_mul_f32 v[44:45], v[46:47], v[42:43] op_sel:[1,0]
	ds_write_b32 v14, v2 offset:1024
	v_pk_fma_f32 v[34:35], v[34:35], v[50:51], v[44:45] op_sel:[1,0,0] neg_lo:[0,0,1] neg_hi:[0,0,1]
	ds_read_b128 v[2:5], v15 offset:15360
	ds_read_b128 v[6:9], v15 offset:15616
	ds_read_b128 v[18:21], v15 offset:15872
	ds_read_b128 v[22:25], v15 offset:16128
	ds_read_b128 v[26:29], v15 offset:16384
	ds_read_b64 v[60:61], v16 offset:16640
	v_pk_fma_f32 v[50:51], v[38:39], v[58:59], v[34:35] op_sel:[1,0,0]
	v_pk_mul_f32 v[34:35], v[48:49], v[42:43] op_sel_hi:[0,1]
	v_pk_fma_f32 v[34:35], v[36:37], v[56:57], v[34:35] op_sel_hi:[0,1,1] neg_lo:[0,0,1] neg_hi:[0,0,1]
	v_pk_fma_f32 v[56:57], v[40:41], v[58:59], v[34:35] op_sel_hi:[0,1,1]
	v_mov_b32_e32 v34, v37
	v_pk_mul_f32 v[36:37], v[48:49], v[42:43] op_sel:[1,0] op_sel_hi:[1,1]
	s_nop 0
	v_pk_fma_f32 v[34:35], v[34:35], v[52:53], v[36:37] op_sel_hi:[0,1,1] neg_lo:[0,0,1] neg_hi:[0,0,1]
	s_waitcnt lgkmcnt(2)
	v_pk_mul_f32 v[62:63], v[22:23], v[50:51] op_sel:[1,0]
	v_pk_fma_f32 v[52:53], v[40:41], v[58:59], v[34:35] op_sel:[1,0,0] op_sel_hi:[1,1,1]
	v_pk_fma_f32 v[22:23], v[22:23], v[54:55], v[62:63] op_sel_hi:[0,1,1]
	v_pk_mul_f32 v[34:35], v[30:31], v[50:51] op_sel:[1,0]
	v_pk_mul_f32 v[62:63], v[24:25], v[52:53] op_sel:[1,0] op_sel_hi:[1,1]
	v_pk_fma_f32 v[30:31], v[30:31], v[54:55], v[34:35] op_sel_hi:[0,1,1]
	v_pk_fma_f32 v[24:25], v[24:25], v[56:57], v[62:63] op_sel_hi:[0,1,1]
	v_pk_mul_f32 v[34:35], v[32:33], v[52:53] op_sel:[1,0] op_sel_hi:[1,1]
	v_pk_add_f32 v[22:23], v[22:23], v[24:25]
	v_pk_fma_f32 v[32:33], v[32:33], v[56:57], v[34:35] op_sel_hi:[0,1,1]
	s_nop 0
	v_add_f32_dpp v22, v22, v22 quad_perm:[1,0,3,2] row_mask:0xf bank_mask:0xf bound_ctrl:1
	v_add_f32_dpp v23, v23, v23 quad_perm:[1,0,3,2] row_mask:0xf bank_mask:0xf bound_ctrl:1
	v_pk_add_f32 v[30:31], v[30:31], v[32:33]
	v_add_f32_dpp v22, v22, v22 quad_perm:[2,3,0,1] row_mask:0xf bank_mask:0xf bound_ctrl:1
	v_add_f32_dpp v23, v23, v23 quad_perm:[2,3,0,1] row_mask:0xf bank_mask:0xf bound_ctrl:1
	v_add_f32_dpp v30, v30, v30 quad_perm:[1,0,3,2] row_mask:0xf bank_mask:0xf bound_ctrl:1
	v_add_f32_dpp v31, v31, v31 quad_perm:[1,0,3,2] row_mask:0xf bank_mask:0xf bound_ctrl:1
	v_add_f32_dpp v22, v22, v22 row_half_mirror row_mask:0xf bank_mask:0xf bound_ctrl:1
	v_add_f32_dpp v23, v23, v23 row_half_mirror row_mask:0xf bank_mask:0xf bound_ctrl:1
	v_add_f32_dpp v30, v30, v30 quad_perm:[2,3,0,1] row_mask:0xf bank_mask:0xf bound_ctrl:1
	v_add_f32_dpp v31, v31, v31 quad_perm:[2,3,0,1] row_mask:0xf bank_mask:0xf bound_ctrl:1
	v_add_f32_dpp v22, v22, v22 row_mirror row_mask:0xf bank_mask:0xf bound_ctrl:1
	v_add_f32_dpp v23, v23, v23 row_mirror row_mask:0xf bank_mask:0xf bound_ctrl:1
	s_waitcnt lgkmcnt(1)
; #define LAS __attribute__((address_space(3)))
; DI unsigned pk2(float a, float b) { f32x2 v = {a, b}; bf2_t r = __builtin_convertvector(v, bf2_t); return __builtin_bit_cast(unsigned, r); }
; DI f32x2 red16p(f32x2 x) { float a = x.x, b = x.y; red16x2(a, b); return (f32x2){a, b}; }
; DI void scan_bh2(const Args& a, int l, int bh, int halfsel, LAS unsigned char* lds) {
;     ...
;             for (int st = 0; st < T; ++st) {
;                 f32x4 nr4, nd4, nk4, nkk4, nb4; f32x2 nv2;
;                 if (st < T - 1) {
;                     const LAS float* o = cur + (st + 1) * 384;
;                     nr4 = *(const LAS f32x4*)(o + kq * 4); nd4 = *(const LAS f32x4*)(o + 64 + kq * 4); nk4 = *(const LAS f32x4*)(o + 128 + kq * 4);
;                     nkk4 = *(const LAS f32x4*)(o + 192 + kq * 4); nb4 = *(const LAS f32x4*)(o + 256 + kq * 4); nv2 = *(const LAS f32x2*)(o + 320 + row0);
;                 }
;                 f32x2 sa = S[0] * kk4[0]; sa += S[1] * kk4[1]; f32x2 sb = S[2] * kk4[2]; sb += S[3] * kk4[3]; sa += sb;
;                 sa = red16p(sa); sa = -sa;
; #pragma unroll
;                 for (int j = 0; j < 4; ++j) S[j] = S[j] * d4[j] + sa * b4[j] + v2 * k4[j];
;                 f32x2 y = S[0] * r4[0]; y += S[1] * r4[1]; f32x2 yc = S[2] * r4[2]; yc += S[3] * r4[3]; y += yc;
;                 y = red16p(y);
;                 *(LAS unsigned*)(yb + st * 128 + row0 * 2) = pk2(y.x, y.y);
;                 if (st < T - 1) { r4 = nr4; d4 = nd4; k4 = nk4; kk4 = nkk4; b4 = nb4; v2 = nv2; }
	v_pk_mul_f32 v[24:25], v[26:27], v[22:23] op_sel_hi:[0,1]
	v_add_f32_dpp v30, v30, v30 row_half_mirror row_mask:0xf bank_mask:0xf bound_ctrl:1
	v_add_f32_dpp v31, v31, v31 row_half_mirror row_mask:0xf bank_mask:0xf bound_ctrl:1
	v_pk_fma_f32 v[24:25], v[6:7], v[54:55], v[24:25] op_sel_hi:[0,1,1] neg_lo:[0,0,1] neg_hi:[0,0,1]
	v_add_f32_dpp v30, v30, v30 row_mirror row_mask:0xf bank_mask:0xf bound_ctrl:1
	v_add_f32_dpp v31, v31, v31 row_mirror row_mask:0xf bank_mask:0xf bound_ctrl:1
	s_waitcnt lgkmcnt(0)
	v_pk_fma_f32 v[54:55], v[18:19], v[60:61], v[24:25] op_sel_hi:[0,1,1]
	v_cvt_pk_bf16_f32 v17, v30, v31
	v_pk_mul_f32 v[24:25], v[26:27], v[22:23] op_sel:[1,0]
	ds_write_b32 v14, v17 offset:1152
	v_pk_fma_f32 v[6:7], v[6:7], v[50:51], v[24:25] op_sel:[1,0,0] neg_lo:[0,0,1] neg_hi:[0,0,1]
	ds_read_b128 v[30:33], v15 offset:16896
	ds_read_b128 v[34:37], v15 offset:17152
	ds_read_b128 v[38:41], v15 offset:17408
	ds_read_b128 v[42:45], v15 offset:17664
	ds_read_b128 v[46:49], v15 offset:17920
	ds_read_b64 v[58:59], v16 offset:18176
	v_pk_fma_f32 v[50:51], v[18:19], v[60:61], v[6:7] op_sel:[1,0,0]
	v_pk_mul_f32 v[6:7], v[28:29], v[22:23] op_sel_hi:[0,1]
	v_pk_fma_f32 v[6:7], v[8:9], v[56:57], v[6:7] op_sel_hi:[0,1,1] neg_lo:[0,0,1] neg_hi:[0,0,1]
	v_pk_fma_f32 v[56:57], v[20:21], v[60:61], v[6:7] op_sel_hi:[0,1,1]
	v_mov_b32_e32 v6, v9
	v_pk_mul_f32 v[8:9], v[28:29], v[22:23] op_sel:[1,0] op_sel_hi:[1,1]
	s_nop 0
	v_pk_fma_f32 v[6:7], v[6:7], v[52:53], v[8:9] op_sel_hi:[0,1,1] neg_lo:[0,0,1] neg_hi:[0,0,1]
	s_waitcnt lgkmcnt(2)
	v_pk_mul_f32 v[62:63], v[42:43], v[50:51] op_sel:[1,0]
	v_pk_fma_f32 v[52:53], v[20:21], v[60:61], v[6:7] op_sel:[1,0,0] op_sel_hi:[1,1,1]
	v_pk_mul_f32 v[6:7], v[2:3], v[50:51] op_sel:[1,0]
	v_pk_fma_f32 v[42:43], v[42:43], v[54:55], v[62:63] op_sel_hi:[0,1,1]
	v_pk_fma_f32 v[2:3], v[2:3], v[54:55], v[6:7] op_sel_hi:[0,1,1]
	v_pk_mul_f32 v[62:63], v[44:45], v[52:53] op_sel:[1,0] op_sel_hi:[1,1]
	v_pk_mul_f32 v[6:7], v[4:5], v[52:53] op_sel:[1,0] op_sel_hi:[1,1]
	v_pk_fma_f32 v[44:45], v[44:45], v[56:57], v[62:63] op_sel_hi:[0,1,1]
	v_pk_fma_f32 v[4:5], v[4:5], v[56:57], v[6:7] op_sel_hi:[0,1,1]
	v_pk_add_f32 v[42:43], v[42:43], v[44:45]
	v_pk_add_f32 v[2:3], v[2:3], v[4:5]
	s_nop 0
	v_add_f32_dpp v42, v42, v42 quad_perm:[1,0,3,2] row_mask:0xf bank_mask:0xf bound_ctrl:1
	v_add_f32_dpp v43, v43, v43 quad_perm:[1,0,3,2] row_mask:0xf bank_mask:0xf bound_ctrl:1
	v_add_f32_dpp v2, v2, v2 quad_perm:[1,0,3,2] row_mask:0xf bank_mask:0xf bound_ctrl:1
	v_add_f32_dpp v3, v3, v3 quad_perm:[1,0,3,2] row_mask:0xf bank_mask:0xf bound_ctrl:1
	v_add_f32_dpp v42, v42, v42 quad_perm:[2,3,0,1] row_mask:0xf bank_mask:0xf bound_ctrl:1
	v_add_f32_dpp v43, v43, v43 quad_perm:[2,3,0,1] row_mask:0xf bank_mask:0xf bound_ctrl:1
	v_add_f32_dpp v2, v2, v2 quad_perm:[2,3,0,1] row_mask:0xf bank_mask:0xf bound_ctrl:1
	v_add_f32_dpp v3, v3, v3 quad_perm:[2,3,0,1] row_mask:0xf bank_mask:0xf bound_ctrl:1
	v_add_f32_dpp v42, v42, v42 row_half_mirror row_mask:0xf bank_mask:0xf bound_ctrl:1
	v_add_f32_dpp v43, v43, v43 row_half_mirror row_mask:0xf bank_mask:0xf bound_ctrl:1
	v_add_f32_dpp v2, v2, v2 row_half_mirror row_mask:0xf bank_mask:0xf bound_ctrl:1
	v_add_f32_dpp v3, v3, v3 row_half_mirror row_mask:0xf bank_mask:0xf bound_ctrl:1
	v_add_f32_dpp v42, v42, v42 row_mirror row_mask:0xf bank_mask:0xf bound_ctrl:1
	v_add_f32_dpp v43, v43, v43 row_mirror row_mask:0xf bank_mask:0xf bound_ctrl:1
	s_waitcnt lgkmcnt(1)
	v_pk_mul_f32 v[44:45], v[46:47], v[42:43] op_sel_hi:[0,1]
	v_add_f32_dpp v2, v2, v2 row_mirror row_mask:0xf bank_mask:0xf bound_ctrl:1
	v_add_f32_dpp v3, v3, v3 row_mirror row_mask:0xf bank_mask:0xf bound_ctrl:1
	v_pk_fma_f32 v[44:45], v[34:35], v[54:55], v[44:45] op_sel_hi:[0,1,1] neg_lo:[0,0,1] neg_hi:[0,0,1]
	v_cvt_pk_bf16_f32 v2, v2, v3
	s_waitcnt lgkmcnt(0)
	v_pk_fma_f32 v[54:55], v[38:39], v[58:59], v[44:45] op_sel_hi:[0,1,1]
	v_pk_mul_f32 v[44:45], v[46:47], v[42:43] op_sel:[1,0]
	ds_write_b32 v14, v2 offset:1280
	v_pk_fma_f32 v[34:35], v[34:35], v[50:51], v[44:45] op_sel:[1,0,0] neg_lo:[0,0,1] neg_hi:[0,0,1]
	ds_read_b128 v[2:5], v15 offset:18432
	ds_read_b128 v[6:9], v15 offset:18688
	ds_read_b128 v[18:21], v15 offset:18944
	ds_read_b128 v[22:25], v15 offset:19200
	ds_read_b128 v[26:29], v15 offset:19456
	ds_read_b64 v[60:61], v16 offset:19712
	v_pk_fma_f32 v[50:51], v[38:39], v[58:59], v[34:35] op_sel:[1,0,0]
	v_pk_mul_f32 v[34:35], v[48:49], v[42:43] op_sel_hi:[0,1]
	v_pk_fma_f32 v[34:35], v[36:37], v[56:57], v[34:35] op_sel_hi:[0,1,1] neg_lo:[0,0,1] neg_hi:[0,0,1]
	v_pk_fma_f32 v[56:57], v[40:41], v[58:59], v[34:35] op_sel_hi:[0,1,1]
	v_mov_b32_e32 v34, v37
	v_pk_mul_f32 v[36:37], v[48:49], v[42:43] op_sel:[1,0] op_sel_hi:[1,1]
	s_nop 0
	v_pk_fma_f32 v[34:35], v[34:35], v[52:53], v[36:37] op_sel_hi:[0,1,1] neg_lo:[0,0,1] neg_hi:[0,0,1]
	s_waitcnt lgkmcnt(2)
; #define LAS __attribute__((address_space(3)))
; DI unsigned pk2(float a, float b) { f32x2 v = {a, b}; bf2_t r = __builtin_convertvector(v, bf2_t); return __builtin_bit_cast(unsigned, r); }
; DI f32x2 red16p(f32x2 x) { float a = x.x, b = x.y; red16x2(a, b); return (f32x2){a, b}; }
; DI void scan_bh2(const Args& a, int l, int bh, int halfsel, LAS unsigned char* lds) {
;     ...
;             for (int st = 0; st < T; ++st) {
;                 f32x4 nr4, nd4, nk4, nkk4, nb4; f32x2 nv2;
;                 if (st < T - 1) {
;                     const LAS float* o = cur + (st + 1) * 384;
;                     nr4 = *(const LAS f32x4*)(o + kq * 4); nd4 = *(const LAS f32x4*)(o + 64 + kq * 4); nk4 = *(const LAS f32x4*)(o + 128 + kq * 4);
;                     nkk4 = *(const LAS f32x4*)(o + 192 + kq * 4); nb4 = *(const LAS f32x4*)(o + 256 + kq * 4); nv2 = *(const LAS f32x2*)(o + 320 + row0);
;                 }
;                 f32x2 sa = S[0] * kk4[0]; sa += S[1] * kk4[1]; f32x2 sb = S[2] * kk4[2]; sb += S[3] * kk4[3]; sa += sb;
;                 sa = red16p(sa); sa = -sa;
; #pragma unroll
;                 for (int j = 0; j < 4; ++j) S[j] = S[j] * d4[j] + sa * b4[j] + v2 * k4[j];
;                 f32x2 y = S[0] * r4[0]; y += S[1] * r4[1]; f32x2 yc = S[2] * r4[2]; yc += S[3] * r4[3]; y += yc;
;                 y = red16p(y);
;                 *(LAS unsigned*)(yb + st * 128 + row0 * 2) = pk2(y.x, y.y);
;                 if (st < T - 1) { r4 = nr4; d4 = nd4; k4 = nk4; kk4 = nkk4; b4 = nb4; v2 = nv2; }
	v_pk_mul_f32 v[62:63], v[22:23], v[50:51] op_sel:[1,0]
	v_pk_fma_f32 v[52:53], v[40:41], v[58:59], v[34:35] op_sel:[1,0,0] op_sel_hi:[1,1,1]
	v_pk_fma_f32 v[22:23], v[22:23], v[54:55], v[62:63] op_sel_hi:[0,1,1]
	v_pk_mul_f32 v[34:35], v[30:31], v[50:51] op_sel:[1,0]
	v_pk_mul_f32 v[62:63], v[24:25], v[52:53] op_sel:[1,0] op_sel_hi:[1,1]
	v_pk_fma_f32 v[30:31], v[30:31], v[54:55], v[34:35] op_sel_hi:[0,1,1]
	v_pk_fma_f32 v[24:25], v[24:25], v[56:57], v[62:63] op_sel_hi:[0,1,1]
	v_pk_mul_f32 v[34:35], v[32:33], v[52:53] op_sel:[1,0] op_sel_hi:[1,1]
	v_pk_add_f32 v[22:23], v[22:23], v[24:25]
	v_pk_fma_f32 v[32:33], v[32:33], v[56:57], v[34:35] op_sel_hi:[0,1,1]
	s_nop 0
	v_add_f32_dpp v22, v22, v22 quad_perm:[1,0,3,2] row_mask:0xf bank_mask:0xf bound_ctrl:1
	v_add_f32_dpp v23, v23, v23 quad_perm:[1,0,3,2] row_mask:0xf bank_mask:0xf bound_ctrl:1
	v_pk_add_f32 v[30:31], v[30:31], v[32:33]
	v_add_f32_dpp v22, v22, v22 quad_perm:[2,3,0,1] row_mask:0xf bank_mask:0xf bound_ctrl:1
	v_add_f32_dpp v23, v23, v23 quad_perm:[2,3,0,1] row_mask:0xf bank_mask:0xf bound_ctrl:1
	v_add_f32_dpp v30, v30, v30 quad_perm:[1,0,3,2] row_mask:0xf bank_mask:0xf bound_ctrl:1
	v_add_f32_dpp v31, v31, v31 quad_perm:[1,0,3,2] row_mask:0xf bank_mask:0xf bound_ctrl:1
	v_add_f32_dpp v22, v22, v22 row_half_mirror row_mask:0xf bank_mask:0xf bound_ctrl:1
	v_add_f32_dpp v23, v23, v23 row_half_mirror row_mask:0xf bank_mask:0xf bound_ctrl:1
	v_add_f32_dpp v30, v30, v30 quad_perm:[2,3,0,1] row_mask:0xf bank_mask:0xf bound_ctrl:1
	v_add_f32_dpp v31, v31, v31 quad_perm:[2,3,0,1] row_mask:0xf bank_mask:0xf bound_ctrl:1
	v_add_f32_dpp v22, v22, v22 row_mirror row_mask:0xf bank_mask:0xf bound_ctrl:1
	v_add_f32_dpp v23, v23, v23 row_mirror row_mask:0xf bank_mask:0xf bound_ctrl:1
	s_waitcnt lgkmcnt(1)
	v_pk_mul_f32 v[24:25], v[26:27], v[22:23] op_sel_hi:[0,1]
	v_add_f32_dpp v30, v30, v30 row_half_mirror row_mask:0xf bank_mask:0xf bound_ctrl:1
	v_add_f32_dpp v31, v31, v31 row_half_mirror row_mask:0xf bank_mask:0xf bound_ctrl:1
	v_pk_fma_f32 v[24:25], v[6:7], v[54:55], v[24:25] op_sel_hi:[0,1,1] neg_lo:[0,0,1] neg_hi:[0,0,1]
	v_add_f32_dpp v30, v30, v30 row_mirror row_mask:0xf bank_mask:0xf bound_ctrl:1
	v_add_f32_dpp v31, v31, v31 row_mirror row_mask:0xf bank_mask:0xf bound_ctrl:1
	s_waitcnt lgkmcnt(0)
	v_pk_fma_f32 v[54:55], v[18:19], v[60:61], v[24:25] op_sel_hi:[0,1,1]
	v_cvt_pk_bf16_f32 v17, v30, v31
	v_pk_mul_f32 v[24:25], v[26:27], v[22:23] op_sel:[1,0]
	ds_write_b32 v14, v17 offset:1408
	v_pk_fma_f32 v[6:7], v[6:7], v[50:51], v[24:25] op_sel:[1,0,0] neg_lo:[0,0,1] neg_hi:[0,0,1]
	ds_read_b128 v[30:33], v15 offset:19968
	ds_read_b128 v[34:37], v15 offset:20224
	ds_read_b128 v[38:41], v15 offset:20480
	ds_read_b128 v[42:45], v15 offset:20736
	ds_read_b128 v[46:49], v15 offset:20992
	ds_read_b64 v[58:59], v16 offset:21248
	v_pk_fma_f32 v[50:51], v[18:19], v[60:61], v[6:7] op_sel:[1,0,0]
	v_pk_mul_f32 v[6:7], v[28:29], v[22:23] op_sel_hi:[0,1]
	v_pk_fma_f32 v[6:7], v[8:9], v[56:57], v[6:7] op_sel_hi:[0,1,1] neg_lo:[0,0,1] neg_hi:[0,0,1]
	v_pk_fma_f32 v[56:57], v[20:21], v[60:61], v[6:7] op_sel_hi:[0,1,1]
	v_mov_b32_e32 v6, v9
	v_pk_mul_f32 v[8:9], v[28:29], v[22:23] op_sel:[1,0] op_sel_hi:[1,1]
	s_nop 0
	v_pk_fma_f32 v[6:7], v[6:7], v[52:53], v[8:9] op_sel_hi:[0,1,1] neg_lo:[0,0,1] neg_hi:[0,0,1]
	s_waitcnt lgkmcnt(2)
	v_pk_mul_f32 v[62:63], v[42:43], v[50:51] op_sel:[1,0]
	v_pk_fma_f32 v[52:53], v[20:21], v[60:61], v[6:7] op_sel:[1,0,0] op_sel_hi:[1,1,1]
	v_pk_mul_f32 v[6:7], v[2:3], v[50:51] op_sel:[1,0]
	v_pk_fma_f32 v[42:43], v[42:43], v[54:55], v[62:63] op_sel_hi:[0,1,1]
	v_pk_fma_f32 v[2:3], v[2:3], v[54:55], v[6:7] op_sel_hi:[0,1,1]
	v_pk_mul_f32 v[62:63], v[44:45], v[52:53] op_sel:[1,0] op_sel_hi:[1,1]
	v_pk_mul_f32 v[6:7], v[4:5], v[52:53] op_sel:[1,0] op_sel_hi:[1,1]
	v_pk_fma_f32 v[44:45], v[44:45], v[56:57], v[62:63] op_sel_hi:[0,1,1]
	v_pk_fma_f32 v[4:5], v[4:5], v[56:57], v[6:7] op_sel_hi:[0,1,1]
	v_pk_add_f32 v[42:43], v[42:43], v[44:45]
	v_pk_add_f32 v[2:3], v[2:3], v[4:5]
	s_nop 0
	v_add_f32_dpp v42, v42, v42 quad_perm:[1,0,3,2] row_mask:0xf bank_mask:0xf bound_ctrl:1
	v_add_f32_dpp v43, v43, v43 quad_perm:[1,0,3,2] row_mask:0xf bank_mask:0xf bound_ctrl:1
	v_add_f32_dpp v2, v2, v2 quad_perm:[1,0,3,2] row_mask:0xf bank_mask:0xf bound_ctrl:1
	v_add_f32_dpp v3, v3, v3 quad_perm:[1,0,3,2] row_mask:0xf bank_mask:0xf bound_ctrl:1
	v_add_f32_dpp v42, v42, v42 quad_perm:[2,3,0,1] row_mask:0xf bank_mask:0xf bound_ctrl:1
	v_add_f32_dpp v43, v43, v43 quad_perm:[2,3,0,1] row_mask:0xf bank_mask:0xf bound_ctrl:1
	v_add_f32_dpp v2, v2, v2 quad_perm:[2,3,0,1] row_mask:0xf bank_mask:0xf bound_ctrl:1
	v_add_f32_dpp v3, v3, v3 quad_perm:[2,3,0,1] row_mask:0xf bank_mask:0xf bound_ctrl:1
	v_add_f32_dpp v42, v42, v42 row_half_mirror row_mask:0xf bank_mask:0xf bound_ctrl:1
	v_add_f32_dpp v43, v43, v43 row_half_mirror row_mask:0xf bank_mask:0xf bound_ctrl:1
	v_add_f32_dpp v2, v2, v2 row_half_mirror row_mask:0xf bank_mask:0xf bound_ctrl:1
	v_add_f32_dpp v3, v3, v3 row_half_mirror row_mask:0xf bank_mask:0xf bound_ctrl:1
	v_add_f32_dpp v42, v42, v42 row_mirror row_mask:0xf bank_mask:0xf bound_ctrl:1
	v_add_f32_dpp v43, v43, v43 row_mirror row_mask:0xf bank_mask:0xf bound_ctrl:1
	s_waitcnt lgkmcnt(1)
	v_pk_mul_f32 v[44:45], v[46:47], v[42:43] op_sel_hi:[0,1]
	v_add_f32_dpp v2, v2, v2 row_mirror row_mask:0xf bank_mask:0xf bound_ctrl:1
	v_add_f32_dpp v3, v3, v3 row_mirror row_mask:0xf bank_mask:0xf bound_ctrl:1
	v_pk_fma_f32 v[44:45], v[34:35], v[54:55], v[44:45] op_sel_hi:[0,1,1] neg_lo:[0,0,1] neg_hi:[0,0,1]
	v_cvt_pk_bf16_f32 v2, v2, v3
	s_waitcnt lgkmcnt(0)
; #define LAS __attribute__((address_space(3)))
; DI unsigned pk2(float a, float b) { f32x2 v = {a, b}; bf2_t r = __builtin_convertvector(v, bf2_t); return __builtin_bit_cast(unsigned, r); }
; DI f32x2 red16p(f32x2 x) { float a = x.x, b = x.y; red16x2(a, b); return (f32x2){a, b}; }
; DI void scan_bh2(const Args& a, int l, int bh, int halfsel, LAS unsigned char* lds) {
;     ...
;             for (int st = 0; st < T; ++st) {
;                 f32x4 nr4, nd4, nk4, nkk4, nb4; f32x2 nv2;
;                 if (st < T - 1) {
;                     const LAS float* o = cur + (st + 1) * 384;
;                     nr4 = *(const LAS f32x4*)(o + kq * 4); nd4 = *(const LAS f32x4*)(o + 64 + kq * 4); nk4 = *(const LAS f32x4*)(o + 128 + kq * 4);
;                     nkk4 = *(const LAS f32x4*)(o + 192 + kq * 4); nb4 = *(const LAS f32x4*)(o + 256 + kq * 4); nv2 = *(const LAS f32x2*)(o + 320 + row0);
;                 }
;                 f32x2 sa = S[0] * kk4[0]; sa += S[1] * kk4[1]; f32x2 sb = S[2] * kk4[2]; sb += S[3] * kk4[3]; sa += sb;
;                 sa = red16p(sa); sa = -sa;
; #pragma unroll
;                 for (int j = 0; j < 4; ++j) S[j] = S[j] * d4[j] + sa * b4[j] + v2 * k4[j];
;                 f32x2 y = S[0] * r4[0]; y += S[1] * r4[1]; f32x2 yc = S[2] * r4[2]; yc += S[3] * r4[3]; y += yc;
;                 y = red16p(y);
;                 *(LAS unsigned*)(yb + st * 128 + row0 * 2) = pk2(y.x, y.y);
;                 if (st < T - 1) { r4 = nr4; d4 = nd4; k4 = nk4; kk4 = nkk4; b4 = nb4; v2 = nv2; }
	v_pk_fma_f32 v[54:55], v[38:39], v[58:59], v[44:45] op_sel_hi:[0,1,1]
	v_pk_mul_f32 v[44:45], v[46:47], v[42:43] op_sel:[1,0]
	ds_write_b32 v14, v2 offset:1536
	v_pk_fma_f32 v[34:35], v[34:35], v[50:51], v[44:45] op_sel:[1,0,0] neg_lo:[0,0,1] neg_hi:[0,0,1]
	ds_read_b128 v[2:5], v15 offset:21504
	ds_read_b128 v[6:9], v15 offset:21760
	ds_read_b128 v[18:21], v15 offset:22016
	ds_read_b128 v[22:25], v15 offset:22272
	ds_read_b128 v[26:29], v15 offset:22528
	ds_read_b64 v[60:61], v16 offset:22784
	v_pk_fma_f32 v[50:51], v[38:39], v[58:59], v[34:35] op_sel:[1,0,0]
	v_pk_mul_f32 v[34:35], v[48:49], v[42:43] op_sel_hi:[0,1]
	v_pk_fma_f32 v[34:35], v[36:37], v[56:57], v[34:35] op_sel_hi:[0,1,1] neg_lo:[0,0,1] neg_hi:[0,0,1]
	v_pk_fma_f32 v[56:57], v[40:41], v[58:59], v[34:35] op_sel_hi:[0,1,1]
	v_mov_b32_e32 v34, v37
	v_pk_mul_f32 v[36:37], v[48:49], v[42:43] op_sel:[1,0] op_sel_hi:[1,1]
	s_nop 0
	v_pk_fma_f32 v[34:35], v[34:35], v[52:53], v[36:37] op_sel_hi:[0,1,1] neg_lo:[0,0,1] neg_hi:[0,0,1]
	s_waitcnt lgkmcnt(2)
	v_pk_mul_f32 v[62:63], v[22:23], v[50:51] op_sel:[1,0]
	v_pk_fma_f32 v[52:53], v[40:41], v[58:59], v[34:35] op_sel:[1,0,0] op_sel_hi:[1,1,1]
	v_pk_fma_f32 v[22:23], v[22:23], v[54:55], v[62:63] op_sel_hi:[0,1,1]
	v_pk_mul_f32 v[34:35], v[30:31], v[50:51] op_sel:[1,0]
	v_pk_mul_f32 v[62:63], v[24:25], v[52:53] op_sel:[1,0] op_sel_hi:[1,1]
	v_pk_fma_f32 v[30:31], v[30:31], v[54:55], v[34:35] op_sel_hi:[0,1,1]
	v_pk_fma_f32 v[24:25], v[24:25], v[56:57], v[62:63] op_sel_hi:[0,1,1]
	v_pk_mul_f32 v[34:35], v[32:33], v[52:53] op_sel:[1,0] op_sel_hi:[1,1]
	v_pk_add_f32 v[22:23], v[22:23], v[24:25]
	v_pk_fma_f32 v[32:33], v[32:33], v[56:57], v[34:35] op_sel_hi:[0,1,1]
	s_nop 0
	v_add_f32_dpp v22, v22, v22 quad_perm:[1,0,3,2] row_mask:0xf bank_mask:0xf bound_ctrl:1
	v_add_f32_dpp v23, v23, v23 quad_perm:[1,0,3,2] row_mask:0xf bank_mask:0xf bound_ctrl:1
	v_pk_add_f32 v[30:31], v[30:31], v[32:33]
	v_add_f32_dpp v22, v22, v22 quad_perm:[2,3,0,1] row_mask:0xf bank_mask:0xf bound_ctrl:1
	v_add_f32_dpp v23, v23, v23 quad_perm:[2,3,0,1] row_mask:0xf bank_mask:0xf bound_ctrl:1
	v_add_f32_dpp v30, v30, v30 quad_perm:[1,0,3,2] row_mask:0xf bank_mask:0xf bound_ctrl:1
	v_add_f32_dpp v31, v31, v31 quad_perm:[1,0,3,2] row_mask:0xf bank_mask:0xf bound_ctrl:1
	v_add_f32_dpp v22, v22, v22 row_half_mirror row_mask:0xf bank_mask:0xf bound_ctrl:1
	v_add_f32_dpp v23, v23, v23 row_half_mirror row_mask:0xf bank_mask:0xf bound_ctrl:1
	v_add_f32_dpp v30, v30, v30 quad_perm:[2,3,0,1] row_mask:0xf bank_mask:0xf bound_ctrl:1
	v_add_f32_dpp v31, v31, v31 quad_perm:[2,3,0,1] row_mask:0xf bank_mask:0xf bound_ctrl:1
	v_add_f32_dpp v22, v22, v22 row_mirror row_mask:0xf bank_mask:0xf bound_ctrl:1
	v_add_f32_dpp v23, v23, v23 row_mirror row_mask:0xf bank_mask:0xf bound_ctrl:1
	s_waitcnt lgkmcnt(1)
	v_pk_mul_f32 v[24:25], v[26:27], v[22:23] op_sel_hi:[0,1]
	v_add_f32_dpp v30, v30, v30 row_half_mirror row_mask:0xf bank_mask:0xf bound_ctrl:1
	v_add_f32_dpp v31, v31, v31 row_half_mirror row_mask:0xf bank_mask:0xf bound_ctrl:1
	v_pk_fma_f32 v[24:25], v[6:7], v[54:55], v[24:25] op_sel_hi:[0,1,1] neg_lo:[0,0,1] neg_hi:[0,0,1]
	v_add_f32_dpp v30, v30, v30 row_mirror row_mask:0xf bank_mask:0xf bound_ctrl:1
	v_add_f32_dpp v31, v31, v31 row_mirror row_mask:0xf bank_mask:0xf bound_ctrl:1
	s_waitcnt lgkmcnt(0)
	v_pk_fma_f32 v[54:55], v[18:19], v[60:61], v[24:25] op_sel_hi:[0,1,1]
	v_cvt_pk_bf16_f32 v17, v30, v31
	v_pk_mul_f32 v[24:25], v[26:27], v[22:23] op_sel:[1,0]
	ds_write_b32 v14, v17 offset:1664
	v_pk_fma_f32 v[6:7], v[6:7], v[50:51], v[24:25] op_sel:[1,0,0] neg_lo:[0,0,1] neg_hi:[0,0,1]
	ds_read_b128 v[30:33], v15 offset:23040
	ds_read_b128 v[34:37], v15 offset:23296
	ds_read_b128 v[38:41], v15 offset:23552
	ds_read_b128 v[42:45], v15 offset:23808
	ds_read_b128 v[46:49], v15 offset:24064
	ds_read_b64 v[58:59], v16 offset:24320
	v_pk_fma_f32 v[50:51], v[18:19], v[60:61], v[6:7] op_sel:[1,0,0]
	v_pk_mul_f32 v[6:7], v[28:29], v[22:23] op_sel_hi:[0,1]
	v_pk_fma_f32 v[6:7], v[8:9], v[56:57], v[6:7] op_sel_hi:[0,1,1] neg_lo:[0,0,1] neg_hi:[0,0,1]
	v_pk_fma_f32 v[56:57], v[20:21], v[60:61], v[6:7] op_sel_hi:[0,1,1]
	v_mov_b32_e32 v6, v9
	v_pk_mul_f32 v[8:9], v[28:29], v[22:23] op_sel:[1,0] op_sel_hi:[1,1]
	s_nop 0
	v_pk_fma_f32 v[6:7], v[6:7], v[52:53], v[8:9] op_sel_hi:[0,1,1] neg_lo:[0,0,1] neg_hi:[0,0,1]
	s_waitcnt lgkmcnt(2)
	v_pk_mul_f32 v[62:63], v[42:43], v[50:51] op_sel:[1,0]
	v_pk_fma_f32 v[52:53], v[20:21], v[60:61], v[6:7] op_sel:[1,0,0] op_sel_hi:[1,1,1]
	v_pk_mul_f32 v[6:7], v[2:3], v[50:51] op_sel:[1,0]
	v_pk_fma_f32 v[42:43], v[42:43], v[54:55], v[62:63] op_sel_hi:[0,1,1]
	v_pk_fma_f32 v[2:3], v[2:3], v[54:55], v[6:7] op_sel_hi:[0,1,1]
	v_pk_mul_f32 v[62:63], v[44:45], v[52:53] op_sel:[1,0] op_sel_hi:[1,1]
	v_pk_mul_f32 v[6:7], v[4:5], v[52:53] op_sel:[1,0] op_sel_hi:[1,1]
	v_pk_fma_f32 v[44:45], v[44:45], v[56:57], v[62:63] op_sel_hi:[0,1,1]
	v_pk_fma_f32 v[4:5], v[4:5], v[56:57], v[6:7] op_sel_hi:[0,1,1]
	v_pk_add_f32 v[42:43], v[42:43], v[44:45]
	v_pk_add_f32 v[2:3], v[2:3], v[4:5]
	s_nop 0
	v_add_f32_dpp v42, v42, v42 quad_perm:[1,0,3,2] row_mask:0xf bank_mask:0xf bound_ctrl:1
	v_add_f32_dpp v43, v43, v43 quad_perm:[1,0,3,2] row_mask:0xf bank_mask:0xf bound_ctrl:1
	v_add_f32_dpp v2, v2, v2 quad_perm:[1,0,3,2] row_mask:0xf bank_mask:0xf bound_ctrl:1
	v_add_f32_dpp v3, v3, v3 quad_perm:[1,0,3,2] row_mask:0xf bank_mask:0xf bound_ctrl:1
	v_add_f32_dpp v42, v42, v42 quad_perm:[2,3,0,1] row_mask:0xf bank_mask:0xf bound_ctrl:1
	v_add_f32_dpp v43, v43, v43 quad_perm:[2,3,0,1] row_mask:0xf bank_mask:0xf bound_ctrl:1
	v_add_f32_dpp v2, v2, v2 quad_perm:[2,3,0,1] row_mask:0xf bank_mask:0xf bound_ctrl:1
	v_add_f32_dpp v3, v3, v3 quad_perm:[2,3,0,1] row_mask:0xf bank_mask:0xf bound_ctrl:1
	v_add_f32_dpp v42, v42, v42 row_half_mirror row_mask:0xf bank_mask:0xf bound_ctrl:1
	v_add_f32_dpp v43, v43, v43 row_half_mirror row_mask:0xf bank_mask:0xf bound_ctrl:1
	v_add_f32_dpp v2, v2, v2 row_half_mirror row_mask:0xf bank_mask:0xf bound_ctrl:1
	v_add_f32_dpp v3, v3, v3 row_half_mirror row_mask:0xf bank_mask:0xf bound_ctrl:1
	v_add_f32_dpp v42, v42, v42 row_mirror row_mask:0xf bank_mask:0xf bound_ctrl:1
	v_add_f32_dpp v43, v43, v43 row_mirror row_mask:0xf bank_mask:0xf bound_ctrl:1
	s_waitcnt lgkmcnt(1)
; #define LAS __attribute__((address_space(3)))
; DI unsigned pk2(float a, float b) { f32x2 v = {a, b}; bf2_t r = __builtin_convertvector(v, bf2_t); return __builtin_bit_cast(unsigned, r); }
; DI f32x2 red16p(f32x2 x) { float a = x.x, b = x.y; red16x2(a, b); return (f32x2){a, b}; }
; DI void scan_bh2(const Args& a, int l, int bh, int halfsel, LAS unsigned char* lds) {
;     ...
;             for (int st = 0; st < T; ++st) {
;                 f32x4 nr4, nd4, nk4, nkk4, nb4; f32x2 nv2;
;                 if (st < T - 1) {
;                     const LAS float* o = cur + (st + 1) * 384;
;                     nr4 = *(const LAS f32x4*)(o + kq * 4); nd4 = *(const LAS f32x4*)(o + 64 + kq * 4); nk4 = *(const LAS f32x4*)(o + 128 + kq * 4);
;                     nkk4 = *(const LAS f32x4*)(o + 192 + kq * 4); nb4 = *(const LAS f32x4*)(o + 256 + kq * 4); nv2 = *(const LAS f32x2*)(o + 320 + row0);
;                 }
;                 f32x2 sa = S[0] * kk4[0]; sa += S[1] * kk4[1]; f32x2 sb = S[2] * kk4[2]; sb += S[3] * kk4[3]; sa += sb;
;                 sa = red16p(sa); sa = -sa;
; #pragma unroll
;                 for (int j = 0; j < 4; ++j) S[j] = S[j] * d4[j] + sa * b4[j] + v2 * k4[j];
;                 f32x2 y = S[0] * r4[0]; y += S[1] * r4[1]; f32x2 yc = S[2] * r4[2]; yc += S[3] * r4[3]; y += yc;
;                 y = red16p(y);
;                 *(LAS unsigned*)(yb + st * 128 + row0 * 2) = pk2(y.x, y.y);
;                 if (st < T - 1) { r4 = nr4; d4 = nd4; k4 = nk4; kk4 = nkk4; b4 = nb4; v2 = nv2; }
	v_pk_mul_f32 v[44:45], v[46:47], v[42:43] op_sel_hi:[0,1]
	v_add_f32_dpp v2, v2, v2 row_mirror row_mask:0xf bank_mask:0xf bound_ctrl:1
	v_add_f32_dpp v3, v3, v3 row_mirror row_mask:0xf bank_mask:0xf bound_ctrl:1
	v_pk_fma_f32 v[44:45], v[34:35], v[54:55], v[44:45] op_sel_hi:[0,1,1] neg_lo:[0,0,1] neg_hi:[0,0,1]
	v_cvt_pk_bf16_f32 v2, v2, v3
	s_waitcnt lgkmcnt(0)
	v_pk_fma_f32 v[54:55], v[38:39], v[58:59], v[44:45] op_sel_hi:[0,1,1]
	v_pk_mul_f32 v[44:45], v[46:47], v[42:43] op_sel:[1,0]
	ds_write_b32 v14, v2 offset:1792
	v_pk_fma_f32 v[34:35], v[34:35], v[50:51], v[44:45] op_sel:[1,0,0] neg_lo:[0,0,1] neg_hi:[0,0,1]
	ds_read_b128 v[2:5], v15 offset:24576
	ds_read_b128 v[6:9], v15 offset:24832
	ds_read_b128 v[18:21], v15 offset:25088
	ds_read_b128 v[22:25], v15 offset:25344
	ds_read_b128 v[26:29], v15 offset:25600
	ds_read_b64 v[60:61], v16 offset:25856
	v_pk_fma_f32 v[50:51], v[38:39], v[58:59], v[34:35] op_sel:[1,0,0]
	v_pk_mul_f32 v[34:35], v[48:49], v[42:43] op_sel_hi:[0,1]
	v_pk_fma_f32 v[34:35], v[36:37], v[56:57], v[34:35] op_sel_hi:[0,1,1] neg_lo:[0,0,1] neg_hi:[0,0,1]
	v_pk_fma_f32 v[56:57], v[40:41], v[58:59], v[34:35] op_sel_hi:[0,1,1]
	v_mov_b32_e32 v34, v37
	v_pk_mul_f32 v[36:37], v[48:49], v[42:43] op_sel:[1,0] op_sel_hi:[1,1]
	s_nop 0
	v_pk_fma_f32 v[34:35], v[34:35], v[52:53], v[36:37] op_sel_hi:[0,1,1] neg_lo:[0,0,1] neg_hi:[0,0,1]
	s_waitcnt lgkmcnt(2)
	v_pk_mul_f32 v[62:63], v[22:23], v[50:51] op_sel:[1,0]
	v_pk_fma_f32 v[52:53], v[40:41], v[58:59], v[34:35] op_sel:[1,0,0] op_sel_hi:[1,1,1]
	v_pk_fma_f32 v[22:23], v[22:23], v[54:55], v[62:63] op_sel_hi:[0,1,1]
	v_pk_mul_f32 v[34:35], v[30:31], v[50:51] op_sel:[1,0]
	v_pk_mul_f32 v[62:63], v[24:25], v[52:53] op_sel:[1,0] op_sel_hi:[1,1]
	v_pk_fma_f32 v[30:31], v[30:31], v[54:55], v[34:35] op_sel_hi:[0,1,1]
	v_pk_fma_f32 v[24:25], v[24:25], v[56:57], v[62:63] op_sel_hi:[0,1,1]
	v_pk_mul_f32 v[34:35], v[32:33], v[52:53] op_sel:[1,0] op_sel_hi:[1,1]
	v_pk_add_f32 v[22:23], v[22:23], v[24:25]
	v_pk_fma_f32 v[32:33], v[32:33], v[56:57], v[34:35] op_sel_hi:[0,1,1]
	s_nop 0
	v_add_f32_dpp v22, v22, v22 quad_perm:[1,0,3,2] row_mask:0xf bank_mask:0xf bound_ctrl:1
	v_add_f32_dpp v23, v23, v23 quad_perm:[1,0,3,2] row_mask:0xf bank_mask:0xf bound_ctrl:1
	v_pk_add_f32 v[30:31], v[30:31], v[32:33]
	v_add_f32_dpp v22, v22, v22 quad_perm:[2,3,0,1] row_mask:0xf bank_mask:0xf bound_ctrl:1
	v_add_f32_dpp v23, v23, v23 quad_perm:[2,3,0,1] row_mask:0xf bank_mask:0xf bound_ctrl:1
	v_add_f32_dpp v30, v30, v30 quad_perm:[1,0,3,2] row_mask:0xf bank_mask:0xf bound_ctrl:1
	v_add_f32_dpp v31, v31, v31 quad_perm:[1,0,3,2] row_mask:0xf bank_mask:0xf bound_ctrl:1
	v_add_f32_dpp v22, v22, v22 row_half_mirror row_mask:0xf bank_mask:0xf bound_ctrl:1
	v_add_f32_dpp v23, v23, v23 row_half_mirror row_mask:0xf bank_mask:0xf bound_ctrl:1
	v_add_f32_dpp v30, v30, v30 quad_perm:[2,3,0,1] row_mask:0xf bank_mask:0xf bound_ctrl:1
	v_add_f32_dpp v31, v31, v31 quad_perm:[2,3,0,1] row_mask:0xf bank_mask:0xf bound_ctrl:1
	v_add_f32_dpp v22, v22, v22 row_mirror row_mask:0xf bank_mask:0xf bound_ctrl:1
	v_add_f32_dpp v23, v23, v23 row_mirror row_mask:0xf bank_mask:0xf bound_ctrl:1
	s_waitcnt lgkmcnt(1)
	v_pk_mul_f32 v[24:25], v[26:27], v[22:23] op_sel_hi:[0,1]
	v_add_f32_dpp v30, v30, v30 row_half_mirror row_mask:0xf bank_mask:0xf bound_ctrl:1
	v_add_f32_dpp v31, v31, v31 row_half_mirror row_mask:0xf bank_mask:0xf bound_ctrl:1
	v_pk_fma_f32 v[24:25], v[6:7], v[54:55], v[24:25] op_sel_hi:[0,1,1] neg_lo:[0,0,1] neg_hi:[0,0,1]
	v_add_f32_dpp v30, v30, v30 row_mirror row_mask:0xf bank_mask:0xf bound_ctrl:1
	v_add_f32_dpp v31, v31, v31 row_mirror row_mask:0xf bank_mask:0xf bound_ctrl:1
	s_waitcnt lgkmcnt(0)
	v_pk_fma_f32 v[54:55], v[18:19], v[60:61], v[24:25] op_sel_hi:[0,1,1]
	v_cvt_pk_bf16_f32 v17, v30, v31
	v_pk_mul_f32 v[24:25], v[26:27], v[22:23] op_sel:[1,0]
	ds_write_b32 v14, v17 offset:1920
	v_pk_fma_f32 v[6:7], v[6:7], v[50:51], v[24:25] op_sel:[1,0,0] neg_lo:[0,0,1] neg_hi:[0,0,1]
	ds_read_b128 v[30:33], v15 offset:26112
	ds_read_b128 v[34:37], v15 offset:26368
	ds_read_b128 v[38:41], v15 offset:26624
	ds_read_b128 v[42:45], v15 offset:26880
	ds_read_b128 v[46:49], v15 offset:27136
	ds_read_b64 v[58:59], v16 offset:27392
	v_pk_fma_f32 v[50:51], v[18:19], v[60:61], v[6:7] op_sel:[1,0,0]
	v_pk_mul_f32 v[6:7], v[28:29], v[22:23] op_sel_hi:[0,1]
	v_pk_fma_f32 v[6:7], v[8:9], v[56:57], v[6:7] op_sel_hi:[0,1,1] neg_lo:[0,0,1] neg_hi:[0,0,1]
	v_pk_fma_f32 v[56:57], v[20:21], v[60:61], v[6:7] op_sel_hi:[0,1,1]
	v_mov_b32_e32 v6, v9
	v_pk_mul_f32 v[8:9], v[28:29], v[22:23] op_sel:[1,0] op_sel_hi:[1,1]
	s_nop 0
	v_pk_fma_f32 v[6:7], v[6:7], v[52:53], v[8:9] op_sel_hi:[0,1,1] neg_lo:[0,0,1] neg_hi:[0,0,1]
	s_waitcnt lgkmcnt(2)
; #define LAS __attribute__((address_space(3)))
; DI unsigned pk2(float a, float b) { f32x2 v = {a, b}; bf2_t r = __builtin_convertvector(v, bf2_t); return __builtin_bit_cast(unsigned, r); }
; DI f32x2 red16p(f32x2 x) { float a = x.x, b = x.y; red16x2(a, b); return (f32x2){a, b}; }
; DI void scan_bh2(const Args& a, int l, int bh, int halfsel, LAS unsigned char* lds) {
;     ...
;             for (int st = 0; st < T; ++st) {
;                 f32x4 nr4, nd4, nk4, nkk4, nb4; f32x2 nv2;
;                 if (st < T - 1) {
;                     const LAS float* o = cur + (st + 1) * 384;
;                     nr4 = *(const LAS f32x4*)(o + kq * 4); nd4 = *(const LAS f32x4*)(o + 64 + kq * 4); nk4 = *(const LAS f32x4*)(o + 128 + kq * 4);
;                     nkk4 = *(const LAS f32x4*)(o + 192 + kq * 4); nb4 = *(const LAS f32x4*)(o + 256 + kq * 4); nv2 = *(const LAS f32x2*)(o + 320 + row0);
;                 }
;                 f32x2 sa = S[0] * kk4[0]; sa += S[1] * kk4[1]; f32x2 sb = S[2] * kk4[2]; sb += S[3] * kk4[3]; sa += sb;
;                 sa = red16p(sa); sa = -sa;
; #pragma unroll
;                 for (int j = 0; j < 4; ++j) S[j] = S[j] * d4[j] + sa * b4[j] + v2 * k4[j];
;                 f32x2 y = S[0] * r4[0]; y += S[1] * r4[1]; f32x2 yc = S[2] * r4[2]; yc += S[3] * r4[3]; y += yc;
;                 y = red16p(y);
;                 *(LAS unsigned*)(yb + st * 128 + row0 * 2) = pk2(y.x, y.y);
;                 if (st < T - 1) { r4 = nr4; d4 = nd4; k4 = nk4; kk4 = nkk4; b4 = nb4; v2 = nv2; }
	v_pk_mul_f32 v[62:63], v[42:43], v[50:51] op_sel:[1,0]
	v_pk_fma_f32 v[52:53], v[20:21], v[60:61], v[6:7] op_sel:[1,0,0] op_sel_hi:[1,1,1]
	v_pk_mul_f32 v[6:7], v[2:3], v[50:51] op_sel:[1,0]
	v_pk_fma_f32 v[42:43], v[42:43], v[54:55], v[62:63] op_sel_hi:[0,1,1]
	v_pk_fma_f32 v[2:3], v[2:3], v[54:55], v[6:7] op_sel_hi:[0,1,1]
	v_pk_mul_f32 v[62:63], v[44:45], v[52:53] op_sel:[1,0] op_sel_hi:[1,1]
	v_pk_mul_f32 v[6:7], v[4:5], v[52:53] op_sel:[1,0] op_sel_hi:[1,1]
	v_pk_fma_f32 v[44:45], v[44:45], v[56:57], v[62:63] op_sel_hi:[0,1,1]
	v_pk_fma_f32 v[4:5], v[4:5], v[56:57], v[6:7] op_sel_hi:[0,1,1]
	v_pk_add_f32 v[42:43], v[42:43], v[44:45]
	v_pk_add_f32 v[2:3], v[2:3], v[4:5]
	s_nop 0
	v_add_f32_dpp v42, v42, v42 quad_perm:[1,0,3,2] row_mask:0xf bank_mask:0xf bound_ctrl:1
	v_add_f32_dpp v43, v43, v43 quad_perm:[1,0,3,2] row_mask:0xf bank_mask:0xf bound_ctrl:1
	v_add_f32_dpp v2, v2, v2 quad_perm:[1,0,3,2] row_mask:0xf bank_mask:0xf bound_ctrl:1
	v_add_f32_dpp v3, v3, v3 quad_perm:[1,0,3,2] row_mask:0xf bank_mask:0xf bound_ctrl:1
	v_add_f32_dpp v42, v42, v42 quad_perm:[2,3,0,1] row_mask:0xf bank_mask:0xf bound_ctrl:1
	v_add_f32_dpp v43, v43, v43 quad_perm:[2,3,0,1] row_mask:0xf bank_mask:0xf bound_ctrl:1
	v_add_f32_dpp v2, v2, v2 quad_perm:[2,3,0,1] row_mask:0xf bank_mask:0xf bound_ctrl:1
	v_add_f32_dpp v3, v3, v3 quad_perm:[2,3,0,1] row_mask:0xf bank_mask:0xf bound_ctrl:1
	v_add_f32_dpp v42, v42, v42 row_half_mirror row_mask:0xf bank_mask:0xf bound_ctrl:1
	v_add_f32_dpp v43, v43, v43 row_half_mirror row_mask:0xf bank_mask:0xf bound_ctrl:1
	v_add_f32_dpp v2, v2, v2 row_half_mirror row_mask:0xf bank_mask:0xf bound_ctrl:1
	v_add_f32_dpp v3, v3, v3 row_half_mirror row_mask:0xf bank_mask:0xf bound_ctrl:1
	v_add_f32_dpp v42, v42, v42 row_mirror row_mask:0xf bank_mask:0xf bound_ctrl:1
	v_add_f32_dpp v43, v43, v43 row_mirror row_mask:0xf bank_mask:0xf bound_ctrl:1
	s_waitcnt lgkmcnt(1)
	v_pk_mul_f32 v[44:45], v[46:47], v[42:43] op_sel_hi:[0,1]
	v_add_f32_dpp v2, v2, v2 row_mirror row_mask:0xf bank_mask:0xf bound_ctrl:1
	v_add_f32_dpp v3, v3, v3 row_mirror row_mask:0xf bank_mask:0xf bound_ctrl:1
	v_pk_fma_f32 v[44:45], v[34:35], v[54:55], v[44:45] op_sel_hi:[0,1,1] neg_lo:[0,0,1] neg_hi:[0,0,1]
	v_cvt_pk_bf16_f32 v2, v2, v3
	s_waitcnt lgkmcnt(0)
	v_pk_fma_f32 v[54:55], v[38:39], v[58:59], v[44:45] op_sel_hi:[0,1,1]
	v_pk_mul_f32 v[44:45], v[46:47], v[42:43] op_sel:[1,0]
	ds_write_b32 v14, v2 offset:2048
	v_pk_fma_f32 v[34:35], v[34:35], v[50:51], v[44:45] op_sel:[1,0,0] neg_lo:[0,0,1] neg_hi:[0,0,1]
	ds_read_b128 v[2:5], v15 offset:27648
	ds_read_b128 v[6:9], v15 offset:27904
	ds_read_b128 v[18:21], v15 offset:28160
	ds_read_b128 v[22:25], v15 offset:28416
	ds_read_b128 v[26:29], v15 offset:28672
	ds_read_b64 v[60:61], v16 offset:28928
	v_pk_fma_f32 v[50:51], v[38:39], v[58:59], v[34:35] op_sel:[1,0,0]
	v_pk_mul_f32 v[34:35], v[48:49], v[42:43] op_sel_hi:[0,1]
	v_pk_fma_f32 v[34:35], v[36:37], v[56:57], v[34:35] op_sel_hi:[0,1,1] neg_lo:[0,0,1] neg_hi:[0,0,1]
	v_pk_fma_f32 v[56:57], v[40:41], v[58:59], v[34:35] op_sel_hi:[0,1,1]
	v_mov_b32_e32 v34, v37
	v_pk_mul_f32 v[36:37], v[48:49], v[42:43] op_sel:[1,0] op_sel_hi:[1,1]
	s_nop 0
	v_pk_fma_f32 v[34:35], v[34:35], v[52:53], v[36:37] op_sel_hi:[0,1,1] neg_lo:[0,0,1] neg_hi:[0,0,1]
	s_waitcnt lgkmcnt(2)
	v_pk_mul_f32 v[62:63], v[22:23], v[50:51] op_sel:[1,0]
	v_pk_fma_f32 v[52:53], v[40:41], v[58:59], v[34:35] op_sel:[1,0,0] op_sel_hi:[1,1,1]
	v_pk_fma_f32 v[22:23], v[22:23], v[54:55], v[62:63] op_sel_hi:[0,1,1]
	v_pk_mul_f32 v[34:35], v[30:31], v[50:51] op_sel:[1,0]
	v_pk_mul_f32 v[62:63], v[24:25], v[52:53] op_sel:[1,0] op_sel_hi:[1,1]
	v_pk_fma_f32 v[30:31], v[30:31], v[54:55], v[34:35] op_sel_hi:[0,1,1]
	v_pk_fma_f32 v[24:25], v[24:25], v[56:57], v[62:63] op_sel_hi:[0,1,1]
	v_pk_mul_f32 v[34:35], v[32:33], v[52:53] op_sel:[1,0] op_sel_hi:[1,1]
	v_pk_add_f32 v[22:23], v[22:23], v[24:25]
	v_pk_fma_f32 v[32:33], v[32:33], v[56:57], v[34:35] op_sel_hi:[0,1,1]
	s_nop 0
	v_add_f32_dpp v22, v22, v22 quad_perm:[1,0,3,2] row_mask:0xf bank_mask:0xf bound_ctrl:1
	v_add_f32_dpp v23, v23, v23 quad_perm:[1,0,3,2] row_mask:0xf bank_mask:0xf bound_ctrl:1
	v_pk_add_f32 v[30:31], v[30:31], v[32:33]
	v_add_f32_dpp v22, v22, v22 quad_perm:[2,3,0,1] row_mask:0xf bank_mask:0xf bound_ctrl:1
	v_add_f32_dpp v23, v23, v23 quad_perm:[2,3,0,1] row_mask:0xf bank_mask:0xf bound_ctrl:1
	v_add_f32_dpp v30, v30, v30 quad_perm:[1,0,3,2] row_mask:0xf bank_mask:0xf bound_ctrl:1
	v_add_f32_dpp v31, v31, v31 quad_perm:[1,0,3,2] row_mask:0xf bank_mask:0xf bound_ctrl:1
	v_add_f32_dpp v22, v22, v22 row_half_mirror row_mask:0xf bank_mask:0xf bound_ctrl:1
	v_add_f32_dpp v23, v23, v23 row_half_mirror row_mask:0xf bank_mask:0xf bound_ctrl:1
	v_add_f32_dpp v30, v30, v30 quad_perm:[2,3,0,1] row_mask:0xf bank_mask:0xf bound_ctrl:1
	v_add_f32_dpp v31, v31, v31 quad_perm:[2,3,0,1] row_mask:0xf bank_mask:0xf bound_ctrl:1
	v_add_f32_dpp v22, v22, v22 row_mirror row_mask:0xf bank_mask:0xf bound_ctrl:1
	v_add_f32_dpp v23, v23, v23 row_mirror row_mask:0xf bank_mask:0xf bound_ctrl:1
	s_waitcnt lgkmcnt(1)
	v_pk_mul_f32 v[24:25], v[26:27], v[22:23] op_sel_hi:[0,1]
	v_add_f32_dpp v30, v30, v30 row_half_mirror row_mask:0xf bank_mask:0xf bound_ctrl:1
	v_add_f32_dpp v31, v31, v31 row_half_mirror row_mask:0xf bank_mask:0xf bound_ctrl:1
	v_pk_fma_f32 v[24:25], v[6:7], v[54:55], v[24:25] op_sel_hi:[0,1,1] neg_lo:[0,0,1] neg_hi:[0,0,1]
	v_add_f32_dpp v30, v30, v30 row_mirror row_mask:0xf bank_mask:0xf bound_ctrl:1
	v_add_f32_dpp v31, v31, v31 row_mirror row_mask:0xf bank_mask:0xf bound_ctrl:1
	s_waitcnt lgkmcnt(0)
; #define LAS __attribute__((address_space(3)))
; DI unsigned pk2(float a, float b) { f32x2 v = {a, b}; bf2_t r = __builtin_convertvector(v, bf2_t); return __builtin_bit_cast(unsigned, r); }
; DI f32x2 red16p(f32x2 x) { float a = x.x, b = x.y; red16x2(a, b); return (f32x2){a, b}; }
; DI void scan_bh2(const Args& a, int l, int bh, int halfsel, LAS unsigned char* lds) {
;     ...
;             for (int st = 0; st < T; ++st) {
;                 f32x4 nr4, nd4, nk4, nkk4, nb4; f32x2 nv2;
;                 if (st < T - 1) {
;                     const LAS float* o = cur + (st + 1) * 384;
;                     nr4 = *(const LAS f32x4*)(o + kq * 4); nd4 = *(const LAS f32x4*)(o + 64 + kq * 4); nk4 = *(const LAS f32x4*)(o + 128 + kq * 4);
;                     nkk4 = *(const LAS f32x4*)(o + 192 + kq * 4); nb4 = *(const LAS f32x4*)(o + 256 + kq * 4); nv2 = *(const LAS f32x2*)(o + 320 + row0);
;                 }
;                 f32x2 sa = S[0] * kk4[0]; sa += S[1] * kk4[1]; f32x2 sb = S[2] * kk4[2]; sb += S[3] * kk4[3]; sa += sb;
;                 sa = red16p(sa); sa = -sa;
; #pragma unroll
;                 for (int j = 0; j < 4; ++j) S[j] = S[j] * d4[j] + sa * b4[j] + v2 * k4[j];
;                 f32x2 y = S[0] * r4[0]; y += S[1] * r4[1]; f32x2 yc = S[2] * r4[2]; yc += S[3] * r4[3]; y += yc;
;                 y = red16p(y);
;                 *(LAS unsigned*)(yb + st * 128 + row0 * 2) = pk2(y.x, y.y);
;                 if (st < T - 1) { r4 = nr4; d4 = nd4; k4 = nk4; kk4 = nkk4; b4 = nb4; v2 = nv2; }
	v_pk_fma_f32 v[54:55], v[18:19], v[60:61], v[24:25] op_sel_hi:[0,1,1]
	v_cvt_pk_bf16_f32 v17, v30, v31
	v_pk_mul_f32 v[24:25], v[26:27], v[22:23] op_sel:[1,0]
	ds_write_b32 v14, v17 offset:2176
	v_pk_fma_f32 v[6:7], v[6:7], v[50:51], v[24:25] op_sel:[1,0,0] neg_lo:[0,0,1] neg_hi:[0,0,1]
	ds_read_b128 v[30:33], v15 offset:29184
	ds_read_b128 v[34:37], v15 offset:29440
	ds_read_b128 v[38:41], v15 offset:29696
	ds_read_b128 v[42:45], v15 offset:29952
	ds_read_b128 v[46:49], v15 offset:30208
	ds_read_b64 v[58:59], v16 offset:30464
	v_pk_fma_f32 v[50:51], v[18:19], v[60:61], v[6:7] op_sel:[1,0,0]
	v_pk_mul_f32 v[6:7], v[28:29], v[22:23] op_sel_hi:[0,1]
	v_pk_fma_f32 v[6:7], v[8:9], v[56:57], v[6:7] op_sel_hi:[0,1,1] neg_lo:[0,0,1] neg_hi:[0,0,1]
	v_pk_fma_f32 v[56:57], v[20:21], v[60:61], v[6:7] op_sel_hi:[0,1,1]
	v_mov_b32_e32 v6, v9
	v_pk_mul_f32 v[8:9], v[28:29], v[22:23] op_sel:[1,0] op_sel_hi:[1,1]
	s_nop 0
	v_pk_fma_f32 v[6:7], v[6:7], v[52:53], v[8:9] op_sel_hi:[0,1,1] neg_lo:[0,0,1] neg_hi:[0,0,1]
	s_waitcnt lgkmcnt(2)
	v_pk_mul_f32 v[62:63], v[42:43], v[50:51] op_sel:[1,0]
	v_pk_fma_f32 v[52:53], v[20:21], v[60:61], v[6:7] op_sel:[1,0,0] op_sel_hi:[1,1,1]
	v_pk_mul_f32 v[6:7], v[2:3], v[50:51] op_sel:[1,0]
	v_pk_fma_f32 v[42:43], v[42:43], v[54:55], v[62:63] op_sel_hi:[0,1,1]
	v_pk_fma_f32 v[2:3], v[2:3], v[54:55], v[6:7] op_sel_hi:[0,1,1]
	v_pk_mul_f32 v[62:63], v[44:45], v[52:53] op_sel:[1,0] op_sel_hi:[1,1]
	v_pk_mul_f32 v[6:7], v[4:5], v[52:53] op_sel:[1,0] op_sel_hi:[1,1]
	v_pk_fma_f32 v[44:45], v[44:45], v[56:57], v[62:63] op_sel_hi:[0,1,1]
	v_pk_fma_f32 v[4:5], v[4:5], v[56:57], v[6:7] op_sel_hi:[0,1,1]
	v_pk_add_f32 v[42:43], v[42:43], v[44:45]
	v_pk_add_f32 v[2:3], v[2:3], v[4:5]
	s_nop 0
	v_add_f32_dpp v42, v42, v42 quad_perm:[1,0,3,2] row_mask:0xf bank_mask:0xf bound_ctrl:1
	v_add_f32_dpp v43, v43, v43 quad_perm:[1,0,3,2] row_mask:0xf bank_mask:0xf bound_ctrl:1
	v_add_f32_dpp v2, v2, v2 quad_perm:[1,0,3,2] row_mask:0xf bank_mask:0xf bound_ctrl:1
	v_add_f32_dpp v3, v3, v3 quad_perm:[1,0,3,2] row_mask:0xf bank_mask:0xf bound_ctrl:1
	v_add_f32_dpp v42, v42, v42 quad_perm:[2,3,0,1] row_mask:0xf bank_mask:0xf bound_ctrl:1
	v_add_f32_dpp v43, v43, v43 quad_perm:[2,3,0,1] row_mask:0xf bank_mask:0xf bound_ctrl:1
	v_add_f32_dpp v2, v2, v2 quad_perm:[2,3,0,1] row_mask:0xf bank_mask:0xf bound_ctrl:1
	v_add_f32_dpp v3, v3, v3 quad_perm:[2,3,0,1] row_mask:0xf bank_mask:0xf bound_ctrl:1
	v_add_f32_dpp v42, v42, v42 row_half_mirror row_mask:0xf bank_mask:0xf bound_ctrl:1
	v_add_f32_dpp v43, v43, v43 row_half_mirror row_mask:0xf bank_mask:0xf bound_ctrl:1
	v_add_f32_dpp v2, v2, v2 row_half_mirror row_mask:0xf bank_mask:0xf bound_ctrl:1
	v_add_f32_dpp v3, v3, v3 row_half_mirror row_mask:0xf bank_mask:0xf bound_ctrl:1
	v_add_f32_dpp v42, v42, v42 row_mirror row_mask:0xf bank_mask:0xf bound_ctrl:1
	v_add_f32_dpp v43, v43, v43 row_mirror row_mask:0xf bank_mask:0xf bound_ctrl:1
	s_waitcnt lgkmcnt(1)
	v_pk_mul_f32 v[44:45], v[46:47], v[42:43] op_sel_hi:[0,1]
	v_add_f32_dpp v2, v2, v2 row_mirror row_mask:0xf bank_mask:0xf bound_ctrl:1
	v_add_f32_dpp v3, v3, v3 row_mirror row_mask:0xf bank_mask:0xf bound_ctrl:1
	v_pk_fma_f32 v[44:45], v[34:35], v[54:55], v[44:45] op_sel_hi:[0,1,1] neg_lo:[0,0,1] neg_hi:[0,0,1]
	v_cvt_pk_bf16_f32 v2, v2, v3
	s_waitcnt lgkmcnt(0)
	v_pk_fma_f32 v[54:55], v[38:39], v[58:59], v[44:45] op_sel_hi:[0,1,1]
	v_pk_mul_f32 v[44:45], v[46:47], v[42:43] op_sel:[1,0]
	ds_write_b32 v14, v2 offset:2304
	v_pk_fma_f32 v[34:35], v[34:35], v[50:51], v[44:45] op_sel:[1,0,0] neg_lo:[0,0,1] neg_hi:[0,0,1]
	ds_read_b128 v[2:5], v15 offset:30720
	ds_read_b128 v[6:9], v15 offset:30976
	ds_read_b128 v[18:21], v15 offset:31232
	ds_read_b128 v[22:25], v15 offset:31488
	ds_read_b128 v[26:29], v15 offset:31744
	ds_read_b64 v[60:61], v16 offset:32000
	v_pk_fma_f32 v[50:51], v[38:39], v[58:59], v[34:35] op_sel:[1,0,0]
	v_pk_mul_f32 v[34:35], v[48:49], v[42:43] op_sel_hi:[0,1]
	v_pk_fma_f32 v[34:35], v[36:37], v[56:57], v[34:35] op_sel_hi:[0,1,1] neg_lo:[0,0,1] neg_hi:[0,0,1]
	v_pk_fma_f32 v[56:57], v[40:41], v[58:59], v[34:35] op_sel_hi:[0,1,1]
	v_mov_b32_e32 v34, v37
	v_pk_mul_f32 v[36:37], v[48:49], v[42:43] op_sel:[1,0] op_sel_hi:[1,1]
	s_nop 0
	v_pk_fma_f32 v[34:35], v[34:35], v[52:53], v[36:37] op_sel_hi:[0,1,1] neg_lo:[0,0,1] neg_hi:[0,0,1]
	s_waitcnt lgkmcnt(2)
	v_pk_mul_f32 v[62:63], v[22:23], v[50:51] op_sel:[1,0]
	v_pk_fma_f32 v[52:53], v[40:41], v[58:59], v[34:35] op_sel:[1,0,0] op_sel_hi:[1,1,1]
	v_pk_fma_f32 v[22:23], v[22:23], v[54:55], v[62:63] op_sel_hi:[0,1,1]
	v_pk_mul_f32 v[62:63], v[24:25], v[52:53] op_sel:[1,0] op_sel_hi:[1,1]
	s_nop 0
	v_pk_fma_f32 v[24:25], v[24:25], v[56:57], v[62:63] op_sel_hi:[0,1,1]
	v_pk_mul_f32 v[34:35], v[30:31], v[50:51] op_sel:[1,0]
	v_pk_add_f32 v[22:23], v[22:23], v[24:25]
	v_pk_fma_f32 v[30:31], v[30:31], v[54:55], v[34:35] op_sel_hi:[0,1,1]
	s_nop 0
	v_add_f32_dpp v22, v22, v22 quad_perm:[1,0,3,2] row_mask:0xf bank_mask:0xf bound_ctrl:1
	v_add_f32_dpp v23, v23, v23 quad_perm:[1,0,3,2] row_mask:0xf bank_mask:0xf bound_ctrl:1
	v_pk_mul_f32 v[34:35], v[32:33], v[52:53] op_sel:[1,0] op_sel_hi:[1,1]
	v_add_f32_dpp v22, v22, v22 quad_perm:[2,3,0,1] row_mask:0xf bank_mask:0xf bound_ctrl:1
	v_add_f32_dpp v23, v23, v23 quad_perm:[2,3,0,1] row_mask:0xf bank_mask:0xf bound_ctrl:1
	v_pk_fma_f32 v[32:33], v[32:33], v[56:57], v[34:35] op_sel_hi:[0,1,1]
	v_add_f32_dpp v22, v22, v22 row_half_mirror row_mask:0xf bank_mask:0xf bound_ctrl:1
	v_add_f32_dpp v23, v23, v23 row_half_mirror row_mask:0xf bank_mask:0xf bound_ctrl:1
	v_pk_add_f32 v[30:31], v[30:31], v[32:33]
	v_add_f32_dpp v22, v22, v22 row_mirror row_mask:0xf bank_mask:0xf bound_ctrl:1
	v_add_f32_dpp v23, v23, v23 row_mirror row_mask:0xf bank_mask:0xf bound_ctrl:1
	s_waitcnt lgkmcnt(1)
; #define LAS __attribute__((address_space(3)))
; DI unsigned pk2(float a, float b) { f32x2 v = {a, b}; bf2_t r = __builtin_convertvector(v, bf2_t); return __builtin_bit_cast(unsigned, r); }
; DI f32x2 red16p(f32x2 x) { float a = x.x, b = x.y; red16x2(a, b); return (f32x2){a, b}; }
; DI void scan_bh2(const Args& a, int l, int bh, int halfsel, LAS unsigned char* lds) {
;     ...
;             for (int st = 0; st < T; ++st) {
;                 f32x4 nr4, nd4, nk4, nkk4, nb4; f32x2 nv2;
;                 if (st < T - 1) {
;                     const LAS float* o = cur + (st + 1) * 384;
;                     nr4 = *(const LAS f32x4*)(o + kq * 4); nd4 = *(const LAS f32x4*)(o + 64 + kq * 4); nk4 = *(const LAS f32x4*)(o + 128 + kq * 4);
;                     nkk4 = *(const LAS f32x4*)(o + 192 + kq * 4); nb4 = *(const LAS f32x4*)(o + 256 + kq * 4); nv2 = *(const LAS f32x2*)(o + 320 + row0);
;                 }
;                 f32x2 sa = S[0] * kk4[0]; sa += S[1] * kk4[1]; f32x2 sb = S[2] * kk4[2]; sb += S[3] * kk4[3]; sa += sb;
;                 sa = red16p(sa); sa = -sa;
; #pragma unroll
;                 for (int j = 0; j < 4; ++j) S[j] = S[j] * d4[j] + sa * b4[j] + v2 * k4[j];
;                 f32x2 y = S[0] * r4[0]; y += S[1] * r4[1]; f32x2 yc = S[2] * r4[2]; yc += S[3] * r4[3]; y += yc;
;                 y = red16p(y);
;                 *(LAS unsigned*)(yb + st * 128 + row0 * 2) = pk2(y.x, y.y);
;                 if (st < T - 1) { r4 = nr4; d4 = nd4; k4 = nk4; kk4 = nkk4; b4 = nb4; v2 = nv2; }
	v_pk_mul_f32 v[24:25], v[26:27], v[22:23] op_sel_hi:[0,1]
	v_add_f32_dpp v30, v30, v30 quad_perm:[1,0,3,2] row_mask:0xf bank_mask:0xf bound_ctrl:1
	v_add_f32_dpp v31, v31, v31 quad_perm:[1,0,3,2] row_mask:0xf bank_mask:0xf bound_ctrl:1
	v_pk_fma_f32 v[24:25], v[6:7], v[54:55], v[24:25] op_sel_hi:[0,1,1] neg_lo:[0,0,1] neg_hi:[0,0,1]
	v_add_f32_dpp v30, v30, v30 quad_perm:[2,3,0,1] row_mask:0xf bank_mask:0xf bound_ctrl:1
	v_add_f32_dpp v31, v31, v31 quad_perm:[2,3,0,1] row_mask:0xf bank_mask:0xf bound_ctrl:1
	s_waitcnt lgkmcnt(0)
	v_pk_fma_f32 v[54:55], v[18:19], v[60:61], v[24:25] op_sel_hi:[0,1,1]
	v_pk_mul_f32 v[24:25], v[26:27], v[22:23] op_sel:[1,0]
	v_add_f32_dpp v30, v30, v30 row_half_mirror row_mask:0xf bank_mask:0xf bound_ctrl:1
	v_add_f32_dpp v31, v31, v31 row_half_mirror row_mask:0xf bank_mask:0xf bound_ctrl:1
	s_nop 0
	v_pk_fma_f32 v[6:7], v[6:7], v[50:51], v[24:25] op_sel:[1,0,0] neg_lo:[0,0,1] neg_hi:[0,0,1]
	v_add_f32_dpp v30, v30, v30 row_mirror row_mask:0xf bank_mask:0xf bound_ctrl:1
	v_add_f32_dpp v31, v31, v31 row_mirror row_mask:0xf bank_mask:0xf bound_ctrl:1
	s_nop 0
	v_cvt_pk_bf16_f32 v17, v30, v31
	v_pk_fma_f32 v[50:51], v[18:19], v[60:61], v[6:7] op_sel:[1,0,0]
	v_pk_mul_f32 v[6:7], v[28:29], v[22:23] op_sel_hi:[0,1]
	ds_write_b32 v14, v17 offset:2432
	v_pk_fma_f32 v[6:7], v[8:9], v[56:57], v[6:7] op_sel_hi:[0,1,1] neg_lo:[0,0,1] neg_hi:[0,0,1]
	ds_read_b128 v[30:33], v15 offset:32768
	ds_read_b128 v[34:37], v15 offset:33024
	ds_read_b128 v[38:41], v15 offset:32256
	ds_read_b128 v[42:45], v15 offset:33280
	ds_read_b128 v[46:49], v15 offset:32512
	ds_read_b64 v[58:59], v16 offset:33536
	v_pk_fma_f32 v[56:57], v[20:21], v[60:61], v[6:7] op_sel_hi:[0,1,1]
	v_mov_b32_e32 v6, v9
	v_pk_mul_f32 v[8:9], v[28:29], v[22:23] op_sel:[1,0] op_sel_hi:[1,1]
	s_nop 0
	v_pk_fma_f32 v[6:7], v[6:7], v[52:53], v[8:9] op_sel_hi:[0,1,1] neg_lo:[0,0,1] neg_hi:[0,0,1]
	s_waitcnt lgkmcnt(4)
	v_pk_mul_f32 v[62:63], v[34:35], v[50:51] op_sel:[1,0]
	v_pk_fma_f32 v[52:53], v[20:21], v[60:61], v[6:7] op_sel:[1,0,0] op_sel_hi:[1,1,1]
	v_pk_fma_f32 v[34:35], v[34:35], v[54:55], v[62:63] op_sel_hi:[0,1,1]
	v_pk_mul_f32 v[6:7], v[2:3], v[50:51] op_sel:[1,0]
	v_pk_mul_f32 v[62:63], v[36:37], v[52:53] op_sel:[1,0] op_sel_hi:[1,1]
	v_pk_fma_f32 v[2:3], v[2:3], v[54:55], v[6:7] op_sel_hi:[0,1,1]
	v_pk_fma_f32 v[36:37], v[36:37], v[56:57], v[62:63] op_sel_hi:[0,1,1]
	v_pk_mul_f32 v[6:7], v[4:5], v[52:53] op_sel:[1,0] op_sel_hi:[1,1]
	v_pk_add_f32 v[34:35], v[34:35], v[36:37]
	v_pk_fma_f32 v[4:5], v[4:5], v[56:57], v[6:7] op_sel_hi:[0,1,1]
	s_nop 0
	v_add_f32_dpp v34, v34, v34 quad_perm:[1,0,3,2] row_mask:0xf bank_mask:0xf bound_ctrl:1
	v_add_f32_dpp v35, v35, v35 quad_perm:[1,0,3,2] row_mask:0xf bank_mask:0xf bound_ctrl:1
	v_pk_add_f32 v[2:3], v[2:3], v[4:5]
	v_add_f32_dpp v34, v34, v34 quad_perm:[2,3,0,1] row_mask:0xf bank_mask:0xf bound_ctrl:1
	v_add_f32_dpp v35, v35, v35 quad_perm:[2,3,0,1] row_mask:0xf bank_mask:0xf bound_ctrl:1
	v_add_f32_dpp v2, v2, v2 quad_perm:[1,0,3,2] row_mask:0xf bank_mask:0xf bound_ctrl:1
	v_add_f32_dpp v3, v3, v3 quad_perm:[1,0,3,2] row_mask:0xf bank_mask:0xf bound_ctrl:1
	v_add_f32_dpp v34, v34, v34 row_half_mirror row_mask:0xf bank_mask:0xf bound_ctrl:1
	v_add_f32_dpp v35, v35, v35 row_half_mirror row_mask:0xf bank_mask:0xf bound_ctrl:1
	v_add_f32_dpp v2, v2, v2 quad_perm:[2,3,0,1] row_mask:0xf bank_mask:0xf bound_ctrl:1
	v_add_f32_dpp v3, v3, v3 quad_perm:[2,3,0,1] row_mask:0xf bank_mask:0xf bound_ctrl:1
	v_add_f32_dpp v34, v34, v34 row_mirror row_mask:0xf bank_mask:0xf bound_ctrl:1
	v_add_f32_dpp v35, v35, v35 row_mirror row_mask:0xf bank_mask:0xf bound_ctrl:1
	s_waitcnt lgkmcnt(2)
	v_pk_mul_f32 v[36:37], v[42:43], v[34:35] op_sel_hi:[0,1]
	v_add_f32_dpp v2, v2, v2 row_half_mirror row_mask:0xf bank_mask:0xf bound_ctrl:1
	v_add_f32_dpp v3, v3, v3 row_half_mirror row_mask:0xf bank_mask:0xf bound_ctrl:1
	s_waitcnt lgkmcnt(1)
	v_pk_fma_f32 v[36:37], v[46:47], v[54:55], v[36:37] op_sel_hi:[0,1,1] neg_lo:[0,0,1] neg_hi:[0,0,1]
	v_add_f32_dpp v2, v2, v2 row_mirror row_mask:0xf bank_mask:0xf bound_ctrl:1
	v_add_f32_dpp v3, v3, v3 row_mirror row_mask:0xf bank_mask:0xf bound_ctrl:1
	s_waitcnt lgkmcnt(0)
	v_pk_fma_f32 v[54:55], v[30:31], v[58:59], v[36:37] op_sel_hi:[0,1,1]
	v_pk_mul_f32 v[36:37], v[42:43], v[34:35] op_sel:[1,0]
	v_cvt_pk_bf16_f32 v2, v2, v3
	v_pk_fma_f32 v[36:37], v[46:47], v[50:51], v[36:37] op_sel:[1,0,0] neg_lo:[0,0,1] neg_hi:[0,0,1]
	ds_write_b32 v14, v2 offset:2560
	v_pk_fma_f32 v[50:51], v[30:31], v[58:59], v[36:37] op_sel:[1,0,0]
	v_pk_mul_f32 v[30:31], v[44:45], v[34:35] op_sel_hi:[0,1]
	ds_read_b128 v[2:5], v15 offset:33792
	ds_read_b128 v[6:9], v15 offset:34048
	ds_read_b128 v[18:21], v15 offset:34304
	ds_read_b128 v[22:25], v15 offset:34560
	ds_read_b128 v[26:29], v15 offset:34816
	ds_read_b64 v[60:61], v16 offset:35072
	v_pk_fma_f32 v[30:31], v[48:49], v[56:57], v[30:31] op_sel_hi:[0,1,1] neg_lo:[0,0,1] neg_hi:[0,0,1]
	v_pk_fma_f32 v[56:57], v[32:33], v[58:59], v[30:31] op_sel_hi:[0,1,1]
	v_pk_mul_f32 v[34:35], v[44:45], v[34:35] op_sel:[1,0] op_sel_hi:[1,1]
	s_nop 0
	v_pk_fma_f32 v[30:31], v[48:49], v[52:53], v[34:35] op_sel:[1,0,0] op_sel_hi:[1,1,1] neg_lo:[0,0,1] neg_hi:[0,0,1]
	s_waitcnt lgkmcnt(2)
; #define LAS __attribute__((address_space(3)))
; DI unsigned pk2(float a, float b) { f32x2 v = {a, b}; bf2_t r = __builtin_convertvector(v, bf2_t); return __builtin_bit_cast(unsigned, r); }
; DI f32x2 red16p(f32x2 x) { float a = x.x, b = x.y; red16x2(a, b); return (f32x2){a, b}; }
; DI void scan_bh2(const Args& a, int l, int bh, int halfsel, LAS unsigned char* lds) {
;     ...
;             for (int st = 0; st < T; ++st) {
;                 f32x4 nr4, nd4, nk4, nkk4, nb4; f32x2 nv2;
;                 if (st < T - 1) {
;                     const LAS float* o = cur + (st + 1) * 384;
;                     nr4 = *(const LAS f32x4*)(o + kq * 4); nd4 = *(const LAS f32x4*)(o + 64 + kq * 4); nk4 = *(const LAS f32x4*)(o + 128 + kq * 4);
;                     nkk4 = *(const LAS f32x4*)(o + 192 + kq * 4); nb4 = *(const LAS f32x4*)(o + 256 + kq * 4); nv2 = *(const LAS f32x2*)(o + 320 + row0);
;                 }
;                 f32x2 sa = S[0] * kk4[0]; sa += S[1] * kk4[1]; f32x2 sb = S[2] * kk4[2]; sb += S[3] * kk4[3]; sa += sb;
;                 sa = red16p(sa); sa = -sa;
; #pragma unroll
;                 for (int j = 0; j < 4; ++j) S[j] = S[j] * d4[j] + sa * b4[j] + v2 * k4[j];
;                 f32x2 y = S[0] * r4[0]; y += S[1] * r4[1]; f32x2 yc = S[2] * r4[2]; yc += S[3] * r4[3]; y += yc;
;                 y = red16p(y);
;                 *(LAS unsigned*)(yb + st * 128 + row0 * 2) = pk2(y.x, y.y);
;                 if (st < T - 1) { r4 = nr4; d4 = nd4; k4 = nk4; kk4 = nkk4; b4 = nb4; v2 = nv2; }
	v_pk_mul_f32 v[62:63], v[22:23], v[50:51] op_sel:[1,0]
	v_pk_fma_f32 v[52:53], v[32:33], v[58:59], v[30:31] op_sel:[1,0,0] op_sel_hi:[1,1,1]
	v_pk_fma_f32 v[22:23], v[22:23], v[54:55], v[62:63] op_sel_hi:[0,1,1]
	v_pk_mul_f32 v[62:63], v[24:25], v[52:53] op_sel:[1,0] op_sel_hi:[1,1]
	s_nop 0
	v_pk_fma_f32 v[24:25], v[24:25], v[56:57], v[62:63] op_sel_hi:[0,1,1]
	v_pk_mul_f32 v[30:31], v[38:39], v[50:51] op_sel:[1,0]
	v_pk_mul_f32 v[32:33], v[40:41], v[52:53] op_sel:[1,0] op_sel_hi:[1,1]
	v_pk_add_f32 v[22:23], v[22:23], v[24:25]
	v_pk_fma_f32 v[30:31], v[38:39], v[54:55], v[30:31] op_sel_hi:[0,1,1]
	v_pk_fma_f32 v[32:33], v[40:41], v[56:57], v[32:33] op_sel_hi:[0,1,1]
	v_add_f32_dpp v22, v22, v22 quad_perm:[1,0,3,2] row_mask:0xf bank_mask:0xf bound_ctrl:1
	v_add_f32_dpp v23, v23, v23 quad_perm:[1,0,3,2] row_mask:0xf bank_mask:0xf bound_ctrl:1
	v_pk_add_f32 v[30:31], v[30:31], v[32:33]
	v_add_f32_dpp v22, v22, v22 quad_perm:[2,3,0,1] row_mask:0xf bank_mask:0xf bound_ctrl:1
	v_add_f32_dpp v23, v23, v23 quad_perm:[2,3,0,1] row_mask:0xf bank_mask:0xf bound_ctrl:1
	v_add_f32_dpp v30, v30, v30 quad_perm:[1,0,3,2] row_mask:0xf bank_mask:0xf bound_ctrl:1
	v_add_f32_dpp v31, v31, v31 quad_perm:[1,0,3,2] row_mask:0xf bank_mask:0xf bound_ctrl:1
	v_add_f32_dpp v22, v22, v22 row_half_mirror row_mask:0xf bank_mask:0xf bound_ctrl:1
	v_add_f32_dpp v23, v23, v23 row_half_mirror row_mask:0xf bank_mask:0xf bound_ctrl:1
	v_add_f32_dpp v30, v30, v30 quad_perm:[2,3,0,1] row_mask:0xf bank_mask:0xf bound_ctrl:1
	v_add_f32_dpp v31, v31, v31 quad_perm:[2,3,0,1] row_mask:0xf bank_mask:0xf bound_ctrl:1
	v_add_f32_dpp v22, v22, v22 row_mirror row_mask:0xf bank_mask:0xf bound_ctrl:1
	v_add_f32_dpp v23, v23, v23 row_mirror row_mask:0xf bank_mask:0xf bound_ctrl:1
	s_waitcnt lgkmcnt(1)
	v_pk_mul_f32 v[24:25], v[26:27], v[22:23] op_sel_hi:[0,1]
	v_add_f32_dpp v30, v30, v30 row_half_mirror row_mask:0xf bank_mask:0xf bound_ctrl:1
	v_add_f32_dpp v31, v31, v31 row_half_mirror row_mask:0xf bank_mask:0xf bound_ctrl:1
	v_pk_fma_f32 v[24:25], v[6:7], v[54:55], v[24:25] op_sel_hi:[0,1,1] neg_lo:[0,0,1] neg_hi:[0,0,1]
	v_add_f32_dpp v30, v30, v30 row_mirror row_mask:0xf bank_mask:0xf bound_ctrl:1
	v_add_f32_dpp v31, v31, v31 row_mirror row_mask:0xf bank_mask:0xf bound_ctrl:1
	s_waitcnt lgkmcnt(0)
	v_pk_fma_f32 v[54:55], v[18:19], v[60:61], v[24:25] op_sel_hi:[0,1,1]
	v_cvt_pk_bf16_f32 v17, v30, v31
	v_pk_mul_f32 v[24:25], v[26:27], v[22:23] op_sel:[1,0]
	ds_write_b32 v14, v17 offset:2688
	v_pk_fma_f32 v[6:7], v[6:7], v[50:51], v[24:25] op_sel:[1,0,0] neg_lo:[0,0,1] neg_hi:[0,0,1]
	ds_read_b128 v[30:33], v15 offset:35328
	ds_read_b128 v[34:37], v15 offset:35584
	ds_read_b128 v[38:41], v15 offset:35840
	ds_read_b128 v[42:45], v15 offset:36096
	ds_read_b128 v[46:49], v15 offset:36352
	ds_read_b64 v[58:59], v16 offset:36608
	v_pk_fma_f32 v[50:51], v[18:19], v[60:61], v[6:7] op_sel:[1,0,0]
	v_pk_mul_f32 v[6:7], v[28:29], v[22:23] op_sel_hi:[0,1]
	v_pk_fma_f32 v[6:7], v[8:9], v[56:57], v[6:7] op_sel_hi:[0,1,1] neg_lo:[0,0,1] neg_hi:[0,0,1]
	v_pk_fma_f32 v[56:57], v[20:21], v[60:61], v[6:7] op_sel_hi:[0,1,1]
	v_mov_b32_e32 v6, v9
	v_pk_mul_f32 v[8:9], v[28:29], v[22:23] op_sel:[1,0] op_sel_hi:[1,1]
	s_nop 0
	v_pk_fma_f32 v[6:7], v[6:7], v[52:53], v[8:9] op_sel_hi:[0,1,1] neg_lo:[0,0,1] neg_hi:[0,0,1]
	s_waitcnt lgkmcnt(2)
	v_pk_mul_f32 v[62:63], v[42:43], v[50:51] op_sel:[1,0]
	v_pk_fma_f32 v[52:53], v[20:21], v[60:61], v[6:7] op_sel:[1,0,0] op_sel_hi:[1,1,1]
	v_pk_mul_f32 v[6:7], v[2:3], v[50:51] op_sel:[1,0]
	v_pk_fma_f32 v[42:43], v[42:43], v[54:55], v[62:63] op_sel_hi:[0,1,1]
	v_pk_fma_f32 v[2:3], v[2:3], v[54:55], v[6:7] op_sel_hi:[0,1,1]
	v_pk_mul_f32 v[62:63], v[44:45], v[52:53] op_sel:[1,0] op_sel_hi:[1,1]
	v_pk_mul_f32 v[6:7], v[4:5], v[52:53] op_sel:[1,0] op_sel_hi:[1,1]
	v_pk_fma_f32 v[44:45], v[44:45], v[56:57], v[62:63] op_sel_hi:[0,1,1]
	v_pk_fma_f32 v[4:5], v[4:5], v[56:57], v[6:7] op_sel_hi:[0,1,1]
	v_pk_add_f32 v[42:43], v[42:43], v[44:45]
	v_pk_add_f32 v[2:3], v[2:3], v[4:5]
	s_nop 0
	v_add_f32_dpp v42, v42, v42 quad_perm:[1,0,3,2] row_mask:0xf bank_mask:0xf bound_ctrl:1
	v_add_f32_dpp v43, v43, v43 quad_perm:[1,0,3,2] row_mask:0xf bank_mask:0xf bound_ctrl:1
	v_add_f32_dpp v2, v2, v2 quad_perm:[1,0,3,2] row_mask:0xf bank_mask:0xf bound_ctrl:1
	v_add_f32_dpp v3, v3, v3 quad_perm:[1,0,3,2] row_mask:0xf bank_mask:0xf bound_ctrl:1
	v_add_f32_dpp v42, v42, v42 quad_perm:[2,3,0,1] row_mask:0xf bank_mask:0xf bound_ctrl:1
	v_add_f32_dpp v43, v43, v43 quad_perm:[2,3,0,1] row_mask:0xf bank_mask:0xf bound_ctrl:1
	v_add_f32_dpp v2, v2, v2 quad_perm:[2,3,0,1] row_mask:0xf bank_mask:0xf bound_ctrl:1
	v_add_f32_dpp v3, v3, v3 quad_perm:[2,3,0,1] row_mask:0xf bank_mask:0xf bound_ctrl:1
	v_add_f32_dpp v42, v42, v42 row_half_mirror row_mask:0xf bank_mask:0xf bound_ctrl:1
	v_add_f32_dpp v43, v43, v43 row_half_mirror row_mask:0xf bank_mask:0xf bound_ctrl:1
	v_add_f32_dpp v2, v2, v2 row_half_mirror row_mask:0xf bank_mask:0xf bound_ctrl:1
	v_add_f32_dpp v3, v3, v3 row_half_mirror row_mask:0xf bank_mask:0xf bound_ctrl:1
	v_add_f32_dpp v42, v42, v42 row_mirror row_mask:0xf bank_mask:0xf bound_ctrl:1
	v_add_f32_dpp v43, v43, v43 row_mirror row_mask:0xf bank_mask:0xf bound_ctrl:1
	s_waitcnt lgkmcnt(1)
	v_pk_mul_f32 v[44:45], v[46:47], v[42:43] op_sel_hi:[0,1]
	v_add_f32_dpp v2, v2, v2 row_mirror row_mask:0xf bank_mask:0xf bound_ctrl:1
	v_add_f32_dpp v3, v3, v3 row_mirror row_mask:0xf bank_mask:0xf bound_ctrl:1
	v_pk_fma_f32 v[44:45], v[34:35], v[54:55], v[44:45] op_sel_hi:[0,1,1] neg_lo:[0,0,1] neg_hi:[0,0,1]
	v_cvt_pk_bf16_f32 v2, v2, v3
	s_waitcnt lgkmcnt(0)
; #define LAS __attribute__((address_space(3)))
; DI unsigned pk2(float a, float b) { f32x2 v = {a, b}; bf2_t r = __builtin_convertvector(v, bf2_t); return __builtin_bit_cast(unsigned, r); }
; DI f32x2 red16p(f32x2 x) { float a = x.x, b = x.y; red16x2(a, b); return (f32x2){a, b}; }
; DI void scan_bh2(const Args& a, int l, int bh, int halfsel, LAS unsigned char* lds) {
;     ...
;             for (int st = 0; st < T; ++st) {
;                 f32x4 nr4, nd4, nk4, nkk4, nb4; f32x2 nv2;
;                 if (st < T - 1) {
;                     const LAS float* o = cur + (st + 1) * 384;
;                     nr4 = *(const LAS f32x4*)(o + kq * 4); nd4 = *(const LAS f32x4*)(o + 64 + kq * 4); nk4 = *(const LAS f32x4*)(o + 128 + kq * 4);
;                     nkk4 = *(const LAS f32x4*)(o + 192 + kq * 4); nb4 = *(const LAS f32x4*)(o + 256 + kq * 4); nv2 = *(const LAS f32x2*)(o + 320 + row0);
;                 }
;                 f32x2 sa = S[0] * kk4[0]; sa += S[1] * kk4[1]; f32x2 sb = S[2] * kk4[2]; sb += S[3] * kk4[3]; sa += sb;
;                 sa = red16p(sa); sa = -sa;
; #pragma unroll
;                 for (int j = 0; j < 4; ++j) S[j] = S[j] * d4[j] + sa * b4[j] + v2 * k4[j];
;                 f32x2 y = S[0] * r4[0]; y += S[1] * r4[1]; f32x2 yc = S[2] * r4[2]; yc += S[3] * r4[3]; y += yc;
;                 y = red16p(y);
;                 *(LAS unsigned*)(yb + st * 128 + row0 * 2) = pk2(y.x, y.y);
;                 if (st < T - 1) { r4 = nr4; d4 = nd4; k4 = nk4; kk4 = nkk4; b4 = nb4; v2 = nv2; }
	v_pk_fma_f32 v[54:55], v[38:39], v[58:59], v[44:45] op_sel_hi:[0,1,1]
	v_pk_mul_f32 v[44:45], v[46:47], v[42:43] op_sel:[1,0]
	ds_write_b32 v14, v2 offset:2816
	v_pk_fma_f32 v[34:35], v[34:35], v[50:51], v[44:45] op_sel:[1,0,0] neg_lo:[0,0,1] neg_hi:[0,0,1]
	ds_read_b128 v[2:5], v15 offset:36864
	ds_read_b128 v[6:9], v15 offset:37120
	ds_read_b128 v[18:21], v15 offset:37376
	ds_read_b128 v[22:25], v15 offset:37632
	ds_read_b128 v[26:29], v15 offset:37888
	ds_read_b64 v[60:61], v16 offset:38144
	v_pk_fma_f32 v[50:51], v[38:39], v[58:59], v[34:35] op_sel:[1,0,0]
	v_pk_mul_f32 v[34:35], v[48:49], v[42:43] op_sel_hi:[0,1]
	v_pk_fma_f32 v[34:35], v[36:37], v[56:57], v[34:35] op_sel_hi:[0,1,1] neg_lo:[0,0,1] neg_hi:[0,0,1]
	v_pk_fma_f32 v[56:57], v[40:41], v[58:59], v[34:35] op_sel_hi:[0,1,1]
	v_mov_b32_e32 v34, v37
	v_pk_mul_f32 v[36:37], v[48:49], v[42:43] op_sel:[1,0] op_sel_hi:[1,1]
	s_nop 0
	v_pk_fma_f32 v[34:35], v[34:35], v[52:53], v[36:37] op_sel_hi:[0,1,1] neg_lo:[0,0,1] neg_hi:[0,0,1]
	s_waitcnt lgkmcnt(2)
	v_pk_mul_f32 v[62:63], v[22:23], v[50:51] op_sel:[1,0]
	v_pk_fma_f32 v[52:53], v[40:41], v[58:59], v[34:35] op_sel:[1,0,0] op_sel_hi:[1,1,1]
	v_pk_fma_f32 v[22:23], v[22:23], v[54:55], v[62:63] op_sel_hi:[0,1,1]
	v_pk_mul_f32 v[34:35], v[30:31], v[50:51] op_sel:[1,0]
	v_pk_mul_f32 v[62:63], v[24:25], v[52:53] op_sel:[1,0] op_sel_hi:[1,1]
	v_pk_fma_f32 v[30:31], v[30:31], v[54:55], v[34:35] op_sel_hi:[0,1,1]
	v_pk_fma_f32 v[24:25], v[24:25], v[56:57], v[62:63] op_sel_hi:[0,1,1]
	v_pk_mul_f32 v[34:35], v[32:33], v[52:53] op_sel:[1,0] op_sel_hi:[1,1]
	v_pk_add_f32 v[22:23], v[22:23], v[24:25]
	v_pk_fma_f32 v[32:33], v[32:33], v[56:57], v[34:35] op_sel_hi:[0,1,1]
	s_nop 0
	v_add_f32_dpp v22, v22, v22 quad_perm:[1,0,3,2] row_mask:0xf bank_mask:0xf bound_ctrl:1
	v_add_f32_dpp v23, v23, v23 quad_perm:[1,0,3,2] row_mask:0xf bank_mask:0xf bound_ctrl:1
	v_pk_add_f32 v[30:31], v[30:31], v[32:33]
	v_add_f32_dpp v22, v22, v22 quad_perm:[2,3,0,1] row_mask:0xf bank_mask:0xf bound_ctrl:1
	v_add_f32_dpp v23, v23, v23 quad_perm:[2,3,0,1] row_mask:0xf bank_mask:0xf bound_ctrl:1
	v_add_f32_dpp v30, v30, v30 quad_perm:[1,0,3,2] row_mask:0xf bank_mask:0xf bound_ctrl:1
	v_add_f32_dpp v31, v31, v31 quad_perm:[1,0,3,2] row_mask:0xf bank_mask:0xf bound_ctrl:1
	v_add_f32_dpp v22, v22, v22 row_half_mirror row_mask:0xf bank_mask:0xf bound_ctrl:1
	v_add_f32_dpp v23, v23, v23 row_half_mirror row_mask:0xf bank_mask:0xf bound_ctrl:1
	v_add_f32_dpp v30, v30, v30 quad_perm:[2,3,0,1] row_mask:0xf bank_mask:0xf bound_ctrl:1
	v_add_f32_dpp v31, v31, v31 quad_perm:[2,3,0,1] row_mask:0xf bank_mask:0xf bound_ctrl:1
	v_add_f32_dpp v22, v22, v22 row_mirror row_mask:0xf bank_mask:0xf bound_ctrl:1
	v_add_f32_dpp v23, v23, v23 row_mirror row_mask:0xf bank_mask:0xf bound_ctrl:1
	s_waitcnt lgkmcnt(1)
	v_pk_mul_f32 v[24:25], v[26:27], v[22:23] op_sel_hi:[0,1]
	v_add_f32_dpp v30, v30, v30 row_half_mirror row_mask:0xf bank_mask:0xf bound_ctrl:1
	v_add_f32_dpp v31, v31, v31 row_half_mirror row_mask:0xf bank_mask:0xf bound_ctrl:1
	v_pk_fma_f32 v[24:25], v[6:7], v[54:55], v[24:25] op_sel_hi:[0,1,1] neg_lo:[0,0,1] neg_hi:[0,0,1]
	v_add_f32_dpp v30, v30, v30 row_mirror row_mask:0xf bank_mask:0xf bound_ctrl:1
	v_add_f32_dpp v31, v31, v31 row_mirror row_mask:0xf bank_mask:0xf bound_ctrl:1
	s_waitcnt lgkmcnt(0)
	v_pk_fma_f32 v[54:55], v[18:19], v[60:61], v[24:25] op_sel_hi:[0,1,1]
	v_cvt_pk_bf16_f32 v17, v30, v31
	v_pk_mul_f32 v[24:25], v[26:27], v[22:23] op_sel:[1,0]
	ds_write_b32 v14, v17 offset:2944
	v_pk_fma_f32 v[6:7], v[6:7], v[50:51], v[24:25] op_sel:[1,0,0] neg_lo:[0,0,1] neg_hi:[0,0,1]
	ds_read_b128 v[30:33], v15 offset:38400
	ds_read_b128 v[34:37], v15 offset:38656
	ds_read_b128 v[38:41], v15 offset:38912
	ds_read_b128 v[42:45], v15 offset:39168
	ds_read_b128 v[46:49], v15 offset:39424
	ds_read_b64 v[58:59], v16 offset:39680
	v_pk_fma_f32 v[50:51], v[18:19], v[60:61], v[6:7] op_sel:[1,0,0]
	v_pk_mul_f32 v[6:7], v[28:29], v[22:23] op_sel_hi:[0,1]
	v_pk_fma_f32 v[6:7], v[8:9], v[56:57], v[6:7] op_sel_hi:[0,1,1] neg_lo:[0,0,1] neg_hi:[0,0,1]
	v_pk_fma_f32 v[56:57], v[20:21], v[60:61], v[6:7] op_sel_hi:[0,1,1]
	v_mov_b32_e32 v6, v9
	v_pk_mul_f32 v[8:9], v[28:29], v[22:23] op_sel:[1,0] op_sel_hi:[1,1]
	s_nop 0
	v_pk_fma_f32 v[6:7], v[6:7], v[52:53], v[8:9] op_sel_hi:[0,1,1] neg_lo:[0,0,1] neg_hi:[0,0,1]
	s_waitcnt lgkmcnt(2)
	v_pk_mul_f32 v[62:63], v[42:43], v[50:51] op_sel:[1,0]
	v_pk_fma_f32 v[52:53], v[20:21], v[60:61], v[6:7] op_sel:[1,0,0] op_sel_hi:[1,1,1]
	v_pk_mul_f32 v[6:7], v[2:3], v[50:51] op_sel:[1,0]
	v_pk_fma_f32 v[42:43], v[42:43], v[54:55], v[62:63] op_sel_hi:[0,1,1]
	v_pk_fma_f32 v[2:3], v[2:3], v[54:55], v[6:7] op_sel_hi:[0,1,1]
	v_pk_mul_f32 v[62:63], v[44:45], v[52:53] op_sel:[1,0] op_sel_hi:[1,1]
	v_pk_mul_f32 v[6:7], v[4:5], v[52:53] op_sel:[1,0] op_sel_hi:[1,1]
	v_pk_fma_f32 v[44:45], v[44:45], v[56:57], v[62:63] op_sel_hi:[0,1,1]
	v_pk_fma_f32 v[4:5], v[4:5], v[56:57], v[6:7] op_sel_hi:[0,1,1]
	v_pk_add_f32 v[42:43], v[42:43], v[44:45]
	v_pk_add_f32 v[2:3], v[2:3], v[4:5]
	s_nop 0
	v_add_f32_dpp v42, v42, v42 quad_perm:[1,0,3,2] row_mask:0xf bank_mask:0xf bound_ctrl:1
	v_add_f32_dpp v43, v43, v43 quad_perm:[1,0,3,2] row_mask:0xf bank_mask:0xf bound_ctrl:1
	v_add_f32_dpp v2, v2, v2 quad_perm:[1,0,3,2] row_mask:0xf bank_mask:0xf bound_ctrl:1
	v_add_f32_dpp v3, v3, v3 quad_perm:[1,0,3,2] row_mask:0xf bank_mask:0xf bound_ctrl:1
	v_add_f32_dpp v42, v42, v42 quad_perm:[2,3,0,1] row_mask:0xf bank_mask:0xf bound_ctrl:1
	v_add_f32_dpp v43, v43, v43 quad_perm:[2,3,0,1] row_mask:0xf bank_mask:0xf bound_ctrl:1
	v_add_f32_dpp v2, v2, v2 quad_perm:[2,3,0,1] row_mask:0xf bank_mask:0xf bound_ctrl:1
	v_add_f32_dpp v3, v3, v3 quad_perm:[2,3,0,1] row_mask:0xf bank_mask:0xf bound_ctrl:1
	v_add_f32_dpp v42, v42, v42 row_half_mirror row_mask:0xf bank_mask:0xf bound_ctrl:1
	v_add_f32_dpp v43, v43, v43 row_half_mirror row_mask:0xf bank_mask:0xf bound_ctrl:1
	v_add_f32_dpp v2, v2, v2 row_half_mirror row_mask:0xf bank_mask:0xf bound_ctrl:1
	v_add_f32_dpp v3, v3, v3 row_half_mirror row_mask:0xf bank_mask:0xf bound_ctrl:1
	v_add_f32_dpp v42, v42, v42 row_mirror row_mask:0xf bank_mask:0xf bound_ctrl:1
	v_add_f32_dpp v43, v43, v43 row_mirror row_mask:0xf bank_mask:0xf bound_ctrl:1
	s_waitcnt lgkmcnt(1)
; #define LAS __attribute__((address_space(3)))
; DI unsigned pk2(float a, float b) { f32x2 v = {a, b}; bf2_t r = __builtin_convertvector(v, bf2_t); return __builtin_bit_cast(unsigned, r); }
; DI f32x2 red16p(f32x2 x) { float a = x.x, b = x.y; red16x2(a, b); return (f32x2){a, b}; }
; DI void scan_bh2(const Args& a, int l, int bh, int halfsel, LAS unsigned char* lds) {
;     ...
;             for (int st = 0; st < T; ++st) {
;                 f32x4 nr4, nd4, nk4, nkk4, nb4; f32x2 nv2;
;                 if (st < T - 1) {
;                     const LAS float* o = cur + (st + 1) * 384;
;                     nr4 = *(const LAS f32x4*)(o + kq * 4); nd4 = *(const LAS f32x4*)(o + 64 + kq * 4); nk4 = *(const LAS f32x4*)(o + 128 + kq * 4);
;                     nkk4 = *(const LAS f32x4*)(o + 192 + kq * 4); nb4 = *(const LAS f32x4*)(o + 256 + kq * 4); nv2 = *(const LAS f32x2*)(o + 320 + row0);
;                 }
;                 f32x2 sa = S[0] * kk4[0]; sa += S[1] * kk4[1]; f32x2 sb = S[2] * kk4[2]; sb += S[3] * kk4[3]; sa += sb;
;                 sa = red16p(sa); sa = -sa;
; #pragma unroll
;                 for (int j = 0; j < 4; ++j) S[j] = S[j] * d4[j] + sa * b4[j] + v2 * k4[j];
;                 f32x2 y = S[0] * r4[0]; y += S[1] * r4[1]; f32x2 yc = S[2] * r4[2]; yc += S[3] * r4[3]; y += yc;
;                 y = red16p(y);
;                 *(LAS unsigned*)(yb + st * 128 + row0 * 2) = pk2(y.x, y.y);
;                 if (st < T - 1) { r4 = nr4; d4 = nd4; k4 = nk4; kk4 = nkk4; b4 = nb4; v2 = nv2; }
	v_pk_mul_f32 v[44:45], v[46:47], v[42:43] op_sel_hi:[0,1]
	v_add_f32_dpp v2, v2, v2 row_mirror row_mask:0xf bank_mask:0xf bound_ctrl:1
	v_add_f32_dpp v3, v3, v3 row_mirror row_mask:0xf bank_mask:0xf bound_ctrl:1
	v_pk_fma_f32 v[44:45], v[34:35], v[54:55], v[44:45] op_sel_hi:[0,1,1] neg_lo:[0,0,1] neg_hi:[0,0,1]
	v_cvt_pk_bf16_f32 v2, v2, v3
	s_waitcnt lgkmcnt(0)
	v_pk_fma_f32 v[54:55], v[38:39], v[58:59], v[44:45] op_sel_hi:[0,1,1]
	v_pk_mul_f32 v[44:45], v[46:47], v[42:43] op_sel:[1,0]
	ds_write_b32 v14, v2 offset:3072
	v_pk_fma_f32 v[34:35], v[34:35], v[50:51], v[44:45] op_sel:[1,0,0] neg_lo:[0,0,1] neg_hi:[0,0,1]
	ds_read_b128 v[2:5], v15 offset:39936
	ds_read_b128 v[6:9], v15 offset:40192
	ds_read_b128 v[18:21], v15 offset:40448
	ds_read_b128 v[22:25], v15 offset:40704
	ds_read_b128 v[26:29], v15 offset:40960
	ds_read_b64 v[60:61], v16 offset:41216
	v_pk_fma_f32 v[50:51], v[38:39], v[58:59], v[34:35] op_sel:[1,0,0]
	v_pk_mul_f32 v[34:35], v[48:49], v[42:43] op_sel_hi:[0,1]
	v_pk_fma_f32 v[34:35], v[36:37], v[56:57], v[34:35] op_sel_hi:[0,1,1] neg_lo:[0,0,1] neg_hi:[0,0,1]
	v_pk_fma_f32 v[56:57], v[40:41], v[58:59], v[34:35] op_sel_hi:[0,1,1]
	v_mov_b32_e32 v34, v37
	v_pk_mul_f32 v[36:37], v[48:49], v[42:43] op_sel:[1,0] op_sel_hi:[1,1]
	s_nop 0
	v_pk_fma_f32 v[34:35], v[34:35], v[52:53], v[36:37] op_sel_hi:[0,1,1] neg_lo:[0,0,1] neg_hi:[0,0,1]
	s_waitcnt lgkmcnt(2)
	v_pk_mul_f32 v[62:63], v[22:23], v[50:51] op_sel:[1,0]
	v_pk_fma_f32 v[52:53], v[40:41], v[58:59], v[34:35] op_sel:[1,0,0] op_sel_hi:[1,1,1]
	v_pk_fma_f32 v[22:23], v[22:23], v[54:55], v[62:63] op_sel_hi:[0,1,1]
	v_pk_mul_f32 v[34:35], v[30:31], v[50:51] op_sel:[1,0]
	v_pk_mul_f32 v[62:63], v[24:25], v[52:53] op_sel:[1,0] op_sel_hi:[1,1]
	v_pk_fma_f32 v[30:31], v[30:31], v[54:55], v[34:35] op_sel_hi:[0,1,1]
	v_pk_fma_f32 v[24:25], v[24:25], v[56:57], v[62:63] op_sel_hi:[0,1,1]
	v_pk_mul_f32 v[34:35], v[32:33], v[52:53] op_sel:[1,0] op_sel_hi:[1,1]
	v_pk_add_f32 v[22:23], v[22:23], v[24:25]
	v_pk_fma_f32 v[32:33], v[32:33], v[56:57], v[34:35] op_sel_hi:[0,1,1]
	s_nop 0
	v_add_f32_dpp v22, v22, v22 quad_perm:[1,0,3,2] row_mask:0xf bank_mask:0xf bound_ctrl:1
	v_add_f32_dpp v23, v23, v23 quad_perm:[1,0,3,2] row_mask:0xf bank_mask:0xf bound_ctrl:1
	v_pk_add_f32 v[30:31], v[30:31], v[32:33]
	v_add_f32_dpp v22, v22, v22 quad_perm:[2,3,0,1] row_mask:0xf bank_mask:0xf bound_ctrl:1
	v_add_f32_dpp v23, v23, v23 quad_perm:[2,3,0,1] row_mask:0xf bank_mask:0xf bound_ctrl:1
	v_add_f32_dpp v30, v30, v30 quad_perm:[1,0,3,2] row_mask:0xf bank_mask:0xf bound_ctrl:1
	v_add_f32_dpp v31, v31, v31 quad_perm:[1,0,3,2] row_mask:0xf bank_mask:0xf bound_ctrl:1
	v_add_f32_dpp v22, v22, v22 row_half_mirror row_mask:0xf bank_mask:0xf bound_ctrl:1
	v_add_f32_dpp v23, v23, v23 row_half_mirror row_mask:0xf bank_mask:0xf bound_ctrl:1
	v_add_f32_dpp v30, v30, v30 quad_perm:[2,3,0,1] row_mask:0xf bank_mask:0xf bound_ctrl:1
	v_add_f32_dpp v31, v31, v31 quad_perm:[2,3,0,1] row_mask:0xf bank_mask:0xf bound_ctrl:1
	v_add_f32_dpp v22, v22, v22 row_mirror row_mask:0xf bank_mask:0xf bound_ctrl:1
	v_add_f32_dpp v23, v23, v23 row_mirror row_mask:0xf bank_mask:0xf bound_ctrl:1
	s_waitcnt lgkmcnt(1)
	v_pk_mul_f32 v[24:25], v[26:27], v[22:23] op_sel_hi:[0,1]
	v_add_f32_dpp v30, v30, v30 row_half_mirror row_mask:0xf bank_mask:0xf bound_ctrl:1
	v_add_f32_dpp v31, v31, v31 row_half_mirror row_mask:0xf bank_mask:0xf bound_ctrl:1
	v_pk_fma_f32 v[24:25], v[6:7], v[54:55], v[24:25] op_sel_hi:[0,1,1] neg_lo:[0,0,1] neg_hi:[0,0,1]
	v_add_f32_dpp v30, v30, v30 row_mirror row_mask:0xf bank_mask:0xf bound_ctrl:1
	v_add_f32_dpp v31, v31, v31 row_mirror row_mask:0xf bank_mask:0xf bound_ctrl:1
	s_waitcnt lgkmcnt(0)
	v_pk_fma_f32 v[54:55], v[18:19], v[60:61], v[24:25] op_sel_hi:[0,1,1]
	v_cvt_pk_bf16_f32 v17, v30, v31
	v_pk_mul_f32 v[24:25], v[26:27], v[22:23] op_sel:[1,0]
	ds_write_b32 v14, v17 offset:3200
	v_pk_fma_f32 v[6:7], v[6:7], v[50:51], v[24:25] op_sel:[1,0,0] neg_lo:[0,0,1] neg_hi:[0,0,1]
	ds_read_b128 v[30:33], v15 offset:41472
	ds_read_b128 v[34:37], v15 offset:41728
	ds_read_b128 v[38:41], v15 offset:41984
	ds_read_b128 v[42:45], v15 offset:42240
	ds_read_b128 v[46:49], v15 offset:42496
	ds_read_b64 v[58:59], v16 offset:42752
	v_pk_fma_f32 v[50:51], v[18:19], v[60:61], v[6:7] op_sel:[1,0,0]
	v_pk_mul_f32 v[6:7], v[28:29], v[22:23] op_sel_hi:[0,1]
	v_pk_fma_f32 v[6:7], v[8:9], v[56:57], v[6:7] op_sel_hi:[0,1,1] neg_lo:[0,0,1] neg_hi:[0,0,1]
	v_pk_fma_f32 v[56:57], v[20:21], v[60:61], v[6:7] op_sel_hi:[0,1,1]
	v_mov_b32_e32 v6, v9
	v_pk_mul_f32 v[8:9], v[28:29], v[22:23] op_sel:[1,0] op_sel_hi:[1,1]
	s_nop 0
	v_pk_fma_f32 v[6:7], v[6:7], v[52:53], v[8:9] op_sel_hi:[0,1,1] neg_lo:[0,0,1] neg_hi:[0,0,1]
	s_waitcnt lgkmcnt(2)
; #define LAS __attribute__((address_space(3)))
; DI unsigned pk2(float a, float b) { f32x2 v = {a, b}; bf2_t r = __builtin_convertvector(v, bf2_t); return __builtin_bit_cast(unsigned, r); }
; DI f32x2 red16p(f32x2 x) { float a = x.x, b = x.y; red16x2(a, b); return (f32x2){a, b}; }
; DI void scan_bh2(const Args& a, int l, int bh, int halfsel, LAS unsigned char* lds) {
;     ...
;             for (int st = 0; st < T; ++st) {
;                 f32x4 nr4, nd4, nk4, nkk4, nb4; f32x2 nv2;
;                 if (st < T - 1) {
;                     const LAS float* o = cur + (st + 1) * 384;
;                     nr4 = *(const LAS f32x4*)(o + kq * 4); nd4 = *(const LAS f32x4*)(o + 64 + kq * 4); nk4 = *(const LAS f32x4*)(o + 128 + kq * 4);
;                     nkk4 = *(const LAS f32x4*)(o + 192 + kq * 4); nb4 = *(const LAS f32x4*)(o + 256 + kq * 4); nv2 = *(const LAS f32x2*)(o + 320 + row0);
;                 }
;                 f32x2 sa = S[0] * kk4[0]; sa += S[1] * kk4[1]; f32x2 sb = S[2] * kk4[2]; sb += S[3] * kk4[3]; sa += sb;
;                 sa = red16p(sa); sa = -sa;
; #pragma unroll
;                 for (int j = 0; j < 4; ++j) S[j] = S[j] * d4[j] + sa * b4[j] + v2 * k4[j];
;                 f32x2 y = S[0] * r4[0]; y += S[1] * r4[1]; f32x2 yc = S[2] * r4[2]; yc += S[3] * r4[3]; y += yc;
;                 y = red16p(y);
;                 *(LAS unsigned*)(yb + st * 128 + row0 * 2) = pk2(y.x, y.y);
;                 if (st < T - 1) { r4 = nr4; d4 = nd4; k4 = nk4; kk4 = nkk4; b4 = nb4; v2 = nv2; }
	v_pk_mul_f32 v[62:63], v[42:43], v[50:51] op_sel:[1,0]
	v_pk_fma_f32 v[52:53], v[20:21], v[60:61], v[6:7] op_sel:[1,0,0] op_sel_hi:[1,1,1]
	v_pk_mul_f32 v[6:7], v[2:3], v[50:51] op_sel:[1,0]
	v_pk_fma_f32 v[42:43], v[42:43], v[54:55], v[62:63] op_sel_hi:[0,1,1]
	v_pk_fma_f32 v[2:3], v[2:3], v[54:55], v[6:7] op_sel_hi:[0,1,1]
	v_pk_mul_f32 v[62:63], v[44:45], v[52:53] op_sel:[1,0] op_sel_hi:[1,1]
	v_pk_mul_f32 v[6:7], v[4:5], v[52:53] op_sel:[1,0] op_sel_hi:[1,1]
	v_pk_fma_f32 v[44:45], v[44:45], v[56:57], v[62:63] op_sel_hi:[0,1,1]
	v_pk_fma_f32 v[4:5], v[4:5], v[56:57], v[6:7] op_sel_hi:[0,1,1]
	v_pk_add_f32 v[42:43], v[42:43], v[44:45]
	v_pk_add_f32 v[2:3], v[2:3], v[4:5]
	s_nop 0
	v_add_f32_dpp v42, v42, v42 quad_perm:[1,0,3,2] row_mask:0xf bank_mask:0xf bound_ctrl:1
	v_add_f32_dpp v43, v43, v43 quad_perm:[1,0,3,2] row_mask:0xf bank_mask:0xf bound_ctrl:1
	v_add_f32_dpp v2, v2, v2 quad_perm:[1,0,3,2] row_mask:0xf bank_mask:0xf bound_ctrl:1
	v_add_f32_dpp v3, v3, v3 quad_perm:[1,0,3,2] row_mask:0xf bank_mask:0xf bound_ctrl:1
	v_add_f32_dpp v42, v42, v42 quad_perm:[2,3,0,1] row_mask:0xf bank_mask:0xf bound_ctrl:1
	v_add_f32_dpp v43, v43, v43 quad_perm:[2,3,0,1] row_mask:0xf bank_mask:0xf bound_ctrl:1
	v_add_f32_dpp v2, v2, v2 quad_perm:[2,3,0,1] row_mask:0xf bank_mask:0xf bound_ctrl:1
	v_add_f32_dpp v3, v3, v3 quad_perm:[2,3,0,1] row_mask:0xf bank_mask:0xf bound_ctrl:1
	v_add_f32_dpp v42, v42, v42 row_half_mirror row_mask:0xf bank_mask:0xf bound_ctrl:1
	v_add_f32_dpp v43, v43, v43 row_half_mirror row_mask:0xf bank_mask:0xf bound_ctrl:1
	v_add_f32_dpp v2, v2, v2 row_half_mirror row_mask:0xf bank_mask:0xf bound_ctrl:1
	v_add_f32_dpp v3, v3, v3 row_half_mirror row_mask:0xf bank_mask:0xf bound_ctrl:1
	v_add_f32_dpp v42, v42, v42 row_mirror row_mask:0xf bank_mask:0xf bound_ctrl:1
	v_add_f32_dpp v43, v43, v43 row_mirror row_mask:0xf bank_mask:0xf bound_ctrl:1
	s_waitcnt lgkmcnt(1)
	v_pk_mul_f32 v[44:45], v[46:47], v[42:43] op_sel_hi:[0,1]
	v_add_f32_dpp v2, v2, v2 row_mirror row_mask:0xf bank_mask:0xf bound_ctrl:1
	v_add_f32_dpp v3, v3, v3 row_mirror row_mask:0xf bank_mask:0xf bound_ctrl:1
	v_pk_fma_f32 v[44:45], v[34:35], v[54:55], v[44:45] op_sel_hi:[0,1,1] neg_lo:[0,0,1] neg_hi:[0,0,1]
	v_cvt_pk_bf16_f32 v2, v2, v3
	s_waitcnt lgkmcnt(0)
	v_pk_fma_f32 v[54:55], v[38:39], v[58:59], v[44:45] op_sel_hi:[0,1,1]
	v_pk_mul_f32 v[44:45], v[46:47], v[42:43] op_sel:[1,0]
	ds_write_b32 v14, v2 offset:3328
	v_pk_fma_f32 v[34:35], v[34:35], v[50:51], v[44:45] op_sel:[1,0,0] neg_lo:[0,0,1] neg_hi:[0,0,1]
	ds_read_b128 v[2:5], v15 offset:43008
	ds_read_b128 v[6:9], v15 offset:43264
	ds_read_b128 v[18:21], v15 offset:43520
	ds_read_b128 v[22:25], v15 offset:43776
	ds_read_b128 v[26:29], v15 offset:44032
	ds_read_b64 v[60:61], v16 offset:44288
	v_pk_fma_f32 v[50:51], v[38:39], v[58:59], v[34:35] op_sel:[1,0,0]
	v_pk_mul_f32 v[34:35], v[48:49], v[42:43] op_sel_hi:[0,1]
	v_pk_fma_f32 v[34:35], v[36:37], v[56:57], v[34:35] op_sel_hi:[0,1,1] neg_lo:[0,0,1] neg_hi:[0,0,1]
	v_pk_fma_f32 v[56:57], v[40:41], v[58:59], v[34:35] op_sel_hi:[0,1,1]
	v_mov_b32_e32 v34, v37
	v_pk_mul_f32 v[36:37], v[48:49], v[42:43] op_sel:[1,0] op_sel_hi:[1,1]
	s_nop 0
	v_pk_fma_f32 v[34:35], v[34:35], v[52:53], v[36:37] op_sel_hi:[0,1,1] neg_lo:[0,0,1] neg_hi:[0,0,1]
	s_waitcnt lgkmcnt(2)
	v_pk_mul_f32 v[62:63], v[22:23], v[50:51] op_sel:[1,0]
	v_pk_fma_f32 v[52:53], v[40:41], v[58:59], v[34:35] op_sel:[1,0,0] op_sel_hi:[1,1,1]
	v_pk_fma_f32 v[22:23], v[22:23], v[54:55], v[62:63] op_sel_hi:[0,1,1]
	v_pk_mul_f32 v[34:35], v[30:31], v[50:51] op_sel:[1,0]
	v_pk_mul_f32 v[62:63], v[24:25], v[52:53] op_sel:[1,0] op_sel_hi:[1,1]
	v_pk_fma_f32 v[30:31], v[30:31], v[54:55], v[34:35] op_sel_hi:[0,1,1]
	v_pk_fma_f32 v[24:25], v[24:25], v[56:57], v[62:63] op_sel_hi:[0,1,1]
	v_pk_mul_f32 v[34:35], v[32:33], v[52:53] op_sel:[1,0] op_sel_hi:[1,1]
	v_pk_add_f32 v[22:23], v[22:23], v[24:25]
	v_pk_fma_f32 v[32:33], v[32:33], v[56:57], v[34:35] op_sel_hi:[0,1,1]
	s_nop 0
	v_add_f32_dpp v22, v22, v22 quad_perm:[1,0,3,2] row_mask:0xf bank_mask:0xf bound_ctrl:1
	v_add_f32_dpp v23, v23, v23 quad_perm:[1,0,3,2] row_mask:0xf bank_mask:0xf bound_ctrl:1
	v_pk_add_f32 v[30:31], v[30:31], v[32:33]
	v_add_f32_dpp v22, v22, v22 quad_perm:[2,3,0,1] row_mask:0xf bank_mask:0xf bound_ctrl:1
	v_add_f32_dpp v23, v23, v23 quad_perm:[2,3,0,1] row_mask:0xf bank_mask:0xf bound_ctrl:1
	v_add_f32_dpp v30, v30, v30 quad_perm:[1,0,3,2] row_mask:0xf bank_mask:0xf bound_ctrl:1
	v_add_f32_dpp v31, v31, v31 quad_perm:[1,0,3,2] row_mask:0xf bank_mask:0xf bound_ctrl:1
	v_add_f32_dpp v22, v22, v22 row_half_mirror row_mask:0xf bank_mask:0xf bound_ctrl:1
	v_add_f32_dpp v23, v23, v23 row_half_mirror row_mask:0xf bank_mask:0xf bound_ctrl:1
	v_add_f32_dpp v30, v30, v30 quad_perm:[2,3,0,1] row_mask:0xf bank_mask:0xf bound_ctrl:1
	v_add_f32_dpp v31, v31, v31 quad_perm:[2,3,0,1] row_mask:0xf bank_mask:0xf bound_ctrl:1
	v_add_f32_dpp v22, v22, v22 row_mirror row_mask:0xf bank_mask:0xf bound_ctrl:1
	v_add_f32_dpp v23, v23, v23 row_mirror row_mask:0xf bank_mask:0xf bound_ctrl:1
	s_waitcnt lgkmcnt(1)
	v_pk_mul_f32 v[24:25], v[26:27], v[22:23] op_sel_hi:[0,1]
	v_add_f32_dpp v30, v30, v30 row_half_mirror row_mask:0xf bank_mask:0xf bound_ctrl:1
	v_add_f32_dpp v31, v31, v31 row_half_mirror row_mask:0xf bank_mask:0xf bound_ctrl:1
	v_pk_fma_f32 v[24:25], v[6:7], v[54:55], v[24:25] op_sel_hi:[0,1,1] neg_lo:[0,0,1] neg_hi:[0,0,1]
	v_add_f32_dpp v30, v30, v30 row_mirror row_mask:0xf bank_mask:0xf bound_ctrl:1
	v_add_f32_dpp v31, v31, v31 row_mirror row_mask:0xf bank_mask:0xf bound_ctrl:1
	s_waitcnt lgkmcnt(0)
; #define LAS __attribute__((address_space(3)))
; DI unsigned pk2(float a, float b) { f32x2 v = {a, b}; bf2_t r = __builtin_convertvector(v, bf2_t); return __builtin_bit_cast(unsigned, r); }
; DI f32x2 red16p(f32x2 x) { float a = x.x, b = x.y; red16x2(a, b); return (f32x2){a, b}; }
; DI void scan_bh2(const Args& a, int l, int bh, int halfsel, LAS unsigned char* lds) {
;     ...
;             for (int st = 0; st < T; ++st) {
;                 f32x4 nr4, nd4, nk4, nkk4, nb4; f32x2 nv2;
;                 if (st < T - 1) {
;                     const LAS float* o = cur + (st + 1) * 384;
;                     nr4 = *(const LAS f32x4*)(o + kq * 4); nd4 = *(const LAS f32x4*)(o + 64 + kq * 4); nk4 = *(const LAS f32x4*)(o + 128 + kq * 4);
;                     nkk4 = *(const LAS f32x4*)(o + 192 + kq * 4); nb4 = *(const LAS f32x4*)(o + 256 + kq * 4); nv2 = *(const LAS f32x2*)(o + 320 + row0);
;                 }
;                 f32x2 sa = S[0] * kk4[0]; sa += S[1] * kk4[1]; f32x2 sb = S[2] * kk4[2]; sb += S[3] * kk4[3]; sa += sb;
;                 sa = red16p(sa); sa = -sa;
; #pragma unroll
;                 for (int j = 0; j < 4; ++j) S[j] = S[j] * d4[j] + sa * b4[j] + v2 * k4[j];
;                 f32x2 y = S[0] * r4[0]; y += S[1] * r4[1]; f32x2 yc = S[2] * r4[2]; yc += S[3] * r4[3]; y += yc;
;                 y = red16p(y);
;                 *(LAS unsigned*)(yb + st * 128 + row0 * 2) = pk2(y.x, y.y);
;                 if (st < T - 1) { r4 = nr4; d4 = nd4; k4 = nk4; kk4 = nkk4; b4 = nb4; v2 = nv2; }
	v_pk_fma_f32 v[54:55], v[18:19], v[60:61], v[24:25] op_sel_hi:[0,1,1]
	v_cvt_pk_bf16_f32 v17, v30, v31
	v_pk_mul_f32 v[24:25], v[26:27], v[22:23] op_sel:[1,0]
	ds_write_b32 v14, v17 offset:3456
	v_pk_fma_f32 v[6:7], v[6:7], v[50:51], v[24:25] op_sel:[1,0,0] neg_lo:[0,0,1] neg_hi:[0,0,1]
	ds_read_b128 v[30:33], v15 offset:44544
	ds_read_b128 v[34:37], v15 offset:44800
	ds_read_b128 v[38:41], v15 offset:45056
	ds_read_b128 v[42:45], v15 offset:45312
	ds_read_b128 v[46:49], v15 offset:45568
	ds_read_b64 v[58:59], v16 offset:45824
	v_pk_fma_f32 v[50:51], v[18:19], v[60:61], v[6:7] op_sel:[1,0,0]
	v_pk_mul_f32 v[6:7], v[28:29], v[22:23] op_sel_hi:[0,1]
	v_pk_fma_f32 v[6:7], v[8:9], v[56:57], v[6:7] op_sel_hi:[0,1,1] neg_lo:[0,0,1] neg_hi:[0,0,1]
	v_pk_fma_f32 v[56:57], v[20:21], v[60:61], v[6:7] op_sel_hi:[0,1,1]
	v_mov_b32_e32 v6, v9
	v_pk_mul_f32 v[8:9], v[28:29], v[22:23] op_sel:[1,0] op_sel_hi:[1,1]
	s_nop 0
	v_pk_fma_f32 v[6:7], v[6:7], v[52:53], v[8:9] op_sel_hi:[0,1,1] neg_lo:[0,0,1] neg_hi:[0,0,1]
	s_waitcnt lgkmcnt(2)
	v_pk_mul_f32 v[62:63], v[42:43], v[50:51] op_sel:[1,0]
	v_pk_fma_f32 v[52:53], v[20:21], v[60:61], v[6:7] op_sel:[1,0,0] op_sel_hi:[1,1,1]
	v_pk_fma_f32 v[42:43], v[42:43], v[54:55], v[62:63] op_sel_hi:[0,1,1]
	v_pk_mul_f32 v[6:7], v[2:3], v[50:51] op_sel:[1,0]
	v_pk_mul_f32 v[62:63], v[44:45], v[52:53] op_sel:[1,0] op_sel_hi:[1,1]
	v_pk_fma_f32 v[2:3], v[2:3], v[54:55], v[6:7] op_sel_hi:[0,1,1]
	v_pk_fma_f32 v[44:45], v[44:45], v[56:57], v[62:63] op_sel_hi:[0,1,1]
	v_pk_mul_f32 v[6:7], v[4:5], v[52:53] op_sel:[1,0] op_sel_hi:[1,1]
	v_pk_add_f32 v[42:43], v[42:43], v[44:45]
	v_pk_fma_f32 v[4:5], v[4:5], v[56:57], v[6:7] op_sel_hi:[0,1,1]
	s_nop 0
	v_add_f32_dpp v42, v42, v42 quad_perm:[1,0,3,2] row_mask:0xf bank_mask:0xf bound_ctrl:1
	v_add_f32_dpp v43, v43, v43 quad_perm:[1,0,3,2] row_mask:0xf bank_mask:0xf bound_ctrl:1
	v_pk_add_f32 v[2:3], v[2:3], v[4:5]
	v_add_f32_dpp v42, v42, v42 quad_perm:[2,3,0,1] row_mask:0xf bank_mask:0xf bound_ctrl:1
	v_add_f32_dpp v43, v43, v43 quad_perm:[2,3,0,1] row_mask:0xf bank_mask:0xf bound_ctrl:1
	v_add_f32_dpp v2, v2, v2 quad_perm:[1,0,3,2] row_mask:0xf bank_mask:0xf bound_ctrl:1
	v_add_f32_dpp v3, v3, v3 quad_perm:[1,0,3,2] row_mask:0xf bank_mask:0xf bound_ctrl:1
	v_add_f32_dpp v42, v42, v42 row_half_mirror row_mask:0xf bank_mask:0xf bound_ctrl:1
	v_add_f32_dpp v43, v43, v43 row_half_mirror row_mask:0xf bank_mask:0xf bound_ctrl:1
	v_add_f32_dpp v2, v2, v2 quad_perm:[2,3,0,1] row_mask:0xf bank_mask:0xf bound_ctrl:1
	v_add_f32_dpp v3, v3, v3 quad_perm:[2,3,0,1] row_mask:0xf bank_mask:0xf bound_ctrl:1
	v_add_f32_dpp v42, v42, v42 row_mirror row_mask:0xf bank_mask:0xf bound_ctrl:1
	v_add_f32_dpp v43, v43, v43 row_mirror row_mask:0xf bank_mask:0xf bound_ctrl:1
	s_waitcnt lgkmcnt(1)
	v_pk_mul_f32 v[44:45], v[46:47], v[42:43] op_sel_hi:[0,1]
	v_add_f32_dpp v2, v2, v2 row_half_mirror row_mask:0xf bank_mask:0xf bound_ctrl:1
	v_add_f32_dpp v3, v3, v3 row_half_mirror row_mask:0xf bank_mask:0xf bound_ctrl:1
	v_pk_fma_f32 v[44:45], v[34:35], v[54:55], v[44:45] op_sel_hi:[0,1,1] neg_lo:[0,0,1] neg_hi:[0,0,1]
	v_add_f32_dpp v2, v2, v2 row_mirror row_mask:0xf bank_mask:0xf bound_ctrl:1
	v_add_f32_dpp v3, v3, v3 row_mirror row_mask:0xf bank_mask:0xf bound_ctrl:1
	s_waitcnt lgkmcnt(0)
	v_pk_fma_f32 v[54:55], v[38:39], v[58:59], v[44:45] op_sel_hi:[0,1,1]
	v_pk_mul_f32 v[44:45], v[46:47], v[42:43] op_sel:[1,0]
	v_cvt_pk_bf16_f32 v2, v2, v3
	v_pk_fma_f32 v[34:35], v[34:35], v[50:51], v[44:45] op_sel:[1,0,0] neg_lo:[0,0,1] neg_hi:[0,0,1]
	ds_write_b32 v14, v2 offset:3584
	v_pk_fma_f32 v[50:51], v[38:39], v[58:59], v[34:35] op_sel:[1,0,0]
	v_pk_mul_f32 v[34:35], v[48:49], v[42:43] op_sel_hi:[0,1]
	ds_read_b128 v[2:5], v15 offset:46080
	ds_read_b128 v[6:9], v15 offset:46336
	ds_read_b128 v[18:21], v15 offset:46592
	ds_read_b128 v[22:25], v15 offset:46848
	ds_read_b128 v[26:29], v15 offset:47104
	ds_read_b64 v[60:61], v16 offset:47360
	v_pk_fma_f32 v[34:35], v[36:37], v[56:57], v[34:35] op_sel_hi:[0,1,1] neg_lo:[0,0,1] neg_hi:[0,0,1]
	v_pk_fma_f32 v[56:57], v[40:41], v[58:59], v[34:35] op_sel_hi:[0,1,1]
	v_mov_b32_e32 v34, v37
	v_pk_mul_f32 v[36:37], v[48:49], v[42:43] op_sel:[1,0] op_sel_hi:[1,1]
	s_nop 0
	v_pk_fma_f32 v[34:35], v[34:35], v[52:53], v[36:37] op_sel_hi:[0,1,1] neg_lo:[0,0,1] neg_hi:[0,0,1]
	v_pk_fma_f32 v[52:53], v[40:41], v[58:59], v[34:35] op_sel:[1,0,0] op_sel_hi:[1,1,1]
	s_waitcnt lgkmcnt(2)
	v_pk_mul_f32 v[58:59], v[22:23], v[50:51] op_sel:[1,0]
	v_pk_mul_f32 v[34:35], v[30:31], v[50:51] op_sel:[1,0]
	v_pk_fma_f32 v[22:23], v[22:23], v[54:55], v[58:59] op_sel_hi:[0,1,1]
	v_pk_mul_f32 v[58:59], v[24:25], v[52:53] op_sel:[1,0] op_sel_hi:[1,1]
	s_nop 0
	v_pk_fma_f32 v[24:25], v[24:25], v[56:57], v[58:59] op_sel_hi:[0,1,1]
	v_pk_add_f32 v[22:23], v[22:23], v[24:25]
	v_pk_fma_f32 v[30:31], v[30:31], v[54:55], v[34:35] op_sel_hi:[0,1,1]
	s_nop 0
	v_add_f32_dpp v22, v22, v22 quad_perm:[1,0,3,2] row_mask:0xf bank_mask:0xf bound_ctrl:1
	v_add_f32_dpp v23, v23, v23 quad_perm:[1,0,3,2] row_mask:0xf bank_mask:0xf bound_ctrl:1
	s_nop 0
	v_add_f32_dpp v22, v22, v22 quad_perm:[2,3,0,1] row_mask:0xf bank_mask:0xf bound_ctrl:1
	v_add_f32_dpp v23, v23, v23 quad_perm:[2,3,0,1] row_mask:0xf bank_mask:0xf bound_ctrl:1
	v_pk_mul_f32 v[34:35], v[32:33], v[52:53] op_sel:[1,0] op_sel_hi:[1,1]
	v_add_f32_dpp v22, v22, v22 row_half_mirror row_mask:0xf bank_mask:0xf bound_ctrl:1
	v_add_f32_dpp v23, v23, v23 row_half_mirror row_mask:0xf bank_mask:0xf bound_ctrl:1
	v_pk_fma_f32 v[32:33], v[32:33], v[56:57], v[34:35] op_sel_hi:[0,1,1]
	v_add_f32_dpp v22, v22, v22 row_mirror row_mask:0xf bank_mask:0xf bound_ctrl:1
	v_add_f32_dpp v23, v23, v23 row_mirror row_mask:0xf bank_mask:0xf bound_ctrl:1
	v_pk_add_f32 v[30:31], v[30:31], v[32:33]
	s_waitcnt lgkmcnt(1)
; #define LAS __attribute__((address_space(3)))
; DI unsigned pk2(float a, float b) { f32x2 v = {a, b}; bf2_t r = __builtin_convertvector(v, bf2_t); return __builtin_bit_cast(unsigned, r); }
; DI f32x2 red16p(f32x2 x) { float a = x.x, b = x.y; red16x2(a, b); return (f32x2){a, b}; }
; DI void scan_bh2(const Args& a, int l, int bh, int halfsel, LAS unsigned char* lds) {
;     ...
;             for (int st = 0; st < T; ++st) {
;                 f32x4 nr4, nd4, nk4, nkk4, nb4; f32x2 nv2;
;                 if (st < T - 1) {
;                     const LAS float* o = cur + (st + 1) * 384;
;                     nr4 = *(const LAS f32x4*)(o + kq * 4); nd4 = *(const LAS f32x4*)(o + 64 + kq * 4); nk4 = *(const LAS f32x4*)(o + 128 + kq * 4);
;                     nkk4 = *(const LAS f32x4*)(o + 192 + kq * 4); nb4 = *(const LAS f32x4*)(o + 256 + kq * 4); nv2 = *(const LAS f32x2*)(o + 320 + row0);
;                 }
;                 f32x2 sa = S[0] * kk4[0]; sa += S[1] * kk4[1]; f32x2 sb = S[2] * kk4[2]; sb += S[3] * kk4[3]; sa += sb;
;                 sa = red16p(sa); sa = -sa;
; #pragma unroll
;                 for (int j = 0; j < 4; ++j) S[j] = S[j] * d4[j] + sa * b4[j] + v2 * k4[j];
;                 f32x2 y = S[0] * r4[0]; y += S[1] * r4[1]; f32x2 yc = S[2] * r4[2]; yc += S[3] * r4[3]; y += yc;
;                 y = red16p(y);
;                 *(LAS unsigned*)(yb + st * 128 + row0 * 2) = pk2(y.x, y.y);
;                 if (st < T - 1) { r4 = nr4; d4 = nd4; k4 = nk4; kk4 = nkk4; b4 = nb4; v2 = nv2; }
;             }
;             __syncthreads();
;             if (tid < T * 4) { const int rowi = tid >> 2, seg = tid & 3;
;                 *(u32x4*)(Y + ((size_t)b * SEQ + c * T + rowi) * 512 + h * 64 + halfsel * 32 + seg * 8) = *(const LAS u32x4*)(yb + rowi * 128 + halfsel * 64 + seg * 16); }
	v_pk_mul_f32 v[24:25], v[26:27], v[22:23] op_sel_hi:[0,1]
	v_pk_mul_f32 v[26:27], v[26:27], v[22:23] op_sel:[1,0]
	v_pk_fma_f32 v[24:25], v[6:7], v[54:55], v[24:25] op_sel_hi:[0,1,1] neg_lo:[0,0,1] neg_hi:[0,0,1]
	v_pk_fma_f32 v[6:7], v[6:7], v[50:51], v[26:27] op_sel:[1,0,0] neg_lo:[0,0,1] neg_hi:[0,0,1]
	s_waitcnt lgkmcnt(0)
	v_pk_fma_f32 v[24:25], v[18:19], v[60:61], v[24:25] op_sel_hi:[0,1,1]
	v_pk_fma_f32 v[6:7], v[18:19], v[60:61], v[6:7] op_sel:[1,0,0]
	v_pk_mul_f32 v[18:19], v[28:29], v[22:23] op_sel_hi:[0,1]
	v_pk_fma_f32 v[18:19], v[8:9], v[56:57], v[18:19] op_sel_hi:[0,1,1] neg_lo:[0,0,1] neg_hi:[0,0,1]
	v_pk_fma_f32 v[18:19], v[20:21], v[60:61], v[18:19] op_sel_hi:[0,1,1]
	v_pk_mul_f32 v[22:23], v[28:29], v[22:23] op_sel:[1,0] op_sel_hi:[1,1]
	s_nop 0
	v_pk_fma_f32 v[8:9], v[8:9], v[52:53], v[22:23] op_sel:[1,0,0] op_sel_hi:[1,1,1] neg_lo:[0,0,1] neg_hi:[0,0,1]
	v_add_f32_dpp v30, v30, v30 quad_perm:[1,0,3,2] row_mask:0xf bank_mask:0xf bound_ctrl:1
	v_add_f32_dpp v31, v31, v31 quad_perm:[1,0,3,2] row_mask:0xf bank_mask:0xf bound_ctrl:1
	v_pk_fma_f32 v[8:9], v[20:21], v[60:61], v[8:9] op_sel:[1,0,0] op_sel_hi:[1,1,1]
	v_pk_mul_f32 v[20:21], v[2:3], v[6:7] op_sel:[1,0]
	v_add_f32_dpp v30, v30, v30 quad_perm:[2,3,0,1] row_mask:0xf bank_mask:0xf bound_ctrl:1
	v_add_f32_dpp v31, v31, v31 quad_perm:[2,3,0,1] row_mask:0xf bank_mask:0xf bound_ctrl:1
	s_nop 0
	v_pk_fma_f32 v[2:3], v[2:3], v[24:25], v[20:21] op_sel_hi:[0,1,1]
	v_add_f32_dpp v30, v30, v30 row_half_mirror row_mask:0xf bank_mask:0xf bound_ctrl:1
	v_add_f32_dpp v31, v31, v31 row_half_mirror row_mask:0xf bank_mask:0xf bound_ctrl:1
	v_pk_mul_f32 v[20:21], v[4:5], v[8:9] op_sel:[1,0] op_sel_hi:[1,1]
	v_add_f32_dpp v30, v30, v30 row_mirror row_mask:0xf bank_mask:0xf bound_ctrl:1
	v_add_f32_dpp v31, v31, v31 row_mirror row_mask:0xf bank_mask:0xf bound_ctrl:1
	v_pk_fma_f32 v[4:5], v[4:5], v[18:19], v[20:21] op_sel_hi:[0,1,1]
	v_cvt_pk_bf16_f32 v17, v30, v31
	ds_write_b32 v14, v17 offset:3712
	v_pk_add_f32 v[2:3], v[2:3], v[4:5]
	ds_read_b128 v[30:33], v15 offset:47616
	ds_read_b128 v[34:37], v15 offset:47872
	ds_read_b128 v[38:41], v15 offset:48128
	ds_read_b128 v[42:45], v15 offset:48384
	ds_read_b128 v[46:49], v15 offset:48640
	ds_read_b64 v[16:17], v16 offset:48896
	v_add_f32_dpp v2, v2, v2 quad_perm:[1,0,3,2] row_mask:0xf bank_mask:0xf bound_ctrl:1
	v_add_f32_dpp v3, v3, v3 quad_perm:[1,0,3,2] row_mask:0xf bank_mask:0xf bound_ctrl:1
	v_add_u32_e32 v14, 0xc00, v14
	v_add_f32_dpp v2, v2, v2 quad_perm:[2,3,0,1] row_mask:0xf bank_mask:0xf bound_ctrl:1
	v_add_f32_dpp v3, v3, v3 quad_perm:[2,3,0,1] row_mask:0xf bank_mask:0xf bound_ctrl:1
	s_waitcnt lgkmcnt(2)
	v_add_f32_dpp v2, v2, v2 row_half_mirror row_mask:0xf bank_mask:0xf bound_ctrl:1
	v_add_f32_dpp v3, v3, v3 row_half_mirror row_mask:0xf bank_mask:0xf bound_ctrl:1
	v_pk_mul_f32 v[4:5], v[44:45], v[8:9] op_sel:[1,0] op_sel_hi:[1,1]
	v_add_f32_dpp v2, v2, v2 row_mirror row_mask:0xf bank_mask:0xf bound_ctrl:1
	v_add_f32_dpp v3, v3, v3 row_mirror row_mask:0xf bank_mask:0xf bound_ctrl:1
	v_pk_fma_f32 v[4:5], v[44:45], v[18:19], v[4:5] op_sel_hi:[0,1,1]
	v_cvt_pk_bf16_f32 v15, v2, v3
	v_pk_mul_f32 v[2:3], v[42:43], v[6:7] op_sel:[1,0]
	s_waitcnt lgkmcnt(1)
	v_mov_b32_e32 v22, v49
	v_pk_fma_f32 v[2:3], v[42:43], v[24:25], v[2:3] op_sel_hi:[0,1,1]
	v_pk_add_f32 v[20:21], v[2:3], v[4:5]
	s_nop 0
	s_nop 0
	v_add_f32_dpp v20, v20, v20 quad_perm:[1,0,3,2] row_mask:0xf bank_mask:0xf bound_ctrl:1
	v_add_f32_dpp v21, v21, v21 quad_perm:[1,0,3,2] row_mask:0xf bank_mask:0xf bound_ctrl:1
	s_nop 0
	v_add_f32_dpp v20, v20, v20 quad_perm:[2,3,0,1] row_mask:0xf bank_mask:0xf bound_ctrl:1
	v_add_f32_dpp v21, v21, v21 quad_perm:[2,3,0,1] row_mask:0xf bank_mask:0xf bound_ctrl:1
	s_nop 0
	v_add_f32_dpp v20, v20, v20 row_half_mirror row_mask:0xf bank_mask:0xf bound_ctrl:1
	v_add_f32_dpp v21, v21, v21 row_half_mirror row_mask:0xf bank_mask:0xf bound_ctrl:1
	s_nop 0
	v_add_f32_dpp v20, v20, v20 row_mirror row_mask:0xf bank_mask:0xf bound_ctrl:1
	v_add_f32_dpp v21, v21, v21 row_mirror row_mask:0xf bank_mask:0xf bound_ctrl:1
	s_nop 0
	v_pk_mul_f32 v[4:5], v[46:47], v[20:21] op_sel:[1,0]
	v_pk_mul_f32 v[2:3], v[46:47], v[20:21] op_sel_hi:[0,1]
	v_pk_fma_f32 v[4:5], v[34:35], v[6:7], v[4:5] op_sel:[1,0,0] neg_lo:[0,0,1] neg_hi:[0,0,1]
	v_pk_mul_f32 v[6:7], v[48:49], v[20:21] op_sel_hi:[0,1]
	v_pk_fma_f32 v[6:7], v[36:37], v[18:19], v[6:7] op_sel_hi:[0,1,1] neg_lo:[0,0,1] neg_hi:[0,0,1]
	v_pk_mul_f32 v[20:21], v[22:23], v[20:21] op_sel_hi:[0,1]
	v_pk_fma_f32 v[8:9], v[36:37], v[8:9], v[20:21] op_sel:[1,0,0] op_sel_hi:[1,1,1] neg_lo:[0,0,1] neg_hi:[0,0,1]
	v_pk_fma_f32 v[2:3], v[34:35], v[24:25], v[2:3] op_sel_hi:[0,1,1] neg_lo:[0,0,1] neg_hi:[0,0,1]
	s_waitcnt lgkmcnt(0)
	v_pk_fma_f32 v[4:5], v[38:39], v[16:17], v[4:5] op_sel:[1,0,0]
	v_pk_fma_f32 v[8:9], v[40:41], v[16:17], v[8:9] op_sel:[1,0,0] op_sel_hi:[1,1,1]
	v_pk_fma_f32 v[2:3], v[38:39], v[16:17], v[2:3] op_sel_hi:[0,1,1]
	v_pk_fma_f32 v[6:7], v[40:41], v[16:17], v[6:7] op_sel_hi:[0,1,1]
	v_pk_mul_f32 v[16:17], v[30:31], v[4:5] op_sel:[1,0]
	v_pk_mul_f32 v[18:19], v[32:33], v[8:9] op_sel:[1,0] op_sel_hi:[1,1]
	v_pk_fma_f32 v[16:17], v[30:31], v[2:3], v[16:17] op_sel_hi:[0,1,1]
	v_pk_fma_f32 v[18:19], v[32:33], v[6:7], v[18:19] op_sel_hi:[0,1,1]
	v_pk_add_f32 v[16:17], v[16:17], v[18:19]
	s_nop 0
	s_nop 0
	v_add_f32_dpp v16, v16, v16 quad_perm:[1,0,3,2] row_mask:0xf bank_mask:0xf bound_ctrl:1
	v_add_f32_dpp v17, v17, v17 quad_perm:[1,0,3,2] row_mask:0xf bank_mask:0xf bound_ctrl:1
	s_nop 0
	v_add_f32_dpp v16, v16, v16 quad_perm:[2,3,0,1] row_mask:0xf bank_mask:0xf bound_ctrl:1
	v_add_f32_dpp v17, v17, v17 quad_perm:[2,3,0,1] row_mask:0xf bank_mask:0xf bound_ctrl:1
	s_nop 0
	v_add_f32_dpp v16, v16, v16 row_half_mirror row_mask:0xf bank_mask:0xf bound_ctrl:1
	v_add_f32_dpp v17, v17, v17 row_half_mirror row_mask:0xf bank_mask:0xf bound_ctrl:1
	s_nop 0
	v_add_f32_dpp v16, v16, v16 row_mirror row_mask:0xf bank_mask:0xf bound_ctrl:1
	v_add_f32_dpp v17, v17, v17 row_mirror row_mask:0xf bank_mask:0xf bound_ctrl:1
	s_nop 0
	v_cvt_pk_bf16_f32 v16, v16, v17
	ds_write2_b32 v14, v15, v16 offset0:192 offset1:224
	s_waitcnt lgkmcnt(0)
	s_barrier
	s_and_saveexec_b64 s[2:3], vcc
	s_cbranch_execz .LBB0_496
	v_readlane_b32 s6, v247, 9
	s_add_i32 s5, s6, s5
	v_add3_u32 v14, s5, v13, v128
	ds_read_b128 v[14:17], v14
	s_waitcnt lgkmcnt(0)
	global_store_dwordx4 v[0:1], v[14:17], off
	s_branch .LBB0_496
